# GEMM K-loops: per-MFMA-cluster s_setprio toggles removed, one static s_setprio 1 for waves 4-7 per GEMM phase (reset at phase end)
# baseline (speedup 1.0000x reference)
; #define PG8_STAGE(bufoff, gbase, voff) do { _Pragma("unroll") for (int _i = 0; _i < 2; ++_i) \
;         __builtin_amdgcn_global_load_lds((const unsigned*)((const char*)(gbase) + (voff)[_i]), (PG8_LAS unsigned*)(lds + (bufoff) + ldsw + _i * 8192), 16, 0, 0); } while (0)
; #define PG8_WAIT_V(n) asm volatile("s_waitcnt vmcnt(" #n ")" ::: "memory")
; #define PG8_BAR __builtin_amdgcn_s_barrier()
; template <class Epi, class Sched, bool ALIGN_EPI = false, bool SP2 = false>
; __device__ __forceinline__ void gemm_phase(PG8_LAS unsigned char* lds, const Gemm g, const Sched& S, const Epi& E) {
;     ...
;         PG8_STAGE(PG8_SB(1, 0), cB + kstep, voffB); PG8_STAGE(PG8_SA(1, 0), cA + kstep, voffA); PG8_STAGE(PG8_SB(1, 1), cB + hstep + kstep, voffB);
;         PG8_WAIT_V(6); PG8_BAR;
;     } else {
;         PG8_STAGE(PG8_SB(0, 0), cB, voffB); PG8_STAGE(PG8_SA(0, 0), cA, voffA); PG8_STAGE(PG8_SB(0, 1), cB + hstep, voffB); PG8_STAGE(PG8_SA(0, 1), cA + hstep, voffA);
;         if (wr == 1) PG8_BAR;
;         PG8_WAIT_V(4); PG8_BAR;
;         PG8_STAGE(PG8_SB(1, 0), cB + kstep, voffB); PG8_STAGE(PG8_SA(1, 0), cA + kstep, voffA); PG8_STAGE(PG8_SB(1, 1), cB + hstep + kstep, voffB);
;         PG8_WAIT_V(6); PG8_BAR;
;     DI void operator()(const f32x4 (&acc)[2][2][4][2], const Unit& u, int wr, int wc, int fr, int fq) const {
;     ...
;             const int head = 2 * (pn & 1) + (wc >> 1), cmp = wc & 1;
;             f32x4 gv[2][2];
; #pragma unroll
;             for (int bj = 0; bj < 2; ++bj)
; #pragma unroll
;                 for (int n = 0; n < 2; ++n) gv[bj][n] = *(const f32x4*)(g + 32 * bj + 8 * fq + 4 * n);
;             const float sgn = fq == 0 ? -1.f : 1.f; const float qs = isk ? 1.f : 0.18033688011112042f;
;             float invr[2][4];
; #pragma unroll
;             for (int n = 0; n < 2; ++n)
; #pragma unroll
;                 for (int t4 = 0; t4 < 4; ++t4) invr[n][t4] = exp2f(-(float)(4 * n + t4) * (18.931568569324174f / 8.0f)) * 0.15915494309189535f;
.LBB0_122:
	v_bfe_u32 v15, v14, 4, 2
	v_and_b32_e32 v165, 15, v14
	v_lshlrev_b32_e32 v16, 4, v15
	v_lshlrev_b32_e32 v14, 2, v14
	s_mov_b64 s[20:21], 0x80
	s_and_b32 s7, s0, 3
	s_lshl_b32 s54, s1, 6
	v_lshl_or_b32 v16, v165, 6, v16
	s_lshl_b32 s1, s1, 13
	v_and_b32_e32 v14, 32, v14
	s_add_i32 m0, s91, 0x18000
	v_lshl_add_u64 v[6:7], v[6:7], 0, s[20:21]
	v_bitop3_b32 v17, v16, s1, v14 bitop3:0xde
	s_lshl_b32 s1, s7, 12
	s_waitcnt vmcnt(2)
	s_barrier
	global_load_lds_dwordx4 v[6:7], off
	v_lshl_add_u64 v[4:5], v[4:5], 0, s[20:21]
	s_add_i32 m0, s91, 0x1a000
	s_add_i32 s55, s91, 0x8000
	s_add_i32 s70, s91, 0xa000
	global_load_lds_dwordx4 v[4:5], off
	v_lshl_add_u64 v[0:1], v[0:1], 0, s[20:21]
	s_mov_b32 m0, s55
	s_add_u32 s4, s10, 0x40080
	global_load_lds_dwordx4 v[0:1], off
	v_lshl_add_u64 v[0:1], v[2:3], 0, s[20:21]
	s_mov_b32 m0, s70
	s_addc_u32 s5, s11, 0
	global_load_lds_dwordx4 v[0:1], off
	s_add_i32 m0, s91, 0x1c000
	v_lshl_add_u64 v[0:1], s[4:5], 0, v[146:147]
	global_load_lds_dwordx4 v[0:1], off
	v_lshl_add_u64 v[0:1], s[4:5], 0, v[150:151]
	s_add_i32 m0, s91, 0x1e000
	v_lshlrev_b32_e32 v154, 3, v15
	global_load_lds_dwordx4 v[0:1], off
	v_cvt_f32_ubyte0_e32 v0, v154
	v_bitop3_b32 v173, v16, s1, v14 bitop3:0xde
	v_mul_f32_e32 v1, 0xbed49a78, v0
	s_mov_b32 s1, 0xc2fc0000
	v_mov_b32_e32 v2, 0x42800000
	v_cmp_gt_f32_e32 vcc, s1, v1
	v_or_b32_e32 v4, 1, v154
	v_cvt_f32_ubyte0_e32 v4, v4
	v_cndmask_b32_e32 v1, 0, v2, vcc
	v_fmac_f32_e32 v1, 0xbed49a78, v0
	v_exp_f32_e32 v0, v1
	v_not_b32_e32 v1, 63
	v_mul_f32_e32 v5, 0xbed49a78, v4
	v_cndmask_b32_e32 v3, 0, v1, vcc
	v_cmp_gt_f32_e32 vcc, s1, v5
	v_ldexp_f32 v0, v0, v3
	v_mul_f32_e32 v177, 0.15915494, v0
	v_cndmask_b32_e32 v5, 0, v2, vcc
	v_fmac_f32_e32 v5, 0xbed49a78, v4
	v_exp_f32_e32 v4, v5
	v_cndmask_b32_e32 v0, 0, v1, vcc
	s_cmpk_lt_u32 s6, 0x100
	s_cselect_b64 s[22:23], -1, 0
	v_ldexp_f32 v0, v4, v0
	v_mul_f32_e32 v178, 0.15915494, v0
	v_or_b32_e32 v0, 2, v154
	v_cvt_f32_ubyte0_e32 v0, v0
	v_mul_f32_e32 v3, 0xbed49a78, v0
	v_cmp_gt_f32_e32 vcc, s1, v3
	v_or_b32_e32 v4, 3, v154
	v_cvt_f32_ubyte0_e32 v4, v4
	v_cndmask_b32_e32 v3, 0, v2, vcc
	v_fmac_f32_e32 v3, 0xbed49a78, v0
	v_mul_f32_e32 v5, 0xbed49a78, v4
	v_exp_f32_e32 v0, v3
	v_cndmask_b32_e32 v3, 0, v1, vcc
	v_cmp_gt_f32_e32 vcc, s1, v5
	s_lshl_b32 s71, s7, 6
	v_ldexp_f32 v0, v0, v3
	v_cndmask_b32_e32 v5, 0, v2, vcc
	v_fmac_f32_e32 v5, 0xbed49a78, v4
	v_exp_f32_e32 v4, v5
	v_mul_f32_e32 v179, 0.15915494, v0
	v_cndmask_b32_e32 v0, 0, v1, vcc
	s_bfe_u32 s79, s0, 0x10001
	v_ldexp_f32 v0, v4, v0
	v_mul_f32_e32 v180, 0.15915494, v0
	v_or_b32_e32 v0, 4, v154
	v_cvt_f32_ubyte0_e32 v0, v0
	v_mul_f32_e32 v3, 0xbed49a78, v0
	v_cmp_gt_f32_e32 vcc, s1, v3
	v_or_b32_e32 v4, 5, v154
	v_cvt_f32_ubyte0_e32 v4, v4
	v_cndmask_b32_e32 v3, 0, v2, vcc
	v_fmac_f32_e32 v3, 0xbed49a78, v0
	v_mul_f32_e32 v5, 0xbed49a78, v4
	v_exp_f32_e32 v0, v3
	v_cndmask_b32_e32 v3, 0, v1, vcc
	v_cmp_gt_f32_e32 vcc, s1, v5
	s_ashr_i32 s80, s3, 31
	v_ldexp_f32 v0, v0, v3
	v_cndmask_b32_e32 v5, 0, v2, vcc
	v_fmac_f32_e32 v5, 0xbed49a78, v4
	v_exp_f32_e32 v4, v5
	v_mul_f32_e32 v181, 0.15915494, v0
	v_cndmask_b32_e32 v0, 0, v1, vcc
	s_ashr_i32 s81, s2, 31
	v_ldexp_f32 v0, v4, v0
	v_mul_f32_e32 v185, 0.15915494, v0
	v_or_b32_e32 v0, 6, v154
	v_cvt_f32_ubyte0_e32 v0, v0
	v_mul_f32_e32 v3, 0xbed49a78, v0
	v_cmp_gt_f32_e32 vcc, s1, v3
	v_or_b32_e32 v4, 7, v154
	v_cvt_f32_ubyte0_e32 v4, v4
	v_cndmask_b32_e32 v3, 0, v2, vcc
	v_fmac_f32_e32 v3, 0xbed49a78, v0
	v_mul_f32_e32 v5, 0xbed49a78, v4
	v_exp_f32_e32 v0, v3
	v_cndmask_b32_e32 v3, 0, v1, vcc
	v_cmp_gt_f32_e32 vcc, s1, v5
	s_add_u32 s24, s72, 0x18480000
	v_ldexp_f32 v0, v0, v3
	v_cndmask_b32_e32 v2, 0, v2, vcc
	v_fmac_f32_e32 v2, 0xbed49a78, v4
	v_exp_f32_e32 v2, v2
	v_mul_f32_e32 v186, 0.15915494, v0
	v_cndmask_b32_e32 v0, 0, v1, vcc
	v_and_b32_e32 v1, 1, v8
	v_ldexp_f32 v0, v2, v0
	v_mul_f32_e32 v187, 0.15915494, v0
	v_lshlrev_b32_e32 v0, 14, v8
	v_and_b32_e32 v0, 0xffff8000, v0
	v_lshl_add_u32 v0, v9, 11, v0
	s_addc_u32 s25, s73, 0
	v_lshl_or_b32 v0, v1, 6, v0
	s_add_u32 s26, s72, 0x20900000
	v_lshl_add_u32 v156, v10, 1, v0
	v_lshlrev_b32_e32 v0, 14, v11
	s_addc_u32 s27, s73, 0
	v_and_b32_e32 v0, 0xffff8000, v0
	s_waitcnt vmcnt(6)
	s_add_u32 s28, s72, 0x10400000
	v_lshl_add_u32 v0, v12, 11, v0
	v_and_b32_e32 v1, 1, v11
	s_addc_u32 s29, s73, 0
	v_lshl_or_b32 v0, v1, 6, v0
	s_add_i32 s82, 0, 0x10000
	s_add_i32 s83, 0, 0x14000
	v_or_b32_e32 v172, s54, v165
	v_or_b32_e32 v174, 16, v165
	v_or_b32_e32 v175, 32, v165
	v_or_b32_e32 v176, 48, v165
	s_movk_i32 s78, 0x1010
	v_or_b32_e32 v188, 0x1010, v165
	v_or_b32_e32 v189, 0x1020, v165
	v_or_b32_e32 v190, 0x1030, v165
	v_or_b32_e32 v191, 0x1040, v165
	v_cmp_eq_u32_e64 s[12:13], 0, v15
	v_cmp_gt_u32_e64 s[4:5], 2, v15
	v_lshl_or_b32 v192, s7, 5, v154
	v_and_or_b32 v193, s71, 64, v154
	v_mov_b32_e32 v157, v153
	v_lshl_add_u32 v158, v13, 1, v0
	v_mov_b32_e32 v159, v153
	v_mov_b64_e32 v[160:161], 0xc3c
	v_mov_b64_e32 v[162:163], 0xc3b
	v_add_u32_e32 v194, s82, v173
	v_add_u32_e32 v195, s83, v173
	v_add_u32_e32 v196, 0, v17
	s_mov_b32 s84, 0x10410
	v_mov_b32_e32 v197, 0x358637bd
	s_mov_b32 s85, 0x800000
	v_mov_b32_e32 v198, 0x3e000000
	v_mbcnt_hi_u32_b32 v199, -1, v155
	v_mov_b32_e32 v200, 0x3e38aa3b
	s_mov_b32 s86, 0
	s_barrier
	v_readfirstlane_b32 s98, v182
	s_nop 0
	s_cmpk_lt_u32 s98, 0x100
	s_cbranch_scc1 .Lprio_p1
	s_setprio 1
.Lprio_p1:
	s_branch .LBB0_125
.LBB0_123:
	s_mov_b64 s[6:7], 0

; #define PG8_STAGE(bufoff, gbase, voff) do { _Pragma("unroll") for (int _i = 0; _i < 2; ++_i) \
;         __builtin_amdgcn_global_load_lds((const unsigned*)((const char*)(gbase) + (voff)[_i]), (PG8_LAS unsigned*)(lds + (bufoff) + ldsw + _i * 8192), 16, 0, 0); } while (0)
; #define PG8_LDA(dst, b, h) do { _Pragma("unroll") for (int m = 0; m < 4; ++m) _Pragma("unroll") for (int k = 0; k < 2; ++k) dst[m][k] = *(const PG8_LAS bf16x8*)(lds + PG8_SA(b, h) + aoff + m * 2048 + k * 1024); } while (0)
; #define PG8_BAR __builtin_amdgcn_s_barrier()
; template <class Epi, class Sched, bool ALIGN_EPI = false, bool SP2 = false>
; __device__ __forceinline__ void gemm_phase(PG8_LAS unsigned char* lds, const Gemm g, const Sched& S, const Epi& E) {
;     ...
;         const char* nA = has_next ? (const char*)g.A + (size_t)nxt.pm * tstep : cA; const char* nB = has_next ? (const char*)g.Bt + (size_t)nxt.pn * tstep : cB;
;         for (int t = 0; t < nt; t += 2) {
;             const bool last = (t == nt - 2);
;             const char* a1 = cA + (size_t)(t + 1) * kstep;
;             const char* a2 = last ? nA : cA + (size_t)(t + 2) * kstep; const char* b2 = last ? nB : cB + (size_t)(t + 2) * kstep;
;             const char* a3 = a2 + kstep; const char* b3 = b2 + kstep;
;             if (last && has_next) S.a_ready(nxt);
;             if constexpr (SP2) {
;             PG8_LDB(B0, 0, 0); PG8_LDB(B1, 0, 1); PG8_SCHED; PG8_LDA(At, 0, 0); PG8_STAGE(PG8_SA(1, 1), a1 + hstep, voffA);
;             PG8_WAIT_V(8); PG8_WAIT_L(0); PG8_BAR; PG8_MMA(0, 0, At, B0); PG8_MMA(0, 1, At, B1); PG8_BAR; PG8_SCHED;
;             PG8_LDA(At, 0, 1); PG8_STAGE(PG8_SB(0, 0), b2, voffB); PG8_STAGE(PG8_SB(0, 1), b2 + hstep, voffB); PG8_STAGE(PG8_SA(0, 0), a2, voffA);
;             PG8_WAIT_V(8); PG8_WAIT_L(0); PG8_BAR; PG8_MMA(1, 0, At, B0); PG8_MMA(1, 1, At, B1); PG8_BAR; PG8_SCHED;
;             PG8_LDB(B0, 1, 0); PG8_LDB(B1, 1, 1); PG8_SCHED; PG8_LDA(At, 1, 0); PG8_STAGE(PG8_SA(0, 1), a2 + hstep, voffA);
;             PG8_WAIT_V(8); PG8_WAIT_L(0); PG8_BAR; PG8_MMA(0, 0, At, B0); PG8_MMA(0, 1, At, B1); PG8_BAR; PG8_SCHED;
;             PG8_LDA(At, 1, 1); PG8_STAGE(PG8_SB(1, 0), b3, voffB); PG8_STAGE(PG8_SB(1, 1), b3 + hstep, voffB); PG8_STAGE(PG8_SA(1, 0), a3, voffA);
;             PG8_WAIT_V(8); PG8_WAIT_L(0); PG8_BAR; PG8_MMA(1, 0, At, B0); PG8_MMA(1, 1, At, B1); PG8_BAR; PG8_SCHED;
.LBB0_131:
	s_ashr_i32 s1, s0, 31
	s_lshl_b64 s[14:15], s[0:1], 19
	s_add_u32 s94, s50, s14
	s_addc_u32 s95, s51, s15
	s_and_b64 s[14:15], s[6:7], exec
	s_cselect_b32 s1, s95, s9
	s_cselect_b32 s16, s94, s8
	s_ashr_i32 s89, s88, 31
	s_lshl_b64 s[14:15], s[88:89], 19
	s_add_u32 s96, s33, s14
	s_addc_u32 s97, s42, s15
	s_and_b64 s[14:15], s[6:7], exec
	s_cselect_b32 s30, s97, s11
	s_cselect_b32 s31, s96, s10
	s_add_u32 s8, s8, 0x40080
	s_addc_u32 s9, s9, 0
	s_add_u32 s34, s10, 0x100
	s_addc_u32 s35, s11, 0
	s_mov_b32 s36, -2
	s_waitcnt lgkmcnt(0)
	ds_read_b128 v[128:131], v194
	ds_read_b128 v[132:135], v194 offset:1024
	ds_read_b128 v[136:139], v194 offset:2048
	ds_read_b128 v[140:143], v194 offset:3072
	ds_read_b128 v[166:169], v195
	ds_read_b128 v[202:205], v195 offset:1024
	ds_read_b128 v[206:209], v195 offset:2048
	ds_read_b128 v[210:213], v195 offset:3072
	s_add_u32 s10, s8, 0xfffc0080
	s_addc_u32 s11, s9, -1
	s_cmp_eq_u32 s36, 12
	s_cselect_b32 s15, s1, s11
	s_cselect_b32 s14, s16, s10
	s_cselect_b32 s11, s30, s35
	s_cselect_b32 s10, s31, s34
	s_add_i32 m0, s91, 0xc000
	ds_read_b128 v[214:217], v196
	ds_read_b128 v[218:221], v196 offset:1024
	ds_read_b128 v[222:225], v196 offset:2048
	ds_read_b128 v[226:229], v196 offset:3072
	ds_read_b128 v[230:233], v196 offset:4096
	ds_read_b128 v[234:237], v196 offset:5120
	ds_read_b128 v[238:241], v196 offset:6144
	ds_read_b128 v[242:245], v196 offset:7168
	global_load_lds_dwordx4 v156, s[8:9]
	s_add_i32 m0, s91, 0xe000
	s_nop 0
	global_load_lds_dwordx4 v158, s[8:9]
	s_waitcnt vmcnt(8)
	s_waitcnt lgkmcnt(0)
	s_barrier
	s_waitcnt lgkmcnt(0)
	v_mfma_f32_16x16x32_bf16 v[124:127], v[128:131], v[214:217], 0
	v_mfma_f32_16x16x32_bf16 v[120:123], v[136:139], v[214:217], 0
	v_mfma_f32_16x16x32_bf16 v[108:111], v[128:131], v[222:225], 0
	v_mfma_f32_16x16x32_bf16 v[104:107], v[136:139], v[222:225], 0
	v_mfma_f32_16x16x32_bf16 v[92:95], v[128:131], v[230:233], 0
	v_mfma_f32_16x16x32_bf16 v[88:91], v[136:139], v[230:233], 0
	v_mfma_f32_16x16x32_bf16 v[76:79], v[128:131], v[238:241], 0
	v_mfma_f32_16x16x32_bf16 v[72:75], v[136:139], v[238:241], 0
	v_mfma_f32_16x16x32_bf16 v[124:127], v[132:135], v[218:221], v[124:127]
	v_mfma_f32_16x16x32_bf16 v[120:123], v[140:143], v[218:221], v[120:123]
	v_mfma_f32_16x16x32_bf16 v[108:111], v[132:135], v[226:229], v[108:111]
	v_mfma_f32_16x16x32_bf16 v[104:107], v[140:143], v[226:229], v[104:107]
	v_mfma_f32_16x16x32_bf16 v[92:95], v[132:135], v[234:237], v[92:95]
	v_mfma_f32_16x16x32_bf16 v[88:91], v[140:143], v[234:237], v[88:91]
	v_mfma_f32_16x16x32_bf16 v[76:79], v[132:135], v[242:245], v[76:79]
	v_mfma_f32_16x16x32_bf16 v[72:75], v[140:143], v[242:245], v[72:75]
	v_mfma_f32_16x16x32_bf16 v[116:119], v[166:169], v[214:217], 0
	v_mfma_f32_16x16x32_bf16 v[112:115], v[206:209], v[214:217], 0
	v_mfma_f32_16x16x32_bf16 v[100:103], v[166:169], v[222:225], 0
	v_mfma_f32_16x16x32_bf16 v[96:99], v[206:209], v[222:225], 0
	v_mfma_f32_16x16x32_bf16 v[84:87], v[166:169], v[230:233], 0
	v_mfma_f32_16x16x32_bf16 v[80:83], v[206:209], v[230:233], 0
	v_mfma_f32_16x16x32_bf16 v[68:71], v[166:169], v[238:241], 0
	v_mfma_f32_16x16x32_bf16 v[64:67], v[206:209], v[238:241], 0
	v_mfma_f32_16x16x32_bf16 v[116:119], v[202:205], v[218:221], v[116:119]
	v_mfma_f32_16x16x32_bf16 v[112:115], v[210:213], v[218:221], v[112:115]
	v_mfma_f32_16x16x32_bf16 v[100:103], v[202:205], v[226:229], v[100:103]
	v_mfma_f32_16x16x32_bf16 v[96:99], v[210:213], v[226:229], v[96:99]
	v_mfma_f32_16x16x32_bf16 v[84:87], v[202:205], v[234:237], v[84:87]
	v_mfma_f32_16x16x32_bf16 v[80:83], v[210:213], v[234:237], v[80:83]
	v_mfma_f32_16x16x32_bf16 v[68:71], v[202:205], v[242:245], v[68:71]
	v_mfma_f32_16x16x32_bf16 v[64:67], v[210:213], v[242:245], v[64:67]
	s_barrier
	s_add_i32 s37, s82, s43
	s_mov_b32 m0, s37
	ds_read_b128 v[214:217], v196 offset:16384
	ds_read_b128 v[218:221], v196 offset:17408
	ds_read_b128 v[222:225], v196 offset:18432
	ds_read_b128 v[226:229], v196 offset:19456
	ds_read_b128 v[230:233], v196 offset:20480
	ds_read_b128 v[234:237], v196 offset:21504
	ds_read_b128 v[238:241], v196 offset:22528
	ds_read_b128 v[242:245], v196 offset:23552
	global_load_lds_dwordx4 v146, s[10:11]
	s_add_i32 m0, s37, 0x2000
	s_add_u32 s38, s10, 0x40000
	s_addc_u32 s39, s11, 0
	s_add_u32 s98, s10, s20
	s_addc_u32 s99, s11, s21
	s_add_u32 s100, s14, s20
	s_addc_u32 s101, s15, s21
	s_add_i32 s37, s83, s43
	global_load_lds_dwordx4 v150, s[10:11]
	s_mov_b32 m0, s37
	s_nop 0
	global_load_lds_dwordx4 v146, s[38:39]
	s_add_i32 m0, s37, 0x2000
	s_nop 0
	global_load_lds_dwordx4 v150, s[38:39]
	s_mov_b32 m0, s91
	s_nop 0
	global_load_lds_dwordx4 v144, s[14:15]
	s_mov_b32 m0, s93
	s_nop 0
	global_load_lds_dwordx4 v148, s[14:15]
	s_waitcnt vmcnt(8)
	s_waitcnt lgkmcnt(0)
	s_barrier
; #define PG8_STAGE(bufoff, gbase, voff) do { _Pragma("unroll") for (int _i = 0; _i < 2; ++_i) \
;         __builtin_amdgcn_global_load_lds((const unsigned*)((const char*)(gbase) + (voff)[_i]), (PG8_LAS unsigned*)(lds + (bufoff) + ldsw + _i * 8192), 16, 0, 0); } while (0)
; #define PG8_LDA(dst, b, h) do { _Pragma("unroll") for (int m = 0; m < 4; ++m) _Pragma("unroll") for (int k = 0; k < 2; ++k) dst[m][k] = *(const PG8_LAS bf16x8*)(lds + PG8_SA(b, h) + aoff + m * 2048 + k * 1024); } while (0)
; #define PG8_LDB(dst, b, h) do { _Pragma("unroll") for (int n = 0; n < 2; ++n) _Pragma("unroll") for (int k = 0; k < 2; ++k) dst[n][k] = *(const PG8_LAS bf16x8*)(lds + PG8_SB(b, h) + boff + n * 2048 + k * 1024); } while (0)
; #define PG8_MMA(ai, bj, At, Bt) do { __builtin_amdgcn_s_setprio(1); _Pragma("unroll") for (int m = 0; m < 4; ++m) _Pragma("unroll") for (int n = 0; n < 2; ++n) _Pragma("unroll") for (int k = 0; k < 2; ++k) \
;         acc[ai][bj][m][n] = __builtin_amdgcn_mfma_f32_16x16x32_bf16(Bt[n][k], At[m][k], acc[ai][bj][m][n], 0, 0, 0); __builtin_amdgcn_s_setprio(0); } while (0)
; #define PG8_WAIT_V(n) asm volatile("s_waitcnt vmcnt(" #n ")" ::: "memory")
; template <class Epi, class Sched, bool ALIGN_EPI = false, bool SP2 = false>
; __device__ __forceinline__ void gemm_phase(PG8_LAS unsigned char* lds, const Gemm g, const Sched& S, const Epi& E) {
;     ...
;             PG8_LDB(B0, 0, 0); PG8_LDB(B1, 0, 1); PG8_SCHED; PG8_LDA(At, 0, 0); PG8_STAGE(PG8_SA(1, 1), a1 + hstep, voffA);
;             PG8_WAIT_V(8); PG8_WAIT_L(0); PG8_BAR; PG8_MMA(0, 0, At, B0); PG8_MMA(0, 1, At, B1); PG8_BAR; PG8_SCHED;
;             PG8_LDA(At, 0, 1); PG8_STAGE(PG8_SB(0, 0), b2, voffB); PG8_STAGE(PG8_SB(0, 1), b2 + hstep, voffB); PG8_STAGE(PG8_SA(0, 0), a2, voffA);
;             PG8_WAIT_V(8); PG8_WAIT_L(0); PG8_BAR; PG8_MMA(1, 0, At, B0); PG8_MMA(1, 1, At, B1); PG8_BAR; PG8_SCHED;
;             PG8_LDB(B0, 1, 0); PG8_LDB(B1, 1, 1); PG8_SCHED; PG8_LDA(At, 1, 0); PG8_STAGE(PG8_SA(0, 1), a2 + hstep, voffA);
;             PG8_WAIT_V(8); PG8_WAIT_L(0); PG8_BAR; PG8_MMA(0, 0, At, B0); PG8_MMA(0, 1, At, B1); PG8_BAR; PG8_SCHED;
;             PG8_LDA(At, 1, 1); PG8_STAGE(PG8_SB(1, 0), b3, voffB); PG8_STAGE(PG8_SB(1, 1), b3 + hstep, voffB); PG8_STAGE(PG8_SA(1, 0), a3, voffA);
;             PG8_WAIT_V(8); PG8_WAIT_L(0); PG8_BAR; PG8_MMA(1, 0, At, B0); PG8_MMA(1, 1, At, B1); PG8_BAR; PG8_SCHED;
	s_waitcnt lgkmcnt(0)
	v_mfma_f32_16x16x32_bf16 v[60:63], v[128:131], v[214:217], 0
	v_mfma_f32_16x16x32_bf16 v[56:59], v[136:139], v[214:217], 0
	v_mfma_f32_16x16x32_bf16 v[44:47], v[128:131], v[222:225], 0
	v_mfma_f32_16x16x32_bf16 v[40:43], v[136:139], v[222:225], 0
	v_mfma_f32_16x16x32_bf16 v[28:31], v[128:131], v[230:233], 0
	v_mfma_f32_16x16x32_bf16 v[24:27], v[136:139], v[230:233], 0
	v_mfma_f32_16x16x32_bf16 v[12:15], v[128:131], v[238:241], 0
	v_mfma_f32_16x16x32_bf16 v[8:11], v[136:139], v[238:241], 0
	v_mfma_f32_16x16x32_bf16 v[60:63], v[132:135], v[218:221], v[60:63]
	v_mfma_f32_16x16x32_bf16 v[56:59], v[140:143], v[218:221], v[56:59]
	v_mfma_f32_16x16x32_bf16 v[44:47], v[132:135], v[226:229], v[44:47]
	v_mfma_f32_16x16x32_bf16 v[40:43], v[140:143], v[226:229], v[40:43]
	v_mfma_f32_16x16x32_bf16 v[28:31], v[132:135], v[234:237], v[28:31]
	v_mfma_f32_16x16x32_bf16 v[24:27], v[140:143], v[234:237], v[24:27]
	v_mfma_f32_16x16x32_bf16 v[12:15], v[132:135], v[242:245], v[12:15]
	v_mfma_f32_16x16x32_bf16 v[8:11], v[140:143], v[242:245], v[8:11]
	v_mfma_f32_16x16x32_bf16 v[52:55], v[166:169], v[214:217], 0
	v_mfma_f32_16x16x32_bf16 v[48:51], v[206:209], v[214:217], 0
	v_mfma_f32_16x16x32_bf16 v[36:39], v[166:169], v[222:225], 0
	v_mfma_f32_16x16x32_bf16 v[32:35], v[206:209], v[222:225], 0
	v_mfma_f32_16x16x32_bf16 v[20:23], v[166:169], v[230:233], 0
	v_mfma_f32_16x16x32_bf16 v[16:19], v[206:209], v[230:233], 0
	v_mfma_f32_16x16x32_bf16 v[4:7], v[166:169], v[238:241], 0
	v_mfma_f32_16x16x32_bf16 v[0:3], v[206:209], v[238:241], 0
	v_mfma_f32_16x16x32_bf16 v[52:55], v[202:205], v[218:221], v[52:55]
	v_mfma_f32_16x16x32_bf16 v[48:51], v[210:213], v[218:221], v[48:51]
	v_mfma_f32_16x16x32_bf16 v[36:39], v[202:205], v[226:229], v[36:39]
	v_mfma_f32_16x16x32_bf16 v[32:35], v[210:213], v[226:229], v[32:35]
	v_mfma_f32_16x16x32_bf16 v[20:23], v[202:205], v[234:237], v[20:23]
	v_mfma_f32_16x16x32_bf16 v[16:19], v[210:213], v[234:237], v[16:19]
	v_mfma_f32_16x16x32_bf16 v[4:7], v[202:205], v[242:245], v[4:7]
	v_mfma_f32_16x16x32_bf16 v[0:3], v[210:213], v[242:245], v[0:3]
	s_barrier
	s_add_i32 s37, 0, 0x18000
	s_add_i32 s38, 0, 0x1c000
	v_add_u32_e32 v140, s37, v173
	v_add_u32_e32 v152, s38, v173
	ds_read_b128 v[128:131], v140
	ds_read_b128 v[132:135], v140 offset:1024
	ds_read_b128 v[136:139], v140 offset:2048
	ds_read_b128 v[140:143], v140 offset:3072
	ds_read_b128 v[166:169], v152
	ds_read_b128 v[202:205], v152 offset:1024
	ds_read_b128 v[206:209], v152 offset:2048
	ds_read_b128 v[210:213], v152 offset:3072
	s_add_u32 s14, s14, 0x40000
	s_addc_u32 s15, s15, 0
	s_mov_b32 m0, s52
	ds_read_b128 v[214:217], v196 offset:32768
	ds_read_b128 v[218:221], v196 offset:33792
	ds_read_b128 v[222:225], v196 offset:34816
	ds_read_b128 v[226:229], v196 offset:35840
	ds_read_b128 v[230:233], v196 offset:36864
	ds_read_b128 v[234:237], v196 offset:37888
	ds_read_b128 v[238:241], v196 offset:38912
	ds_read_b128 v[242:245], v196 offset:39936
	global_load_lds_dwordx4 v144, s[14:15]
	s_mov_b32 m0, s53
	s_nop 0
	global_load_lds_dwordx4 v148, s[14:15]
	s_waitcnt vmcnt(8)
	s_waitcnt lgkmcnt(0)
	s_barrier
	s_waitcnt lgkmcnt(0)
	v_mfma_f32_16x16x32_bf16 v[124:127], v[128:131], v[214:217], v[124:127]
	v_mfma_f32_16x16x32_bf16 v[120:123], v[136:139], v[214:217], v[120:123]
	v_mfma_f32_16x16x32_bf16 v[108:111], v[128:131], v[222:225], v[108:111]
	v_mfma_f32_16x16x32_bf16 v[104:107], v[136:139], v[222:225], v[104:107]
	v_mfma_f32_16x16x32_bf16 v[92:95], v[128:131], v[230:233], v[92:95]
	v_mfma_f32_16x16x32_bf16 v[88:91], v[136:139], v[230:233], v[88:91]
	v_mfma_f32_16x16x32_bf16 v[76:79], v[128:131], v[238:241], v[76:79]
	v_mfma_f32_16x16x32_bf16 v[72:75], v[136:139], v[238:241], v[72:75]
	v_mfma_f32_16x16x32_bf16 v[124:127], v[132:135], v[218:221], v[124:127]
	v_mfma_f32_16x16x32_bf16 v[120:123], v[140:143], v[218:221], v[120:123]
	v_mfma_f32_16x16x32_bf16 v[108:111], v[132:135], v[226:229], v[108:111]
	v_mfma_f32_16x16x32_bf16 v[104:107], v[140:143], v[226:229], v[104:107]
	v_mfma_f32_16x16x32_bf16 v[92:95], v[132:135], v[234:237], v[92:95]
	v_mfma_f32_16x16x32_bf16 v[88:91], v[140:143], v[234:237], v[88:91]
	v_mfma_f32_16x16x32_bf16 v[76:79], v[132:135], v[242:245], v[76:79]
	v_mfma_f32_16x16x32_bf16 v[72:75], v[140:143], v[242:245], v[72:75]
	v_mfma_f32_16x16x32_bf16 v[116:119], v[166:169], v[214:217], v[116:119]
	v_mfma_f32_16x16x32_bf16 v[112:115], v[206:209], v[214:217], v[112:115]
	v_mfma_f32_16x16x32_bf16 v[100:103], v[166:169], v[222:225], v[100:103]
	v_mfma_f32_16x16x32_bf16 v[96:99], v[206:209], v[222:225], v[96:99]
	v_mfma_f32_16x16x32_bf16 v[84:87], v[166:169], v[230:233], v[84:87]
	v_mfma_f32_16x16x32_bf16 v[80:83], v[206:209], v[230:233], v[80:83]
	v_mfma_f32_16x16x32_bf16 v[68:71], v[166:169], v[238:241], v[68:71]
	v_mfma_f32_16x16x32_bf16 v[64:67], v[206:209], v[238:241], v[64:67]
	v_mfma_f32_16x16x32_bf16 v[116:119], v[202:205], v[218:221], v[116:119]
	v_mfma_f32_16x16x32_bf16 v[112:115], v[210:213], v[218:221], v[112:115]
	v_mfma_f32_16x16x32_bf16 v[100:103], v[202:205], v[226:229], v[100:103]
	v_mfma_f32_16x16x32_bf16 v[96:99], v[210:213], v[226:229], v[96:99]
	v_mfma_f32_16x16x32_bf16 v[84:87], v[202:205], v[234:237], v[84:87]
	v_mfma_f32_16x16x32_bf16 v[80:83], v[210:213], v[234:237], v[80:83]
	v_mfma_f32_16x16x32_bf16 v[68:71], v[202:205], v[242:245], v[68:71]
	v_mfma_f32_16x16x32_bf16 v[64:67], v[210:213], v[242:245], v[64:67]
	s_barrier
; #define PG8_STAGE(bufoff, gbase, voff) do { _Pragma("unroll") for (int _i = 0; _i < 2; ++_i) \
;         __builtin_amdgcn_global_load_lds((const unsigned*)((const char*)(gbase) + (voff)[_i]), (PG8_LAS unsigned*)(lds + (bufoff) + ldsw + _i * 8192), 16, 0, 0); } while (0)
; #define PG8_LDA(dst, b, h) do { _Pragma("unroll") for (int m = 0; m < 4; ++m) _Pragma("unroll") for (int k = 0; k < 2; ++k) dst[m][k] = *(const PG8_LAS bf16x8*)(lds + PG8_SA(b, h) + aoff + m * 2048 + k * 1024); } while (0)
; #define PG8_LDB(dst, b, h) do { _Pragma("unroll") for (int n = 0; n < 2; ++n) _Pragma("unroll") for (int k = 0; k < 2; ++k) dst[n][k] = *(const PG8_LAS bf16x8*)(lds + PG8_SB(b, h) + boff + n * 2048 + k * 1024); } while (0)
; #define PG8_MMA(ai, bj, At, Bt) do { __builtin_amdgcn_s_setprio(1); _Pragma("unroll") for (int m = 0; m < 4; ++m) _Pragma("unroll") for (int n = 0; n < 2; ++n) _Pragma("unroll") for (int k = 0; k < 2; ++k) \
;         acc[ai][bj][m][n] = __builtin_amdgcn_mfma_f32_16x16x32_bf16(Bt[n][k], At[m][k], acc[ai][bj][m][n], 0, 0, 0); __builtin_amdgcn_s_setprio(0); } while (0)
; #define PG8_WAIT_V(n) asm volatile("s_waitcnt vmcnt(" #n ")" ::: "memory")
; template <class Epi, class Sched, bool ALIGN_EPI = false, bool SP2 = false>
; __device__ __forceinline__ void gemm_phase(PG8_LAS unsigned char* lds, const Gemm g, const Sched& S, const Epi& E) {
;     ...
;             PG8_LDB(B0, 0, 0); PG8_LDB(B1, 0, 1); PG8_SCHED; PG8_LDA(At, 0, 0); PG8_STAGE(PG8_SA(1, 1), a1 + hstep, voffA);
;             PG8_WAIT_V(8); PG8_WAIT_L(0); PG8_BAR; PG8_MMA(0, 0, At, B0); PG8_MMA(0, 1, At, B1); PG8_BAR; PG8_SCHED;
;             PG8_LDA(At, 0, 1); PG8_STAGE(PG8_SB(0, 0), b2, voffB); PG8_STAGE(PG8_SB(0, 1), b2 + hstep, voffB); PG8_STAGE(PG8_SA(0, 0), a2, voffA);
;             PG8_WAIT_V(8); PG8_WAIT_L(0); PG8_BAR; PG8_MMA(1, 0, At, B0); PG8_MMA(1, 1, At, B1); PG8_BAR; PG8_SCHED;
;             PG8_LDB(B0, 1, 0); PG8_LDB(B1, 1, 1); PG8_SCHED; PG8_LDA(At, 1, 0); PG8_STAGE(PG8_SA(0, 1), a2 + hstep, voffA);
;             PG8_WAIT_V(8); PG8_WAIT_L(0); PG8_BAR; PG8_MMA(0, 0, At, B0); PG8_MMA(0, 1, At, B1); PG8_BAR; PG8_SCHED;
;             PG8_LDA(At, 1, 1); PG8_STAGE(PG8_SB(1, 0), b3, voffB); PG8_STAGE(PG8_SB(1, 1), b3 + hstep, voffB); PG8_STAGE(PG8_SA(1, 0), a3, voffA);
;             PG8_WAIT_V(8); PG8_WAIT_L(0); PG8_BAR; PG8_MMA(1, 0, At, B0); PG8_MMA(1, 1, At, B1); PG8_BAR; PG8_SCHED;
	s_add_i32 s14, s37, s43
	s_mov_b32 m0, s14
	ds_read_b128 v[214:217], v196 offset:49152
	ds_read_b128 v[218:221], v196 offset:50176
	ds_read_b128 v[222:225], v196 offset:51200
	ds_read_b128 v[226:229], v196 offset:52224
	ds_read_b128 v[230:233], v196 offset:53248
	ds_read_b128 v[234:237], v196 offset:54272
	ds_read_b128 v[238:241], v196 offset:55296
	ds_read_b128 v[242:245], v196 offset:56320
	global_load_lds_dwordx4 v146, s[98:99]
	s_add_i32 m0, s14, 0x2000
	s_add_u32 s10, s10, 0x40080
	s_addc_u32 s11, s11, 0
	s_add_i32 s14, s38, s43
	global_load_lds_dwordx4 v150, s[98:99]
	s_mov_b32 m0, s14
	s_nop 0
	global_load_lds_dwordx4 v146, s[10:11]
	s_add_i32 m0, s14, 0x2000
	s_nop 0
	global_load_lds_dwordx4 v150, s[10:11]
	s_mov_b32 m0, s55
	s_nop 0
	global_load_lds_dwordx4 v144, s[100:101]
	s_mov_b32 m0, s70
	s_nop 0
	global_load_lds_dwordx4 v148, s[100:101]
	s_waitcnt vmcnt(8)
	s_waitcnt lgkmcnt(0)
	s_barrier
	s_waitcnt lgkmcnt(0)
	v_mfma_f32_16x16x32_bf16 v[60:63], v[128:131], v[214:217], v[60:63]
	v_mfma_f32_16x16x32_bf16 v[56:59], v[136:139], v[214:217], v[56:59]
	v_mfma_f32_16x16x32_bf16 v[44:47], v[128:131], v[222:225], v[44:47]
	v_mfma_f32_16x16x32_bf16 v[40:43], v[136:139], v[222:225], v[40:43]
	v_mfma_f32_16x16x32_bf16 v[28:31], v[128:131], v[230:233], v[28:31]
	v_mfma_f32_16x16x32_bf16 v[24:27], v[136:139], v[230:233], v[24:27]
	v_mfma_f32_16x16x32_bf16 v[12:15], v[128:131], v[238:241], v[12:15]
	v_mfma_f32_16x16x32_bf16 v[8:11], v[136:139], v[238:241], v[8:11]
	v_mfma_f32_16x16x32_bf16 v[60:63], v[132:135], v[218:221], v[60:63]
	v_mfma_f32_16x16x32_bf16 v[56:59], v[140:143], v[218:221], v[56:59]
	v_mfma_f32_16x16x32_bf16 v[44:47], v[132:135], v[226:229], v[44:47]
	v_mfma_f32_16x16x32_bf16 v[40:43], v[140:143], v[226:229], v[40:43]
	v_mfma_f32_16x16x32_bf16 v[28:31], v[132:135], v[234:237], v[28:31]
	v_mfma_f32_16x16x32_bf16 v[24:27], v[140:143], v[234:237], v[24:27]
	v_mfma_f32_16x16x32_bf16 v[12:15], v[132:135], v[242:245], v[12:15]
	v_mfma_f32_16x16x32_bf16 v[8:11], v[140:143], v[242:245], v[8:11]
	v_mfma_f32_16x16x32_bf16 v[52:55], v[166:169], v[214:217], v[52:55]
	v_mfma_f32_16x16x32_bf16 v[48:51], v[206:209], v[214:217], v[48:51]
	v_mfma_f32_16x16x32_bf16 v[36:39], v[166:169], v[222:225], v[36:39]
	v_mfma_f32_16x16x32_bf16 v[32:35], v[206:209], v[222:225], v[32:35]
	v_mfma_f32_16x16x32_bf16 v[20:23], v[166:169], v[230:233], v[20:23]
	v_mfma_f32_16x16x32_bf16 v[16:19], v[206:209], v[230:233], v[16:19]
	v_mfma_f32_16x16x32_bf16 v[4:7], v[166:169], v[238:241], v[4:7]
	v_mfma_f32_16x16x32_bf16 v[0:3], v[206:209], v[238:241], v[0:3]
	v_mfma_f32_16x16x32_bf16 v[52:55], v[202:205], v[218:221], v[52:55]
	v_mfma_f32_16x16x32_bf16 v[48:51], v[210:213], v[218:221], v[48:51]
	v_mfma_f32_16x16x32_bf16 v[36:39], v[202:205], v[226:229], v[36:39]
	v_mfma_f32_16x16x32_bf16 v[32:35], v[210:213], v[226:229], v[32:35]
	v_mfma_f32_16x16x32_bf16 v[20:23], v[202:205], v[234:237], v[20:23]
	v_mfma_f32_16x16x32_bf16 v[16:19], v[210:213], v[234:237], v[16:19]
	v_mfma_f32_16x16x32_bf16 v[4:7], v[202:205], v[242:245], v[4:7]
	v_mfma_f32_16x16x32_bf16 v[0:3], v[210:213], v[242:245], v[0:3]
	s_barrier
	s_add_i32 s36, s36, 2
	s_add_u32 s8, s8, 0x100
	s_addc_u32 s9, s9, 0
	s_add_u32 s34, s34, 0x100
	s_addc_u32 s35, s35, 0
	s_cmp_gt_u32 s36, 13
.LBB0_132:
	ds_read_b128 v[128:131], v194
	ds_read_b128 v[132:135], v194 offset:1024
	ds_read_b128 v[136:139], v194 offset:2048
	ds_read_b128 v[140:143], v194 offset:3072
	ds_read_b128 v[166:169], v195
	ds_read_b128 v[202:205], v195 offset:1024
	ds_read_b128 v[206:209], v195 offset:2048
	ds_read_b128 v[210:213], v195 offset:3072
	s_add_u32 s10, s8, 0xfffc0080
	s_addc_u32 s11, s9, -1
	s_cmp_eq_u32 s36, 12
	s_cselect_b32 s15, s1, s11
	s_cselect_b32 s14, s16, s10
	s_cselect_b32 s11, s30, s35
	s_cselect_b32 s10, s31, s34
	s_add_i32 m0, s91, 0xc000
	ds_read_b128 v[214:217], v196
	ds_read_b128 v[218:221], v196 offset:1024
	ds_read_b128 v[222:225], v196 offset:2048
	ds_read_b128 v[226:229], v196 offset:3072
	ds_read_b128 v[230:233], v196 offset:4096
	ds_read_b128 v[234:237], v196 offset:5120
	ds_read_b128 v[238:241], v196 offset:6144
	ds_read_b128 v[242:245], v196 offset:7168
	global_load_lds_dwordx4 v156, s[8:9]
	s_add_i32 m0, s91, 0xe000
	s_nop 0
	global_load_lds_dwordx4 v158, s[8:9]
	s_waitcnt vmcnt(8)
	s_waitcnt lgkmcnt(0)
	s_barrier
	s_waitcnt lgkmcnt(0)
	v_mfma_f32_16x16x32_bf16 v[124:127], v[128:131], v[214:217], v[124:127]
	v_mfma_f32_16x16x32_bf16 v[120:123], v[136:139], v[214:217], v[120:123]
	v_mfma_f32_16x16x32_bf16 v[108:111], v[128:131], v[222:225], v[108:111]
	v_mfma_f32_16x16x32_bf16 v[104:107], v[136:139], v[222:225], v[104:107]
	v_mfma_f32_16x16x32_bf16 v[92:95], v[128:131], v[230:233], v[92:95]
	v_mfma_f32_16x16x32_bf16 v[88:91], v[136:139], v[230:233], v[88:91]
	v_mfma_f32_16x16x32_bf16 v[76:79], v[128:131], v[238:241], v[76:79]
	v_mfma_f32_16x16x32_bf16 v[72:75], v[136:139], v[238:241], v[72:75]
	v_mfma_f32_16x16x32_bf16 v[124:127], v[132:135], v[218:221], v[124:127]
	v_mfma_f32_16x16x32_bf16 v[120:123], v[140:143], v[218:221], v[120:123]
	v_mfma_f32_16x16x32_bf16 v[108:111], v[132:135], v[226:229], v[108:111]
	v_mfma_f32_16x16x32_bf16 v[104:107], v[140:143], v[226:229], v[104:107]
	v_mfma_f32_16x16x32_bf16 v[92:95], v[132:135], v[234:237], v[92:95]
	v_mfma_f32_16x16x32_bf16 v[88:91], v[140:143], v[234:237], v[88:91]
	v_mfma_f32_16x16x32_bf16 v[76:79], v[132:135], v[242:245], v[76:79]
	v_mfma_f32_16x16x32_bf16 v[72:75], v[140:143], v[242:245], v[72:75]
	v_mfma_f32_16x16x32_bf16 v[116:119], v[166:169], v[214:217], v[116:119]
	v_mfma_f32_16x16x32_bf16 v[112:115], v[206:209], v[214:217], v[112:115]
	v_mfma_f32_16x16x32_bf16 v[100:103], v[166:169], v[222:225], v[100:103]
	v_mfma_f32_16x16x32_bf16 v[96:99], v[206:209], v[222:225], v[96:99]
	v_mfma_f32_16x16x32_bf16 v[84:87], v[166:169], v[230:233], v[84:87]
	v_mfma_f32_16x16x32_bf16 v[80:83], v[206:209], v[230:233], v[80:83]
	v_mfma_f32_16x16x32_bf16 v[68:71], v[166:169], v[238:241], v[68:71]
	v_mfma_f32_16x16x32_bf16 v[64:67], v[206:209], v[238:241], v[64:67]
	v_mfma_f32_16x16x32_bf16 v[116:119], v[202:205], v[218:221], v[116:119]
	v_mfma_f32_16x16x32_bf16 v[112:115], v[210:213], v[218:221], v[112:115]
	v_mfma_f32_16x16x32_bf16 v[100:103], v[202:205], v[226:229], v[100:103]
	v_mfma_f32_16x16x32_bf16 v[96:99], v[210:213], v[226:229], v[96:99]
	v_mfma_f32_16x16x32_bf16 v[84:87], v[202:205], v[234:237], v[84:87]
	v_mfma_f32_16x16x32_bf16 v[80:83], v[210:213], v[234:237], v[80:83]
	v_mfma_f32_16x16x32_bf16 v[68:71], v[202:205], v[242:245], v[68:71]
	v_mfma_f32_16x16x32_bf16 v[64:67], v[210:213], v[242:245], v[64:67]
	s_barrier
; #define PG8_STAGE(bufoff, gbase, voff) do { _Pragma("unroll") for (int _i = 0; _i < 2; ++_i) \
;         __builtin_amdgcn_global_load_lds((const unsigned*)((const char*)(gbase) + (voff)[_i]), (PG8_LAS unsigned*)(lds + (bufoff) + ldsw + _i * 8192), 16, 0, 0); } while (0)
; #define PG8_LDA(dst, b, h) do { _Pragma("unroll") for (int m = 0; m < 4; ++m) _Pragma("unroll") for (int k = 0; k < 2; ++k) dst[m][k] = *(const PG8_LAS bf16x8*)(lds + PG8_SA(b, h) + aoff + m * 2048 + k * 1024); } while (0)
; #define PG8_LDB(dst, b, h) do { _Pragma("unroll") for (int n = 0; n < 2; ++n) _Pragma("unroll") for (int k = 0; k < 2; ++k) dst[n][k] = *(const PG8_LAS bf16x8*)(lds + PG8_SB(b, h) + boff + n * 2048 + k * 1024); } while (0)
; #define PG8_MMA(ai, bj, At, Bt) do { __builtin_amdgcn_s_setprio(1); _Pragma("unroll") for (int m = 0; m < 4; ++m) _Pragma("unroll") for (int n = 0; n < 2; ++n) _Pragma("unroll") for (int k = 0; k < 2; ++k) \
;         acc[ai][bj][m][n] = __builtin_amdgcn_mfma_f32_16x16x32_bf16(Bt[n][k], At[m][k], acc[ai][bj][m][n], 0, 0, 0); __builtin_amdgcn_s_setprio(0); } while (0)
; #define PG8_WAIT_V(n) asm volatile("s_waitcnt vmcnt(" #n ")" ::: "memory")
; template <class Epi, class Sched, bool ALIGN_EPI = false, bool SP2 = false>
; __device__ __forceinline__ void gemm_phase(PG8_LAS unsigned char* lds, const Gemm g, const Sched& S, const Epi& E) {
;     ...
;             PG8_LDB(B0, 0, 0); PG8_LDB(B1, 0, 1); PG8_SCHED; PG8_LDA(At, 0, 0); PG8_STAGE(PG8_SA(1, 1), a1 + hstep, voffA);
;             PG8_WAIT_V(8); PG8_WAIT_L(0); PG8_BAR; PG8_MMA(0, 0, At, B0); PG8_MMA(0, 1, At, B1); PG8_BAR; PG8_SCHED;
;             PG8_LDA(At, 0, 1); PG8_STAGE(PG8_SB(0, 0), b2, voffB); PG8_STAGE(PG8_SB(0, 1), b2 + hstep, voffB); PG8_STAGE(PG8_SA(0, 0), a2, voffA);
;             PG8_WAIT_V(8); PG8_WAIT_L(0); PG8_BAR; PG8_MMA(1, 0, At, B0); PG8_MMA(1, 1, At, B1); PG8_BAR; PG8_SCHED;
;             PG8_LDB(B0, 1, 0); PG8_LDB(B1, 1, 1); PG8_SCHED; PG8_LDA(At, 1, 0); PG8_STAGE(PG8_SA(0, 1), a2 + hstep, voffA);
;             PG8_WAIT_V(8); PG8_WAIT_L(0); PG8_BAR; PG8_MMA(0, 0, At, B0); PG8_MMA(0, 1, At, B1); PG8_BAR; PG8_SCHED;
;             PG8_LDA(At, 1, 1); PG8_STAGE(PG8_SB(1, 0), b3, voffB); PG8_STAGE(PG8_SB(1, 1), b3 + hstep, voffB); PG8_STAGE(PG8_SA(1, 0), a3, voffA);
;             PG8_WAIT_V(8); PG8_WAIT_L(0); PG8_BAR; PG8_MMA(1, 0, At, B0); PG8_MMA(1, 1, At, B1); PG8_BAR; PG8_SCHED;
	s_add_i32 s37, s82, s43
	s_mov_b32 m0, s37
	ds_read_b128 v[214:217], v196 offset:16384
	ds_read_b128 v[218:221], v196 offset:17408
	ds_read_b128 v[222:225], v196 offset:18432
	ds_read_b128 v[226:229], v196 offset:19456
	ds_read_b128 v[230:233], v196 offset:20480
	ds_read_b128 v[234:237], v196 offset:21504
	ds_read_b128 v[238:241], v196 offset:22528
	ds_read_b128 v[242:245], v196 offset:23552
	global_load_lds_dwordx4 v146, s[10:11]
	s_add_i32 m0, s37, 0x2000
	s_add_u32 s38, s10, 0x40000
	s_addc_u32 s39, s11, 0
	s_add_u32 s98, s10, s20
	s_addc_u32 s99, s11, s21
	s_add_u32 s100, s14, s20
	s_addc_u32 s101, s15, s21
	s_add_i32 s37, s83, s43
	global_load_lds_dwordx4 v150, s[10:11]
	s_mov_b32 m0, s37
	s_nop 0
	global_load_lds_dwordx4 v146, s[38:39]
	s_add_i32 m0, s37, 0x2000
	s_nop 0
	global_load_lds_dwordx4 v150, s[38:39]
	s_mov_b32 m0, s91
	s_nop 0
	global_load_lds_dwordx4 v144, s[14:15]
	s_mov_b32 m0, s93
	s_nop 0
	global_load_lds_dwordx4 v148, s[14:15]
	s_waitcnt vmcnt(8)
	s_waitcnt lgkmcnt(0)
	s_barrier
	s_waitcnt lgkmcnt(0)
	v_mfma_f32_16x16x32_bf16 v[60:63], v[128:131], v[214:217], v[60:63]
	v_mfma_f32_16x16x32_bf16 v[56:59], v[136:139], v[214:217], v[56:59]
	v_mfma_f32_16x16x32_bf16 v[44:47], v[128:131], v[222:225], v[44:47]
	v_mfma_f32_16x16x32_bf16 v[40:43], v[136:139], v[222:225], v[40:43]
	v_mfma_f32_16x16x32_bf16 v[28:31], v[128:131], v[230:233], v[28:31]
	v_mfma_f32_16x16x32_bf16 v[24:27], v[136:139], v[230:233], v[24:27]
	v_mfma_f32_16x16x32_bf16 v[12:15], v[128:131], v[238:241], v[12:15]
	v_mfma_f32_16x16x32_bf16 v[8:11], v[136:139], v[238:241], v[8:11]
	v_mfma_f32_16x16x32_bf16 v[60:63], v[132:135], v[218:221], v[60:63]
	v_mfma_f32_16x16x32_bf16 v[56:59], v[140:143], v[218:221], v[56:59]
	v_mfma_f32_16x16x32_bf16 v[44:47], v[132:135], v[226:229], v[44:47]
	v_mfma_f32_16x16x32_bf16 v[40:43], v[140:143], v[226:229], v[40:43]
	v_mfma_f32_16x16x32_bf16 v[28:31], v[132:135], v[234:237], v[28:31]
	v_mfma_f32_16x16x32_bf16 v[24:27], v[140:143], v[234:237], v[24:27]
	v_mfma_f32_16x16x32_bf16 v[12:15], v[132:135], v[242:245], v[12:15]
	v_mfma_f32_16x16x32_bf16 v[8:11], v[140:143], v[242:245], v[8:11]
	v_mfma_f32_16x16x32_bf16 v[52:55], v[166:169], v[214:217], v[52:55]
	v_mfma_f32_16x16x32_bf16 v[48:51], v[206:209], v[214:217], v[48:51]
	v_mfma_f32_16x16x32_bf16 v[36:39], v[166:169], v[222:225], v[36:39]
	v_mfma_f32_16x16x32_bf16 v[32:35], v[206:209], v[222:225], v[32:35]
	v_mfma_f32_16x16x32_bf16 v[20:23], v[166:169], v[230:233], v[20:23]
	v_mfma_f32_16x16x32_bf16 v[16:19], v[206:209], v[230:233], v[16:19]
	v_mfma_f32_16x16x32_bf16 v[4:7], v[166:169], v[238:241], v[4:7]
	v_mfma_f32_16x16x32_bf16 v[0:3], v[206:209], v[238:241], v[0:3]
	v_mfma_f32_16x16x32_bf16 v[52:55], v[202:205], v[218:221], v[52:55]
	v_mfma_f32_16x16x32_bf16 v[48:51], v[210:213], v[218:221], v[48:51]
	v_mfma_f32_16x16x32_bf16 v[36:39], v[202:205], v[226:229], v[36:39]
	v_mfma_f32_16x16x32_bf16 v[32:35], v[210:213], v[226:229], v[32:35]
	v_mfma_f32_16x16x32_bf16 v[20:23], v[202:205], v[234:237], v[20:23]
	v_mfma_f32_16x16x32_bf16 v[16:19], v[210:213], v[234:237], v[16:19]
	v_mfma_f32_16x16x32_bf16 v[4:7], v[202:205], v[242:245], v[4:7]
	v_mfma_f32_16x16x32_bf16 v[0:3], v[210:213], v[242:245], v[0:3]
	s_barrier
	s_add_i32 s37, 0, 0x18000
	s_add_i32 s38, 0, 0x1c000
	v_add_u32_e32 v140, s37, v173
	v_add_u32_e32 v152, s38, v173
	ds_read_b128 v[128:131], v140
	ds_read_b128 v[132:135], v140 offset:1024
	ds_read_b128 v[136:139], v140 offset:2048
	ds_read_b128 v[140:143], v140 offset:3072
	ds_read_b128 v[166:169], v152
	ds_read_b128 v[202:205], v152 offset:1024
	ds_read_b128 v[206:209], v152 offset:2048
	ds_read_b128 v[210:213], v152 offset:3072
	s_add_u32 s14, s14, 0x40000
	s_addc_u32 s15, s15, 0
	s_mov_b32 m0, s52
	ds_read_b128 v[214:217], v196 offset:32768
	ds_read_b128 v[218:221], v196 offset:33792
	ds_read_b128 v[222:225], v196 offset:34816
	ds_read_b128 v[226:229], v196 offset:35840
	ds_read_b128 v[230:233], v196 offset:36864
	ds_read_b128 v[234:237], v196 offset:37888
	ds_read_b128 v[238:241], v196 offset:38912
	ds_read_b128 v[242:245], v196 offset:39936
	global_load_lds_dwordx4 v144, s[14:15]
	s_mov_b32 m0, s53
	s_nop 0
	global_load_lds_dwordx4 v148, s[14:15]
	s_waitcnt vmcnt(8)
	s_waitcnt lgkmcnt(0)
	s_barrier
; #define PG8_STAGE(bufoff, gbase, voff) do { _Pragma("unroll") for (int _i = 0; _i < 2; ++_i) \
;         __builtin_amdgcn_global_load_lds((const unsigned*)((const char*)(gbase) + (voff)[_i]), (PG8_LAS unsigned*)(lds + (bufoff) + ldsw + _i * 8192), 16, 0, 0); } while (0)
; #define PG8_LDA(dst, b, h) do { _Pragma("unroll") for (int m = 0; m < 4; ++m) _Pragma("unroll") for (int k = 0; k < 2; ++k) dst[m][k] = *(const PG8_LAS bf16x8*)(lds + PG8_SA(b, h) + aoff + m * 2048 + k * 1024); } while (0)
; #define PG8_LDB(dst, b, h) do { _Pragma("unroll") for (int n = 0; n < 2; ++n) _Pragma("unroll") for (int k = 0; k < 2; ++k) dst[n][k] = *(const PG8_LAS bf16x8*)(lds + PG8_SB(b, h) + boff + n * 2048 + k * 1024); } while (0)
; #define PG8_MMA(ai, bj, At, Bt) do { __builtin_amdgcn_s_setprio(1); _Pragma("unroll") for (int m = 0; m < 4; ++m) _Pragma("unroll") for (int n = 0; n < 2; ++n) _Pragma("unroll") for (int k = 0; k < 2; ++k) \
;         acc[ai][bj][m][n] = __builtin_amdgcn_mfma_f32_16x16x32_bf16(Bt[n][k], At[m][k], acc[ai][bj][m][n], 0, 0, 0); __builtin_amdgcn_s_setprio(0); } while (0)
; template <class Epi, class Sched, bool ALIGN_EPI = false, bool SP2 = false>
; __device__ __forceinline__ void gemm_phase(PG8_LAS unsigned char* lds, const Gemm g, const Sched& S, const Epi& E) {
;     ...
;             PG8_LDB(B0, 0, 0); PG8_LDB(B1, 0, 1); PG8_SCHED; PG8_LDA(At, 0, 0); PG8_STAGE(PG8_SA(1, 1), a1 + hstep, voffA);
;             PG8_WAIT_V(8); PG8_WAIT_L(0); PG8_BAR; PG8_MMA(0, 0, At, B0); PG8_MMA(0, 1, At, B1); PG8_BAR; PG8_SCHED;
;             PG8_LDA(At, 0, 1); PG8_STAGE(PG8_SB(0, 0), b2, voffB); PG8_STAGE(PG8_SB(0, 1), b2 + hstep, voffB); PG8_STAGE(PG8_SA(0, 0), a2, voffA);
;             PG8_WAIT_V(8); PG8_WAIT_L(0); PG8_BAR; PG8_MMA(1, 0, At, B0); PG8_MMA(1, 1, At, B1); PG8_BAR; PG8_SCHED;
;             PG8_LDB(B0, 1, 0); PG8_LDB(B1, 1, 1); PG8_SCHED; PG8_LDA(At, 1, 0); PG8_STAGE(PG8_SA(0, 1), a2 + hstep, voffA);
;             PG8_WAIT_V(8); PG8_WAIT_L(0); PG8_BAR; PG8_MMA(0, 0, At, B0); PG8_MMA(0, 1, At, B1); PG8_BAR; PG8_SCHED;
;             PG8_LDA(At, 1, 1); PG8_STAGE(PG8_SB(1, 0), b3, voffB); PG8_STAGE(PG8_SB(1, 1), b3 + hstep, voffB); PG8_STAGE(PG8_SA(1, 0), a3, voffA);
;             PG8_WAIT_V(8); PG8_WAIT_L(0); PG8_BAR; PG8_MMA(1, 0, At, B0); PG8_MMA(1, 1, At, B1); PG8_BAR; PG8_SCHED;
;     ...
;         if constexpr (ALIGN_EPI) { if (wr == 0) PG8_BAR; }
	s_waitcnt lgkmcnt(0)
	v_mfma_f32_16x16x32_bf16 v[124:127], v[128:131], v[214:217], v[124:127]
	v_mfma_f32_16x16x32_bf16 v[120:123], v[136:139], v[214:217], v[120:123]
	v_mfma_f32_16x16x32_bf16 v[108:111], v[128:131], v[222:225], v[108:111]
	v_mfma_f32_16x16x32_bf16 v[104:107], v[136:139], v[222:225], v[104:107]
	v_mfma_f32_16x16x32_bf16 v[92:95], v[128:131], v[230:233], v[92:95]
	v_mfma_f32_16x16x32_bf16 v[88:91], v[136:139], v[230:233], v[88:91]
	v_mfma_f32_16x16x32_bf16 v[76:79], v[128:131], v[238:241], v[76:79]
	v_mfma_f32_16x16x32_bf16 v[72:75], v[136:139], v[238:241], v[72:75]
	v_mfma_f32_16x16x32_bf16 v[124:127], v[132:135], v[218:221], v[124:127]
	v_mfma_f32_16x16x32_bf16 v[120:123], v[140:143], v[218:221], v[120:123]
	v_mfma_f32_16x16x32_bf16 v[108:111], v[132:135], v[226:229], v[108:111]
	v_mfma_f32_16x16x32_bf16 v[104:107], v[140:143], v[226:229], v[104:107]
	v_mfma_f32_16x16x32_bf16 v[92:95], v[132:135], v[234:237], v[92:95]
	v_mfma_f32_16x16x32_bf16 v[88:91], v[140:143], v[234:237], v[88:91]
	v_mfma_f32_16x16x32_bf16 v[76:79], v[132:135], v[242:245], v[76:79]
	v_mfma_f32_16x16x32_bf16 v[72:75], v[140:143], v[242:245], v[72:75]
	v_mfma_f32_16x16x32_bf16 v[116:119], v[166:169], v[214:217], v[116:119]
	v_mfma_f32_16x16x32_bf16 v[112:115], v[206:209], v[214:217], v[112:115]
	v_mfma_f32_16x16x32_bf16 v[100:103], v[166:169], v[222:225], v[100:103]
	v_mfma_f32_16x16x32_bf16 v[96:99], v[206:209], v[222:225], v[96:99]
	v_mfma_f32_16x16x32_bf16 v[84:87], v[166:169], v[230:233], v[84:87]
	v_mfma_f32_16x16x32_bf16 v[80:83], v[206:209], v[230:233], v[80:83]
	v_mfma_f32_16x16x32_bf16 v[68:71], v[166:169], v[238:241], v[68:71]
	v_mfma_f32_16x16x32_bf16 v[64:67], v[206:209], v[238:241], v[64:67]
	v_mfma_f32_16x16x32_bf16 v[116:119], v[202:205], v[218:221], v[116:119]
	v_mfma_f32_16x16x32_bf16 v[112:115], v[210:213], v[218:221], v[112:115]
	v_mfma_f32_16x16x32_bf16 v[100:103], v[202:205], v[226:229], v[100:103]
	v_mfma_f32_16x16x32_bf16 v[96:99], v[210:213], v[226:229], v[96:99]
	v_mfma_f32_16x16x32_bf16 v[84:87], v[202:205], v[234:237], v[84:87]
	v_mfma_f32_16x16x32_bf16 v[80:83], v[210:213], v[234:237], v[80:83]
	v_mfma_f32_16x16x32_bf16 v[68:71], v[202:205], v[242:245], v[68:71]
	v_mfma_f32_16x16x32_bf16 v[64:67], v[210:213], v[242:245], v[64:67]
	s_barrier
	s_add_i32 s14, s37, s43
	s_mov_b32 m0, s14
	ds_read_b128 v[214:217], v196 offset:49152
	ds_read_b128 v[218:221], v196 offset:50176
	ds_read_b128 v[222:225], v196 offset:51200
	ds_read_b128 v[226:229], v196 offset:52224
	ds_read_b128 v[230:233], v196 offset:53248
	ds_read_b128 v[234:237], v196 offset:54272
	ds_read_b128 v[238:241], v196 offset:55296
	ds_read_b128 v[242:245], v196 offset:56320
	global_load_lds_dwordx4 v146, s[98:99]
	s_add_i32 m0, s14, 0x2000
	s_add_u32 s10, s10, 0x40080
	s_addc_u32 s11, s11, 0
	s_add_i32 s14, s38, s43
	global_load_lds_dwordx4 v150, s[98:99]
	s_mov_b32 m0, s14
	s_nop 0
	global_load_lds_dwordx4 v146, s[10:11]
	s_add_i32 m0, s14, 0x2000
	s_nop 0
	global_load_lds_dwordx4 v150, s[10:11]
	s_mov_b32 m0, s55
	s_nop 0
	global_load_lds_dwordx4 v144, s[100:101]
	s_mov_b32 m0, s70
	s_nop 0
	global_load_lds_dwordx4 v148, s[100:101]
	s_waitcnt vmcnt(8)
	s_waitcnt lgkmcnt(0)
	s_barrier
	s_waitcnt lgkmcnt(0)
	v_mfma_f32_16x16x32_bf16 v[60:63], v[128:131], v[214:217], v[60:63]
	v_mfma_f32_16x16x32_bf16 v[56:59], v[136:139], v[214:217], v[56:59]
	v_mfma_f32_16x16x32_bf16 v[44:47], v[128:131], v[222:225], v[44:47]
	v_mfma_f32_16x16x32_bf16 v[40:43], v[136:139], v[222:225], v[40:43]
	v_mfma_f32_16x16x32_bf16 v[28:31], v[128:131], v[230:233], v[28:31]
	v_mfma_f32_16x16x32_bf16 v[24:27], v[136:139], v[230:233], v[24:27]
	v_mfma_f32_16x16x32_bf16 v[12:15], v[128:131], v[238:241], v[12:15]
	v_mfma_f32_16x16x32_bf16 v[8:11], v[136:139], v[238:241], v[8:11]
	v_mfma_f32_16x16x32_bf16 v[60:63], v[132:135], v[218:221], v[60:63]
	v_mfma_f32_16x16x32_bf16 v[56:59], v[140:143], v[218:221], v[56:59]
	v_mfma_f32_16x16x32_bf16 v[44:47], v[132:135], v[226:229], v[44:47]
	v_mfma_f32_16x16x32_bf16 v[40:43], v[140:143], v[226:229], v[40:43]
	v_mfma_f32_16x16x32_bf16 v[28:31], v[132:135], v[234:237], v[28:31]
	v_mfma_f32_16x16x32_bf16 v[24:27], v[140:143], v[234:237], v[24:27]
	v_mfma_f32_16x16x32_bf16 v[12:15], v[132:135], v[242:245], v[12:15]
	v_mfma_f32_16x16x32_bf16 v[8:11], v[140:143], v[242:245], v[8:11]
	v_mfma_f32_16x16x32_bf16 v[52:55], v[166:169], v[214:217], v[52:55]
	v_mfma_f32_16x16x32_bf16 v[48:51], v[206:209], v[214:217], v[48:51]
	v_mfma_f32_16x16x32_bf16 v[36:39], v[166:169], v[222:225], v[36:39]
	v_mfma_f32_16x16x32_bf16 v[32:35], v[206:209], v[222:225], v[32:35]
	v_mfma_f32_16x16x32_bf16 v[20:23], v[166:169], v[230:233], v[20:23]
	v_mfma_f32_16x16x32_bf16 v[16:19], v[206:209], v[230:233], v[16:19]
	v_mfma_f32_16x16x32_bf16 v[4:7], v[166:169], v[238:241], v[4:7]
	v_mfma_f32_16x16x32_bf16 v[0:3], v[206:209], v[238:241], v[0:3]
	v_mfma_f32_16x16x32_bf16 v[52:55], v[202:205], v[218:221], v[52:55]
	v_mfma_f32_16x16x32_bf16 v[48:51], v[210:213], v[218:221], v[48:51]
	v_mfma_f32_16x16x32_bf16 v[36:39], v[202:205], v[226:229], v[36:39]
	v_mfma_f32_16x16x32_bf16 v[32:35], v[210:213], v[226:229], v[32:35]
	v_mfma_f32_16x16x32_bf16 v[20:23], v[202:205], v[234:237], v[20:23]
	v_mfma_f32_16x16x32_bf16 v[16:19], v[210:213], v[234:237], v[16:19]
	v_mfma_f32_16x16x32_bf16 v[4:7], v[202:205], v[242:245], v[4:7]
	v_mfma_f32_16x16x32_bf16 v[0:3], v[210:213], v[242:245], v[0:3]
	s_barrier
	s_add_i32 s36, s36, 2
	s_add_u32 s8, s8, 0x100
	s_addc_u32 s9, s9, 0
	s_add_u32 s34, s34, 0x100
	s_addc_u32 s35, s35, 0
	s_cmp_gt_u32 s36, 13
	s_cbranch_scc0 .LBB0_132
	s_and_b64 vcc, exec, s[22:23]
	s_cbranch_vccz .LBB0_135
	s_barrier

; #define PG8_WAIT_V(n) asm volatile("s_waitcnt vmcnt(" #n ")" ::: "memory")
; #define PG8_BAR __builtin_amdgcn_s_barrier()
; template <class Epi, class Sched, bool ALIGN_EPI = false, bool SP2 = false>
; __device__ __forceinline__ void gemm_phase(PG8_LAS unsigned char* lds, const Gemm g, const Sched& S, const Epi& E) {
;     ...
;     PG8_WAIT_V(0);
;     if constexpr (!ALIGN_EPI) { if (wr == 0) PG8_BAR; }
;     PG8_BAR;
.LBB0_580:
	s_setprio 0
	s_waitcnt vmcnt(0)
	v_readlane_b32 s12, v254, 2
	v_readlane_b32 s14, v254, 4
	v_readlane_b32 s13, v254, 3
	v_readlane_b32 s15, v254, 5
	s_barrier

; #define PG8_STAGE(bufoff, gbase, voff) do { _Pragma("unroll") for (int _i = 0; _i < 2; ++_i) \
;         __builtin_amdgcn_global_load_lds((const unsigned*)((const char*)(gbase) + (voff)[_i]), (PG8_LAS unsigned*)(lds + (bufoff) + ldsw + _i * 8192), 16, 0, 0); } while (0)
; #define PG8_WAIT_V(n) asm volatile("s_waitcnt vmcnt(" #n ")" ::: "memory")
; #define PG8_BAR __builtin_amdgcn_s_barrier()
; template <class Epi, class Sched, bool ALIGN_EPI = false, bool SP2 = false>
; __device__ __forceinline__ void gemm_phase(PG8_LAS unsigned char* lds, const Gemm g, const Sched& S, const Epi& E) {
;     ...
;         PG8_STAGE(PG8_SB(1, 0), cB + kstep, voffB); PG8_STAGE(PG8_SA(1, 0), cA + kstep, voffA); PG8_STAGE(PG8_SB(1, 1), cB + hstep + kstep, voffB);
;         PG8_WAIT_V(6); PG8_BAR;
;     } else {
;         PG8_STAGE(PG8_SB(0, 0), cB, voffB); PG8_STAGE(PG8_SA(0, 0), cA, voffA); PG8_STAGE(PG8_SB(0, 1), cB + hstep, voffB); PG8_STAGE(PG8_SA(0, 1), cA + hstep, voffA);
;         if (wr == 1) PG8_BAR;
;         PG8_WAIT_V(4); PG8_BAR;
;         PG8_STAGE(PG8_SB(1, 0), cB + kstep, voffB); PG8_STAGE(PG8_SA(1, 0), cA + kstep, voffA); PG8_STAGE(PG8_SB(1, 1), cB + hstep + kstep, voffB);
;         PG8_WAIT_V(6); PG8_BAR;
.LBB0_804:
	s_add_u32 s14, s74, 0x33c58400
	s_mov_b64 s[16:17], 0x80
	s_addc_u32 s15, s75, 0
	s_and_b32 s45, s6, 3
	s_add_i32 m0, s41, 0x18000
	v_lshl_add_u64 v[6:7], v[6:7], 0, s[16:17]
	s_lshl_b32 s6, s7, 13
	s_lshl_b32 s9, s45, 12
	s_waitcnt vmcnt(2)
	s_barrier
	global_load_lds_dwordx4 v[6:7], off
	v_lshl_add_u64 v[4:5], v[4:5], 0, s[16:17]
	s_add_i32 m0, s41, 0x1a000
	s_add_i32 s46, s41, 0x8000
	s_add_i32 s47, s41, 0xa000
	global_load_lds_dwordx4 v[4:5], off
	v_lshl_add_u64 v[0:1], v[0:1], 0, s[16:17]
	s_mov_b32 m0, s46
	s_add_u32 s18, s36, 0x40080
	global_load_lds_dwordx4 v[0:1], off
	v_lshl_add_u64 v[0:1], v[2:3], 0, s[16:17]
	s_mov_b32 m0, s47
	s_addc_u32 s19, s37, 0
	global_load_lds_dwordx4 v[0:1], off
	s_add_i32 m0, s41, 0x1c000
	v_lshl_add_u64 v[0:1], s[18:19], 0, v[130:131]
	global_load_lds_dwordx4 v[0:1], off
	v_lshl_add_u64 v[0:1], s[18:19], 0, v[134:135]
	s_add_i32 m0, s41, 0x1e000
	s_cmpk_lt_u32 s8, 0x100
	global_load_lds_dwordx4 v[0:1], off
	v_bfe_u32 v1, v8, 4, 2
	v_and_b32_e32 v0, 15, v8
	v_lshlrev_b32_e32 v3, 4, v1
	v_lshl_or_b32 v148, s7, 6, v0
	v_lshl_or_b32 v0, v0, 6, v3
	v_lshlrev_b32_e32 v3, 2, v8
	v_and_b32_e32 v3, 32, v3
	v_bitop3_b32 v4, v0, s6, v3 bitop3:0xde
	v_bitop3_b32 v149, v0, s9, v3 bitop3:0xde
	v_lshlrev_b32_e32 v0, 14, v9
	v_and_b32_e32 v0, 0xffff8000, v0
	v_lshlrev_b32_e32 v2, 3, v1
	v_cmp_eq_u32_e64 s[6:7], 0, v1
	v_lshl_add_u32 v0, v10, 11, v0
	v_and_b32_e32 v1, 1, v9
	v_lshl_or_b32 v0, v1, 6, v0
	v_lshl_add_u32 v136, v11, 1, v0
	v_lshlrev_b32_e32 v0, 14, v12
	v_and_b32_e32 v0, 0xffff8000, v0
	s_waitcnt vmcnt(6)
	v_lshl_add_u32 v0, v13, 11, v0
	v_and_b32_e32 v1, 1, v12
	s_cselect_b64 s[18:19], -1, 0
	v_lshl_or_b32 v0, v1, 6, v0
	s_add_i32 s55, 0, 0x10000
	s_add_i32 s56, 0, 0x14000
	v_lshl_or_b32 v150, s45, 5, v2
	s_ashr_i32 s48, s3, 31
	s_ashr_i32 s49, s2, 31
	v_mov_b32_e32 v137, v131
	v_lshl_add_u32 v138, v14, 1, v0
	v_mov_b32_e32 v139, v131
	v_mov_b64_e32 v[140:141], 0x410
	v_mov_b64_e32 v[142:143], 0x40f
	s_movk_i32 s54, 0x83
	v_add_u32_e32 v151, s55, v149
	v_add_u32_e32 v152, s56, v149
	v_add_u32_e32 v153, 0, v4
	s_mov_b32 s57, 0
	s_barrier
	v_readfirstlane_b32 s98, v182
	s_nop 0
	s_cmpk_lt_u32 s98, 0x100
	s_cbranch_scc1 .Lprio_p3
	s_setprio 1
.Lprio_p3:
	s_branch .LBB0_807
.LBB0_805:
	s_mov_b64 s[8:9], 0

; #define PG8_STAGE(bufoff, gbase, voff) do { _Pragma("unroll") for (int _i = 0; _i < 2; ++_i) \
;         __builtin_amdgcn_global_load_lds((const unsigned*)((const char*)(gbase) + (voff)[_i]), (PG8_LAS unsigned*)(lds + (bufoff) + ldsw + _i * 8192), 16, 0, 0); } while (0)
; #define PG8_LDA(dst, b, h) do { _Pragma("unroll") for (int m = 0; m < 4; ++m) _Pragma("unroll") for (int k = 0; k < 2; ++k) dst[m][k] = *(const PG8_LAS bf16x8*)(lds + PG8_SA(b, h) + aoff + m * 2048 + k * 1024); } while (0)
; #define PG8_BAR __builtin_amdgcn_s_barrier()
; template <class Epi, class Sched, bool ALIGN_EPI = false, bool SP2 = false>
; __device__ __forceinline__ void gemm_phase(PG8_LAS unsigned char* lds, const Gemm g, const Sched& S, const Epi& E) {
;     ...
;         const char* nA = has_next ? (const char*)g.A + (size_t)nxt.pm * tstep : cA; const char* nB = has_next ? (const char*)g.Bt + (size_t)nxt.pn * tstep : cB;
;         for (int t = 0; t < nt; t += 2) {
;             const bool last = (t == nt - 2);
;             const char* a1 = cA + (size_t)(t + 1) * kstep;
;             const char* a2 = last ? nA : cA + (size_t)(t + 2) * kstep; const char* b2 = last ? nB : cB + (size_t)(t + 2) * kstep;
;             const char* a3 = a2 + kstep; const char* b3 = b2 + kstep;
;             if (last && has_next) S.a_ready(nxt);
;             if constexpr (SP2) {
;             PG8_LDB(B0, 0, 0); PG8_LDB(B1, 0, 1); PG8_SCHED; PG8_LDA(At, 0, 0); PG8_STAGE(PG8_SA(1, 1), a1 + hstep, voffA);
;             PG8_WAIT_V(8); PG8_WAIT_L(0); PG8_BAR; PG8_MMA(0, 0, At, B0); PG8_MMA(0, 1, At, B1); PG8_BAR; PG8_SCHED;
;             PG8_LDA(At, 0, 1); PG8_STAGE(PG8_SB(0, 0), b2, voffB); PG8_STAGE(PG8_SB(0, 1), b2 + hstep, voffB); PG8_STAGE(PG8_SA(0, 0), a2, voffA);
;             PG8_WAIT_V(8); PG8_WAIT_L(0); PG8_BAR; PG8_MMA(1, 0, At, B0); PG8_MMA(1, 1, At, B1); PG8_BAR; PG8_SCHED;
;             PG8_LDB(B0, 1, 0); PG8_LDB(B1, 1, 1); PG8_SCHED; PG8_LDA(At, 1, 0); PG8_STAGE(PG8_SA(0, 1), a2 + hstep, voffA);
;             PG8_WAIT_V(8); PG8_WAIT_L(0); PG8_BAR; PG8_MMA(0, 0, At, B0); PG8_MMA(0, 1, At, B1); PG8_BAR; PG8_SCHED;
;             PG8_LDA(At, 1, 1); PG8_STAGE(PG8_SB(1, 0), b3, voffB); PG8_STAGE(PG8_SB(1, 1), b3 + hstep, voffB); PG8_STAGE(PG8_SA(1, 0), a3, voffA);
;             PG8_WAIT_V(8); PG8_WAIT_L(0); PG8_BAR; PG8_MMA(1, 0, At, B0); PG8_MMA(1, 1, At, B1); PG8_BAR; PG8_SCHED;
.LBB0_809:
	s_ashr_i32 s23, s22, 31
	s_lshl_b64 s[24:25], s[22:23], 19
	s_add_u32 s24, s33, s24
	s_addc_u32 s25, s84, s25
	s_and_b64 s[26:27], s[8:9], exec
	s_cselect_b32 s23, s25, s31
	s_cselect_b32 s29, s24, s30
	s_ashr_i32 s21, s20, 31
	s_lshl_b64 s[26:27], s[20:21], 19
	s_add_u32 s26, s34, s26
	s_addc_u32 s27, s35, s27
	s_and_b64 s[38:39], s[8:9], exec
	s_cselect_b32 s21, s27, s37
	s_cselect_b32 s58, s26, s36
	s_add_u32 s30, s30, 0x40080
	s_addc_u32 s31, s31, 0
	s_add_u32 s59, s36, 0x100
	s_addc_u32 s60, s37, 0
	s_mov_b32 s61, -2
	s_waitcnt lgkmcnt(0)
	s_waitcnt vmcnt(0)
	ds_read_b128 v[144:147], v151
	ds_read_b128 v[154:157], v151 offset:1024
	ds_read_b128 v[158:161], v151 offset:2048
	ds_read_b128 v[162:165], v151 offset:3072
	ds_read_b128 v[166:169], v152
	ds_read_b128 v[170:173], v152 offset:1024
	ds_read_b128 v[174:177], v152 offset:2048
	ds_read_b128 v[178:181], v152 offset:3072
	s_add_u32 s36, s30, 0xfffc0080
	s_addc_u32 s37, s31, -1
	s_cmp_eq_u32 s61, 12
	s_cselect_b32 s39, s23, s37
	s_cselect_b32 s38, s29, s36
	s_cselect_b32 s37, s21, s60
	s_cselect_b32 s36, s58, s59
	s_add_i32 m0, s41, 0xc000
	ds_read_b128 v[188:191], v153
	ds_read_b128 v[192:195], v153 offset:1024
	ds_read_b128 v[196:199], v153 offset:2048
	ds_read_b128 v[200:203], v153 offset:3072
	ds_read_b128 v[204:207], v153 offset:4096
	ds_read_b128 v[208:211], v153 offset:5120
	ds_read_b128 v[212:215], v153 offset:6144
	ds_read_b128 v[216:219], v153 offset:7168
	global_load_lds_dwordx4 v136, s[30:31]
	s_add_i32 m0, s41, 0xe000
	s_nop 0
	global_load_lds_dwordx4 v138, s[30:31]
	s_waitcnt vmcnt(8)
	s_waitcnt lgkmcnt(0)
	s_barrier
	s_waitcnt lgkmcnt(0)
	v_mfma_f32_16x16x32_bf16 v[124:127], v[144:147], v[188:191], 0
	v_mfma_f32_16x16x32_bf16 v[120:123], v[158:161], v[188:191], 0
	v_mfma_f32_16x16x32_bf16 v[108:111], v[144:147], v[196:199], 0
	v_mfma_f32_16x16x32_bf16 v[104:107], v[158:161], v[196:199], 0
	v_mfma_f32_16x16x32_bf16 v[92:95], v[144:147], v[204:207], 0
	v_mfma_f32_16x16x32_bf16 v[88:91], v[158:161], v[204:207], 0
	v_mfma_f32_16x16x32_bf16 v[76:79], v[144:147], v[212:215], 0
	v_mfma_f32_16x16x32_bf16 v[72:75], v[158:161], v[212:215], 0
	v_mfma_f32_16x16x32_bf16 v[124:127], v[154:157], v[192:195], v[124:127]
	v_mfma_f32_16x16x32_bf16 v[120:123], v[162:165], v[192:195], v[120:123]
	v_mfma_f32_16x16x32_bf16 v[108:111], v[154:157], v[200:203], v[108:111]
	v_mfma_f32_16x16x32_bf16 v[104:107], v[162:165], v[200:203], v[104:107]
	v_mfma_f32_16x16x32_bf16 v[92:95], v[154:157], v[208:211], v[92:95]
	v_mfma_f32_16x16x32_bf16 v[88:91], v[162:165], v[208:211], v[88:91]
	v_mfma_f32_16x16x32_bf16 v[76:79], v[154:157], v[216:219], v[76:79]
	v_mfma_f32_16x16x32_bf16 v[72:75], v[162:165], v[216:219], v[72:75]
	v_mfma_f32_16x16x32_bf16 v[116:119], v[166:169], v[188:191], 0
	v_mfma_f32_16x16x32_bf16 v[112:115], v[174:177], v[188:191], 0
	v_mfma_f32_16x16x32_bf16 v[100:103], v[166:169], v[196:199], 0
	v_mfma_f32_16x16x32_bf16 v[96:99], v[174:177], v[196:199], 0
	v_mfma_f32_16x16x32_bf16 v[84:87], v[166:169], v[204:207], 0
	v_mfma_f32_16x16x32_bf16 v[80:83], v[174:177], v[204:207], 0
	v_mfma_f32_16x16x32_bf16 v[68:71], v[166:169], v[212:215], 0
	v_mfma_f32_16x16x32_bf16 v[64:67], v[174:177], v[212:215], 0
	v_mfma_f32_16x16x32_bf16 v[116:119], v[170:173], v[192:195], v[116:119]
	v_mfma_f32_16x16x32_bf16 v[112:115], v[178:181], v[192:195], v[112:115]
	v_mfma_f32_16x16x32_bf16 v[100:103], v[170:173], v[200:203], v[100:103]
	v_mfma_f32_16x16x32_bf16 v[96:99], v[178:181], v[200:203], v[96:99]
	v_mfma_f32_16x16x32_bf16 v[84:87], v[170:173], v[208:211], v[84:87]
	v_mfma_f32_16x16x32_bf16 v[80:83], v[178:181], v[208:211], v[80:83]
	v_mfma_f32_16x16x32_bf16 v[68:71], v[170:173], v[216:219], v[68:71]
	v_mfma_f32_16x16x32_bf16 v[64:67], v[178:181], v[216:219], v[64:67]
	s_barrier
	s_add_i32 s62, s55, s40
	s_mov_b32 m0, s62
	ds_read_b128 v[188:191], v153 offset:16384
	ds_read_b128 v[192:195], v153 offset:17408
	ds_read_b128 v[196:199], v153 offset:18432
	ds_read_b128 v[200:203], v153 offset:19456
	ds_read_b128 v[204:207], v153 offset:20480
	ds_read_b128 v[208:211], v153 offset:21504
	ds_read_b128 v[212:215], v153 offset:22528
	ds_read_b128 v[216:219], v153 offset:23552
	global_load_lds_dwordx4 v130, s[36:37]
	s_add_i32 m0, s62, 0x2000
	s_add_u32 s62, s36, 0x40000
	s_addc_u32 s63, s37, 0
	s_add_u32 s98, s36, s16
	s_addc_u32 s99, s37, s17
	s_add_u32 s100, s38, s16
	s_addc_u32 s101, s39, s17
	s_add_i32 s64, s56, s40
	global_load_lds_dwordx4 v134, s[36:37]
	s_mov_b32 m0, s64
	s_nop 0
	global_load_lds_dwordx4 v130, s[62:63]
	s_add_i32 m0, s64, 0x2000
	s_nop 0
	global_load_lds_dwordx4 v134, s[62:63]
	s_mov_b32 m0, s41
	s_nop 0
	global_load_lds_dwordx4 v128, s[38:39]
	s_mov_b32 m0, s42
	s_nop 0
	global_load_lds_dwordx4 v132, s[38:39]
	s_waitcnt vmcnt(8)
	s_waitcnt lgkmcnt(0)
	s_barrier
; #define PG8_STAGE(bufoff, gbase, voff) do { _Pragma("unroll") for (int _i = 0; _i < 2; ++_i) \
;         __builtin_amdgcn_global_load_lds((const unsigned*)((const char*)(gbase) + (voff)[_i]), (PG8_LAS unsigned*)(lds + (bufoff) + ldsw + _i * 8192), 16, 0, 0); } while (0)
; #define PG8_LDA(dst, b, h) do { _Pragma("unroll") for (int m = 0; m < 4; ++m) _Pragma("unroll") for (int k = 0; k < 2; ++k) dst[m][k] = *(const PG8_LAS bf16x8*)(lds + PG8_SA(b, h) + aoff + m * 2048 + k * 1024); } while (0)
; #define PG8_LDB(dst, b, h) do { _Pragma("unroll") for (int n = 0; n < 2; ++n) _Pragma("unroll") for (int k = 0; k < 2; ++k) dst[n][k] = *(const PG8_LAS bf16x8*)(lds + PG8_SB(b, h) + boff + n * 2048 + k * 1024); } while (0)
; #define PG8_MMA(ai, bj, At, Bt) do { __builtin_amdgcn_s_setprio(1); _Pragma("unroll") for (int m = 0; m < 4; ++m) _Pragma("unroll") for (int n = 0; n < 2; ++n) _Pragma("unroll") for (int k = 0; k < 2; ++k) \
;         acc[ai][bj][m][n] = __builtin_amdgcn_mfma_f32_16x16x32_bf16(Bt[n][k], At[m][k], acc[ai][bj][m][n], 0, 0, 0); __builtin_amdgcn_s_setprio(0); } while (0)
; #define PG8_WAIT_V(n) asm volatile("s_waitcnt vmcnt(" #n ")" ::: "memory")
; template <class Epi, class Sched, bool ALIGN_EPI = false, bool SP2 = false>
; __device__ __forceinline__ void gemm_phase(PG8_LAS unsigned char* lds, const Gemm g, const Sched& S, const Epi& E) {
;     ...
;             PG8_LDB(B0, 0, 0); PG8_LDB(B1, 0, 1); PG8_SCHED; PG8_LDA(At, 0, 0); PG8_STAGE(PG8_SA(1, 1), a1 + hstep, voffA);
;             PG8_WAIT_V(8); PG8_WAIT_L(0); PG8_BAR; PG8_MMA(0, 0, At, B0); PG8_MMA(0, 1, At, B1); PG8_BAR; PG8_SCHED;
;             PG8_LDA(At, 0, 1); PG8_STAGE(PG8_SB(0, 0), b2, voffB); PG8_STAGE(PG8_SB(0, 1), b2 + hstep, voffB); PG8_STAGE(PG8_SA(0, 0), a2, voffA);
;             PG8_WAIT_V(8); PG8_WAIT_L(0); PG8_BAR; PG8_MMA(1, 0, At, B0); PG8_MMA(1, 1, At, B1); PG8_BAR; PG8_SCHED;
;             PG8_LDB(B0, 1, 0); PG8_LDB(B1, 1, 1); PG8_SCHED; PG8_LDA(At, 1, 0); PG8_STAGE(PG8_SA(0, 1), a2 + hstep, voffA);
;             PG8_WAIT_V(8); PG8_WAIT_L(0); PG8_BAR; PG8_MMA(0, 0, At, B0); PG8_MMA(0, 1, At, B1); PG8_BAR; PG8_SCHED;
;             PG8_LDA(At, 1, 1); PG8_STAGE(PG8_SB(1, 0), b3, voffB); PG8_STAGE(PG8_SB(1, 1), b3 + hstep, voffB); PG8_STAGE(PG8_SA(1, 0), a3, voffA);
;             PG8_WAIT_V(8); PG8_WAIT_L(0); PG8_BAR; PG8_MMA(1, 0, At, B0); PG8_MMA(1, 1, At, B1); PG8_BAR; PG8_SCHED;
	s_waitcnt lgkmcnt(0)
	v_mfma_f32_16x16x32_bf16 v[60:63], v[144:147], v[188:191], 0
	v_mfma_f32_16x16x32_bf16 v[56:59], v[158:161], v[188:191], 0
	v_mfma_f32_16x16x32_bf16 v[44:47], v[144:147], v[196:199], 0
	v_mfma_f32_16x16x32_bf16 v[40:43], v[158:161], v[196:199], 0
	v_mfma_f32_16x16x32_bf16 v[28:31], v[144:147], v[204:207], 0
	v_mfma_f32_16x16x32_bf16 v[24:27], v[158:161], v[204:207], 0
	v_mfma_f32_16x16x32_bf16 v[12:15], v[144:147], v[212:215], 0
	v_mfma_f32_16x16x32_bf16 v[8:11], v[158:161], v[212:215], 0
	v_mfma_f32_16x16x32_bf16 v[60:63], v[154:157], v[192:195], v[60:63]
	v_mfma_f32_16x16x32_bf16 v[56:59], v[162:165], v[192:195], v[56:59]
	v_mfma_f32_16x16x32_bf16 v[44:47], v[154:157], v[200:203], v[44:47]
	v_mfma_f32_16x16x32_bf16 v[40:43], v[162:165], v[200:203], v[40:43]
	v_mfma_f32_16x16x32_bf16 v[28:31], v[154:157], v[208:211], v[28:31]
	v_mfma_f32_16x16x32_bf16 v[24:27], v[162:165], v[208:211], v[24:27]
	v_mfma_f32_16x16x32_bf16 v[12:15], v[154:157], v[216:219], v[12:15]
	v_mfma_f32_16x16x32_bf16 v[8:11], v[162:165], v[216:219], v[8:11]
	v_mfma_f32_16x16x32_bf16 v[52:55], v[166:169], v[188:191], 0
	v_mfma_f32_16x16x32_bf16 v[48:51], v[174:177], v[188:191], 0
	v_mfma_f32_16x16x32_bf16 v[36:39], v[166:169], v[196:199], 0
	v_mfma_f32_16x16x32_bf16 v[32:35], v[174:177], v[196:199], 0
	v_mfma_f32_16x16x32_bf16 v[20:23], v[166:169], v[204:207], 0
	v_mfma_f32_16x16x32_bf16 v[16:19], v[174:177], v[204:207], 0
	v_mfma_f32_16x16x32_bf16 v[4:7], v[166:169], v[212:215], 0
	v_mfma_f32_16x16x32_bf16 v[0:3], v[174:177], v[212:215], 0
	v_mfma_f32_16x16x32_bf16 v[52:55], v[170:173], v[192:195], v[52:55]
	v_mfma_f32_16x16x32_bf16 v[48:51], v[178:181], v[192:195], v[48:51]
	v_mfma_f32_16x16x32_bf16 v[36:39], v[170:173], v[200:203], v[36:39]
	v_mfma_f32_16x16x32_bf16 v[32:35], v[178:181], v[200:203], v[32:35]
	v_mfma_f32_16x16x32_bf16 v[20:23], v[170:173], v[208:211], v[20:23]
	v_mfma_f32_16x16x32_bf16 v[16:19], v[178:181], v[208:211], v[16:19]
	v_mfma_f32_16x16x32_bf16 v[4:7], v[170:173], v[216:219], v[4:7]
	v_mfma_f32_16x16x32_bf16 v[0:3], v[178:181], v[216:219], v[0:3]
	s_barrier
	s_add_i32 s62, 0, 0x18000
	s_add_i32 s63, 0, 0x1c000
	v_add_u32_e32 v162, s62, v149
	v_add_u32_e32 v178, s63, v149
	ds_read_b128 v[144:147], v162
	ds_read_b128 v[154:157], v162 offset:1024
	ds_read_b128 v[158:161], v162 offset:2048
	ds_read_b128 v[162:165], v162 offset:3072
	ds_read_b128 v[166:169], v178
	ds_read_b128 v[170:173], v178 offset:1024
	ds_read_b128 v[174:177], v178 offset:2048
	ds_read_b128 v[178:181], v178 offset:3072
	s_add_u32 s38, s38, 0x40000
	s_addc_u32 s39, s39, 0
	s_mov_b32 m0, s43
	ds_read_b128 v[188:191], v153 offset:32768
	ds_read_b128 v[192:195], v153 offset:33792
	ds_read_b128 v[196:199], v153 offset:34816
	ds_read_b128 v[200:203], v153 offset:35840
	ds_read_b128 v[204:207], v153 offset:36864
	ds_read_b128 v[208:211], v153 offset:37888
	ds_read_b128 v[212:215], v153 offset:38912
	ds_read_b128 v[216:219], v153 offset:39936
	global_load_lds_dwordx4 v128, s[38:39]
	s_mov_b32 m0, s44
	s_nop 0
	global_load_lds_dwordx4 v132, s[38:39]
	s_waitcnt vmcnt(8)
	s_waitcnt lgkmcnt(0)
	s_barrier
	s_waitcnt lgkmcnt(0)
	v_mfma_f32_16x16x32_bf16 v[124:127], v[144:147], v[188:191], v[124:127]
	v_mfma_f32_16x16x32_bf16 v[120:123], v[158:161], v[188:191], v[120:123]
	v_mfma_f32_16x16x32_bf16 v[108:111], v[144:147], v[196:199], v[108:111]
	v_mfma_f32_16x16x32_bf16 v[104:107], v[158:161], v[196:199], v[104:107]
	v_mfma_f32_16x16x32_bf16 v[92:95], v[144:147], v[204:207], v[92:95]
	v_mfma_f32_16x16x32_bf16 v[88:91], v[158:161], v[204:207], v[88:91]
	v_mfma_f32_16x16x32_bf16 v[76:79], v[144:147], v[212:215], v[76:79]
	v_mfma_f32_16x16x32_bf16 v[72:75], v[158:161], v[212:215], v[72:75]
	v_mfma_f32_16x16x32_bf16 v[124:127], v[154:157], v[192:195], v[124:127]
	v_mfma_f32_16x16x32_bf16 v[120:123], v[162:165], v[192:195], v[120:123]
	v_mfma_f32_16x16x32_bf16 v[108:111], v[154:157], v[200:203], v[108:111]
	v_mfma_f32_16x16x32_bf16 v[104:107], v[162:165], v[200:203], v[104:107]
	v_mfma_f32_16x16x32_bf16 v[92:95], v[154:157], v[208:211], v[92:95]
	v_mfma_f32_16x16x32_bf16 v[88:91], v[162:165], v[208:211], v[88:91]
	v_mfma_f32_16x16x32_bf16 v[76:79], v[154:157], v[216:219], v[76:79]
	v_mfma_f32_16x16x32_bf16 v[72:75], v[162:165], v[216:219], v[72:75]
	v_mfma_f32_16x16x32_bf16 v[116:119], v[166:169], v[188:191], v[116:119]
	v_mfma_f32_16x16x32_bf16 v[112:115], v[174:177], v[188:191], v[112:115]
	v_mfma_f32_16x16x32_bf16 v[100:103], v[166:169], v[196:199], v[100:103]
	v_mfma_f32_16x16x32_bf16 v[96:99], v[174:177], v[196:199], v[96:99]
	v_mfma_f32_16x16x32_bf16 v[84:87], v[166:169], v[204:207], v[84:87]
	v_mfma_f32_16x16x32_bf16 v[80:83], v[174:177], v[204:207], v[80:83]
	v_mfma_f32_16x16x32_bf16 v[68:71], v[166:169], v[212:215], v[68:71]
	v_mfma_f32_16x16x32_bf16 v[64:67], v[174:177], v[212:215], v[64:67]
	v_mfma_f32_16x16x32_bf16 v[116:119], v[170:173], v[192:195], v[116:119]
	v_mfma_f32_16x16x32_bf16 v[112:115], v[178:181], v[192:195], v[112:115]
	v_mfma_f32_16x16x32_bf16 v[100:103], v[170:173], v[200:203], v[100:103]
	v_mfma_f32_16x16x32_bf16 v[96:99], v[178:181], v[200:203], v[96:99]
	v_mfma_f32_16x16x32_bf16 v[84:87], v[170:173], v[208:211], v[84:87]
	v_mfma_f32_16x16x32_bf16 v[80:83], v[178:181], v[208:211], v[80:83]
	v_mfma_f32_16x16x32_bf16 v[68:71], v[170:173], v[216:219], v[68:71]
	v_mfma_f32_16x16x32_bf16 v[64:67], v[178:181], v[216:219], v[64:67]
	s_barrier
; #define PG8_STAGE(bufoff, gbase, voff) do { _Pragma("unroll") for (int _i = 0; _i < 2; ++_i) \
;         __builtin_amdgcn_global_load_lds((const unsigned*)((const char*)(gbase) + (voff)[_i]), (PG8_LAS unsigned*)(lds + (bufoff) + ldsw + _i * 8192), 16, 0, 0); } while (0)
; #define PG8_LDA(dst, b, h) do { _Pragma("unroll") for (int m = 0; m < 4; ++m) _Pragma("unroll") for (int k = 0; k < 2; ++k) dst[m][k] = *(const PG8_LAS bf16x8*)(lds + PG8_SA(b, h) + aoff + m * 2048 + k * 1024); } while (0)
; #define PG8_LDB(dst, b, h) do { _Pragma("unroll") for (int n = 0; n < 2; ++n) _Pragma("unroll") for (int k = 0; k < 2; ++k) dst[n][k] = *(const PG8_LAS bf16x8*)(lds + PG8_SB(b, h) + boff + n * 2048 + k * 1024); } while (0)
; #define PG8_MMA(ai, bj, At, Bt) do { __builtin_amdgcn_s_setprio(1); _Pragma("unroll") for (int m = 0; m < 4; ++m) _Pragma("unroll") for (int n = 0; n < 2; ++n) _Pragma("unroll") for (int k = 0; k < 2; ++k) \
;         acc[ai][bj][m][n] = __builtin_amdgcn_mfma_f32_16x16x32_bf16(Bt[n][k], At[m][k], acc[ai][bj][m][n], 0, 0, 0); __builtin_amdgcn_s_setprio(0); } while (0)
; #define PG8_WAIT_V(n) asm volatile("s_waitcnt vmcnt(" #n ")" ::: "memory")
; template <class Epi, class Sched, bool ALIGN_EPI = false, bool SP2 = false>
; __device__ __forceinline__ void gemm_phase(PG8_LAS unsigned char* lds, const Gemm g, const Sched& S, const Epi& E) {
;     ...
;             PG8_LDB(B0, 0, 0); PG8_LDB(B1, 0, 1); PG8_SCHED; PG8_LDA(At, 0, 0); PG8_STAGE(PG8_SA(1, 1), a1 + hstep, voffA);
;             PG8_WAIT_V(8); PG8_WAIT_L(0); PG8_BAR; PG8_MMA(0, 0, At, B0); PG8_MMA(0, 1, At, B1); PG8_BAR; PG8_SCHED;
;             PG8_LDA(At, 0, 1); PG8_STAGE(PG8_SB(0, 0), b2, voffB); PG8_STAGE(PG8_SB(0, 1), b2 + hstep, voffB); PG8_STAGE(PG8_SA(0, 0), a2, voffA);
;             PG8_WAIT_V(8); PG8_WAIT_L(0); PG8_BAR; PG8_MMA(1, 0, At, B0); PG8_MMA(1, 1, At, B1); PG8_BAR; PG8_SCHED;
;             PG8_LDB(B0, 1, 0); PG8_LDB(B1, 1, 1); PG8_SCHED; PG8_LDA(At, 1, 0); PG8_STAGE(PG8_SA(0, 1), a2 + hstep, voffA);
;             PG8_WAIT_V(8); PG8_WAIT_L(0); PG8_BAR; PG8_MMA(0, 0, At, B0); PG8_MMA(0, 1, At, B1); PG8_BAR; PG8_SCHED;
;             PG8_LDA(At, 1, 1); PG8_STAGE(PG8_SB(1, 0), b3, voffB); PG8_STAGE(PG8_SB(1, 1), b3 + hstep, voffB); PG8_STAGE(PG8_SA(1, 0), a3, voffA);
;             PG8_WAIT_V(8); PG8_WAIT_L(0); PG8_BAR; PG8_MMA(1, 0, At, B0); PG8_MMA(1, 1, At, B1); PG8_BAR; PG8_SCHED;
	s_add_i32 s38, s62, s40
	s_mov_b32 m0, s38
	ds_read_b128 v[188:191], v153 offset:49152
	ds_read_b128 v[192:195], v153 offset:50176
	ds_read_b128 v[196:199], v153 offset:51200
	ds_read_b128 v[200:203], v153 offset:52224
	ds_read_b128 v[204:207], v153 offset:53248
	ds_read_b128 v[208:211], v153 offset:54272
	ds_read_b128 v[212:215], v153 offset:55296
	ds_read_b128 v[216:219], v153 offset:56320
	global_load_lds_dwordx4 v130, s[98:99]
	s_add_i32 m0, s38, 0x2000
	s_add_u32 s36, s36, 0x40080
	s_addc_u32 s37, s37, 0
	s_add_i32 s38, s63, s40
	global_load_lds_dwordx4 v134, s[98:99]
	s_mov_b32 m0, s38
	s_nop 0
	global_load_lds_dwordx4 v130, s[36:37]
	s_add_i32 m0, s38, 0x2000
	s_nop 0
	global_load_lds_dwordx4 v134, s[36:37]
	s_mov_b32 m0, s46
	s_nop 0
	global_load_lds_dwordx4 v128, s[100:101]
	s_mov_b32 m0, s47
	s_nop 0
	global_load_lds_dwordx4 v132, s[100:101]
	s_waitcnt vmcnt(8)
	s_waitcnt lgkmcnt(0)
	s_barrier
	s_waitcnt lgkmcnt(0)
	v_mfma_f32_16x16x32_bf16 v[60:63], v[144:147], v[188:191], v[60:63]
	v_mfma_f32_16x16x32_bf16 v[56:59], v[158:161], v[188:191], v[56:59]
	v_mfma_f32_16x16x32_bf16 v[44:47], v[144:147], v[196:199], v[44:47]
	v_mfma_f32_16x16x32_bf16 v[40:43], v[158:161], v[196:199], v[40:43]
	v_mfma_f32_16x16x32_bf16 v[28:31], v[144:147], v[204:207], v[28:31]
	v_mfma_f32_16x16x32_bf16 v[24:27], v[158:161], v[204:207], v[24:27]
	v_mfma_f32_16x16x32_bf16 v[12:15], v[144:147], v[212:215], v[12:15]
	v_mfma_f32_16x16x32_bf16 v[8:11], v[158:161], v[212:215], v[8:11]
	v_mfma_f32_16x16x32_bf16 v[60:63], v[154:157], v[192:195], v[60:63]
	v_mfma_f32_16x16x32_bf16 v[56:59], v[162:165], v[192:195], v[56:59]
	v_mfma_f32_16x16x32_bf16 v[44:47], v[154:157], v[200:203], v[44:47]
	v_mfma_f32_16x16x32_bf16 v[40:43], v[162:165], v[200:203], v[40:43]
	v_mfma_f32_16x16x32_bf16 v[28:31], v[154:157], v[208:211], v[28:31]
	v_mfma_f32_16x16x32_bf16 v[24:27], v[162:165], v[208:211], v[24:27]
	v_mfma_f32_16x16x32_bf16 v[12:15], v[154:157], v[216:219], v[12:15]
	v_mfma_f32_16x16x32_bf16 v[8:11], v[162:165], v[216:219], v[8:11]
	v_mfma_f32_16x16x32_bf16 v[52:55], v[166:169], v[188:191], v[52:55]
	v_mfma_f32_16x16x32_bf16 v[48:51], v[174:177], v[188:191], v[48:51]
	v_mfma_f32_16x16x32_bf16 v[36:39], v[166:169], v[196:199], v[36:39]
	v_mfma_f32_16x16x32_bf16 v[32:35], v[174:177], v[196:199], v[32:35]
	v_mfma_f32_16x16x32_bf16 v[20:23], v[166:169], v[204:207], v[20:23]
	v_mfma_f32_16x16x32_bf16 v[16:19], v[174:177], v[204:207], v[16:19]
	v_mfma_f32_16x16x32_bf16 v[4:7], v[166:169], v[212:215], v[4:7]
	v_mfma_f32_16x16x32_bf16 v[0:3], v[174:177], v[212:215], v[0:3]
	v_mfma_f32_16x16x32_bf16 v[52:55], v[170:173], v[192:195], v[52:55]
	v_mfma_f32_16x16x32_bf16 v[48:51], v[178:181], v[192:195], v[48:51]
	v_mfma_f32_16x16x32_bf16 v[36:39], v[170:173], v[200:203], v[36:39]
	v_mfma_f32_16x16x32_bf16 v[32:35], v[178:181], v[200:203], v[32:35]
	v_mfma_f32_16x16x32_bf16 v[20:23], v[170:173], v[208:211], v[20:23]
	v_mfma_f32_16x16x32_bf16 v[16:19], v[178:181], v[208:211], v[16:19]
	v_mfma_f32_16x16x32_bf16 v[4:7], v[170:173], v[216:219], v[4:7]
	v_mfma_f32_16x16x32_bf16 v[0:3], v[178:181], v[216:219], v[0:3]
	s_barrier
	s_add_i32 s61, s61, 2
	s_add_u32 s30, s30, 0x100
	s_addc_u32 s31, s31, 0
	s_add_u32 s59, s59, 0x100
	s_addc_u32 s60, s60, 0
	s_cmp_gt_u32 s61, 13
.LBB0_810:
	ds_read_b128 v[144:147], v151
	ds_read_b128 v[154:157], v151 offset:1024
	ds_read_b128 v[158:161], v151 offset:2048
	ds_read_b128 v[162:165], v151 offset:3072
	ds_read_b128 v[166:169], v152
	ds_read_b128 v[170:173], v152 offset:1024
	ds_read_b128 v[174:177], v152 offset:2048
	ds_read_b128 v[178:181], v152 offset:3072
	s_add_u32 s36, s30, 0xfffc0080
	s_addc_u32 s37, s31, -1
	s_cmp_eq_u32 s61, 12
	s_cselect_b32 s39, s23, s37
	s_cselect_b32 s38, s29, s36
	s_cselect_b32 s37, s21, s60
	s_cselect_b32 s36, s58, s59
	s_add_i32 m0, s41, 0xc000
	ds_read_b128 v[188:191], v153
	ds_read_b128 v[192:195], v153 offset:1024
	ds_read_b128 v[196:199], v153 offset:2048
	ds_read_b128 v[200:203], v153 offset:3072
	ds_read_b128 v[204:207], v153 offset:4096
	ds_read_b128 v[208:211], v153 offset:5120
	ds_read_b128 v[212:215], v153 offset:6144
	ds_read_b128 v[216:219], v153 offset:7168
	global_load_lds_dwordx4 v136, s[30:31]
	s_add_i32 m0, s41, 0xe000
	s_nop 0
	global_load_lds_dwordx4 v138, s[30:31]
	s_waitcnt vmcnt(8)
	s_waitcnt lgkmcnt(0)
	s_barrier
	s_waitcnt lgkmcnt(0)
	v_mfma_f32_16x16x32_bf16 v[124:127], v[144:147], v[188:191], v[124:127]
	v_mfma_f32_16x16x32_bf16 v[120:123], v[158:161], v[188:191], v[120:123]
	v_mfma_f32_16x16x32_bf16 v[108:111], v[144:147], v[196:199], v[108:111]
	v_mfma_f32_16x16x32_bf16 v[104:107], v[158:161], v[196:199], v[104:107]
	v_mfma_f32_16x16x32_bf16 v[92:95], v[144:147], v[204:207], v[92:95]
	v_mfma_f32_16x16x32_bf16 v[88:91], v[158:161], v[204:207], v[88:91]
	v_mfma_f32_16x16x32_bf16 v[76:79], v[144:147], v[212:215], v[76:79]
	v_mfma_f32_16x16x32_bf16 v[72:75], v[158:161], v[212:215], v[72:75]
	v_mfma_f32_16x16x32_bf16 v[124:127], v[154:157], v[192:195], v[124:127]
	v_mfma_f32_16x16x32_bf16 v[120:123], v[162:165], v[192:195], v[120:123]
	v_mfma_f32_16x16x32_bf16 v[108:111], v[154:157], v[200:203], v[108:111]
	v_mfma_f32_16x16x32_bf16 v[104:107], v[162:165], v[200:203], v[104:107]
	v_mfma_f32_16x16x32_bf16 v[92:95], v[154:157], v[208:211], v[92:95]
	v_mfma_f32_16x16x32_bf16 v[88:91], v[162:165], v[208:211], v[88:91]
	v_mfma_f32_16x16x32_bf16 v[76:79], v[154:157], v[216:219], v[76:79]
	v_mfma_f32_16x16x32_bf16 v[72:75], v[162:165], v[216:219], v[72:75]
	v_mfma_f32_16x16x32_bf16 v[116:119], v[166:169], v[188:191], v[116:119]
	v_mfma_f32_16x16x32_bf16 v[112:115], v[174:177], v[188:191], v[112:115]
	v_mfma_f32_16x16x32_bf16 v[100:103], v[166:169], v[196:199], v[100:103]
	v_mfma_f32_16x16x32_bf16 v[96:99], v[174:177], v[196:199], v[96:99]
	v_mfma_f32_16x16x32_bf16 v[84:87], v[166:169], v[204:207], v[84:87]
	v_mfma_f32_16x16x32_bf16 v[80:83], v[174:177], v[204:207], v[80:83]
	v_mfma_f32_16x16x32_bf16 v[68:71], v[166:169], v[212:215], v[68:71]
	v_mfma_f32_16x16x32_bf16 v[64:67], v[174:177], v[212:215], v[64:67]
	v_mfma_f32_16x16x32_bf16 v[116:119], v[170:173], v[192:195], v[116:119]
	v_mfma_f32_16x16x32_bf16 v[112:115], v[178:181], v[192:195], v[112:115]
	v_mfma_f32_16x16x32_bf16 v[100:103], v[170:173], v[200:203], v[100:103]
	v_mfma_f32_16x16x32_bf16 v[96:99], v[178:181], v[200:203], v[96:99]
	v_mfma_f32_16x16x32_bf16 v[84:87], v[170:173], v[208:211], v[84:87]
	v_mfma_f32_16x16x32_bf16 v[80:83], v[178:181], v[208:211], v[80:83]
	v_mfma_f32_16x16x32_bf16 v[68:71], v[170:173], v[216:219], v[68:71]
	v_mfma_f32_16x16x32_bf16 v[64:67], v[178:181], v[216:219], v[64:67]
	s_barrier
; #define PG8_STAGE(bufoff, gbase, voff) do { _Pragma("unroll") for (int _i = 0; _i < 2; ++_i) \
;         __builtin_amdgcn_global_load_lds((const unsigned*)((const char*)(gbase) + (voff)[_i]), (PG8_LAS unsigned*)(lds + (bufoff) + ldsw + _i * 8192), 16, 0, 0); } while (0)
; #define PG8_LDA(dst, b, h) do { _Pragma("unroll") for (int m = 0; m < 4; ++m) _Pragma("unroll") for (int k = 0; k < 2; ++k) dst[m][k] = *(const PG8_LAS bf16x8*)(lds + PG8_SA(b, h) + aoff + m * 2048 + k * 1024); } while (0)
; #define PG8_LDB(dst, b, h) do { _Pragma("unroll") for (int n = 0; n < 2; ++n) _Pragma("unroll") for (int k = 0; k < 2; ++k) dst[n][k] = *(const PG8_LAS bf16x8*)(lds + PG8_SB(b, h) + boff + n * 2048 + k * 1024); } while (0)
; #define PG8_MMA(ai, bj, At, Bt) do { __builtin_amdgcn_s_setprio(1); _Pragma("unroll") for (int m = 0; m < 4; ++m) _Pragma("unroll") for (int n = 0; n < 2; ++n) _Pragma("unroll") for (int k = 0; k < 2; ++k) \
;         acc[ai][bj][m][n] = __builtin_amdgcn_mfma_f32_16x16x32_bf16(Bt[n][k], At[m][k], acc[ai][bj][m][n], 0, 0, 0); __builtin_amdgcn_s_setprio(0); } while (0)
; #define PG8_WAIT_V(n) asm volatile("s_waitcnt vmcnt(" #n ")" ::: "memory")
; template <class Epi, class Sched, bool ALIGN_EPI = false, bool SP2 = false>
; __device__ __forceinline__ void gemm_phase(PG8_LAS unsigned char* lds, const Gemm g, const Sched& S, const Epi& E) {
;     ...
;             PG8_LDB(B0, 0, 0); PG8_LDB(B1, 0, 1); PG8_SCHED; PG8_LDA(At, 0, 0); PG8_STAGE(PG8_SA(1, 1), a1 + hstep, voffA);
;             PG8_WAIT_V(8); PG8_WAIT_L(0); PG8_BAR; PG8_MMA(0, 0, At, B0); PG8_MMA(0, 1, At, B1); PG8_BAR; PG8_SCHED;
;             PG8_LDA(At, 0, 1); PG8_STAGE(PG8_SB(0, 0), b2, voffB); PG8_STAGE(PG8_SB(0, 1), b2 + hstep, voffB); PG8_STAGE(PG8_SA(0, 0), a2, voffA);
;             PG8_WAIT_V(8); PG8_WAIT_L(0); PG8_BAR; PG8_MMA(1, 0, At, B0); PG8_MMA(1, 1, At, B1); PG8_BAR; PG8_SCHED;
;             PG8_LDB(B0, 1, 0); PG8_LDB(B1, 1, 1); PG8_SCHED; PG8_LDA(At, 1, 0); PG8_STAGE(PG8_SA(0, 1), a2 + hstep, voffA);
;             PG8_WAIT_V(8); PG8_WAIT_L(0); PG8_BAR; PG8_MMA(0, 0, At, B0); PG8_MMA(0, 1, At, B1); PG8_BAR; PG8_SCHED;
;             PG8_LDA(At, 1, 1); PG8_STAGE(PG8_SB(1, 0), b3, voffB); PG8_STAGE(PG8_SB(1, 1), b3 + hstep, voffB); PG8_STAGE(PG8_SA(1, 0), a3, voffA);
;             PG8_WAIT_V(8); PG8_WAIT_L(0); PG8_BAR; PG8_MMA(1, 0, At, B0); PG8_MMA(1, 1, At, B1); PG8_BAR; PG8_SCHED;
	s_add_i32 s62, s55, s40
	s_mov_b32 m0, s62
	ds_read_b128 v[188:191], v153 offset:16384
	ds_read_b128 v[192:195], v153 offset:17408
	ds_read_b128 v[196:199], v153 offset:18432
	ds_read_b128 v[200:203], v153 offset:19456
	ds_read_b128 v[204:207], v153 offset:20480
	ds_read_b128 v[208:211], v153 offset:21504
	ds_read_b128 v[212:215], v153 offset:22528
	ds_read_b128 v[216:219], v153 offset:23552
	global_load_lds_dwordx4 v130, s[36:37]
	s_add_i32 m0, s62, 0x2000
	s_add_u32 s62, s36, 0x40000
	s_addc_u32 s63, s37, 0
	s_add_u32 s98, s36, s16
	s_addc_u32 s99, s37, s17
	s_add_u32 s100, s38, s16
	s_addc_u32 s101, s39, s17
	s_add_i32 s64, s56, s40
	global_load_lds_dwordx4 v134, s[36:37]
	s_mov_b32 m0, s64
	s_nop 0
	global_load_lds_dwordx4 v130, s[62:63]
	s_add_i32 m0, s64, 0x2000
	s_nop 0
	global_load_lds_dwordx4 v134, s[62:63]
	s_mov_b32 m0, s41
	s_nop 0
	global_load_lds_dwordx4 v128, s[38:39]
	s_mov_b32 m0, s42
	s_nop 0
	global_load_lds_dwordx4 v132, s[38:39]
	s_waitcnt vmcnt(8)
	s_waitcnt lgkmcnt(0)
	s_barrier
	s_waitcnt lgkmcnt(0)
	v_mfma_f32_16x16x32_bf16 v[60:63], v[144:147], v[188:191], v[60:63]
	v_mfma_f32_16x16x32_bf16 v[56:59], v[158:161], v[188:191], v[56:59]
	v_mfma_f32_16x16x32_bf16 v[44:47], v[144:147], v[196:199], v[44:47]
	v_mfma_f32_16x16x32_bf16 v[40:43], v[158:161], v[196:199], v[40:43]
	v_mfma_f32_16x16x32_bf16 v[28:31], v[144:147], v[204:207], v[28:31]
	v_mfma_f32_16x16x32_bf16 v[24:27], v[158:161], v[204:207], v[24:27]
	v_mfma_f32_16x16x32_bf16 v[12:15], v[144:147], v[212:215], v[12:15]
	v_mfma_f32_16x16x32_bf16 v[8:11], v[158:161], v[212:215], v[8:11]
	v_mfma_f32_16x16x32_bf16 v[60:63], v[154:157], v[192:195], v[60:63]
	v_mfma_f32_16x16x32_bf16 v[56:59], v[162:165], v[192:195], v[56:59]
	v_mfma_f32_16x16x32_bf16 v[44:47], v[154:157], v[200:203], v[44:47]
	v_mfma_f32_16x16x32_bf16 v[40:43], v[162:165], v[200:203], v[40:43]
	v_mfma_f32_16x16x32_bf16 v[28:31], v[154:157], v[208:211], v[28:31]
	v_mfma_f32_16x16x32_bf16 v[24:27], v[162:165], v[208:211], v[24:27]
	v_mfma_f32_16x16x32_bf16 v[12:15], v[154:157], v[216:219], v[12:15]
	v_mfma_f32_16x16x32_bf16 v[8:11], v[162:165], v[216:219], v[8:11]
	v_mfma_f32_16x16x32_bf16 v[52:55], v[166:169], v[188:191], v[52:55]
	v_mfma_f32_16x16x32_bf16 v[48:51], v[174:177], v[188:191], v[48:51]
	v_mfma_f32_16x16x32_bf16 v[36:39], v[166:169], v[196:199], v[36:39]
	v_mfma_f32_16x16x32_bf16 v[32:35], v[174:177], v[196:199], v[32:35]
	v_mfma_f32_16x16x32_bf16 v[20:23], v[166:169], v[204:207], v[20:23]
	v_mfma_f32_16x16x32_bf16 v[16:19], v[174:177], v[204:207], v[16:19]
	v_mfma_f32_16x16x32_bf16 v[4:7], v[166:169], v[212:215], v[4:7]
	v_mfma_f32_16x16x32_bf16 v[0:3], v[174:177], v[212:215], v[0:3]
	v_mfma_f32_16x16x32_bf16 v[52:55], v[170:173], v[192:195], v[52:55]
	v_mfma_f32_16x16x32_bf16 v[48:51], v[178:181], v[192:195], v[48:51]
	v_mfma_f32_16x16x32_bf16 v[36:39], v[170:173], v[200:203], v[36:39]
	v_mfma_f32_16x16x32_bf16 v[32:35], v[178:181], v[200:203], v[32:35]
	v_mfma_f32_16x16x32_bf16 v[20:23], v[170:173], v[208:211], v[20:23]
	v_mfma_f32_16x16x32_bf16 v[16:19], v[178:181], v[208:211], v[16:19]
	v_mfma_f32_16x16x32_bf16 v[4:7], v[170:173], v[216:219], v[4:7]
	v_mfma_f32_16x16x32_bf16 v[0:3], v[178:181], v[216:219], v[0:3]
	s_barrier
	s_add_i32 s62, 0, 0x18000
	s_add_i32 s63, 0, 0x1c000
	v_add_u32_e32 v162, s62, v149
	v_add_u32_e32 v178, s63, v149
	ds_read_b128 v[144:147], v162
	ds_read_b128 v[154:157], v162 offset:1024
	ds_read_b128 v[158:161], v162 offset:2048
	ds_read_b128 v[162:165], v162 offset:3072
	ds_read_b128 v[166:169], v178
	ds_read_b128 v[170:173], v178 offset:1024
	ds_read_b128 v[174:177], v178 offset:2048
	ds_read_b128 v[178:181], v178 offset:3072
	s_add_u32 s38, s38, 0x40000
	s_addc_u32 s39, s39, 0
	s_mov_b32 m0, s43
	ds_read_b128 v[188:191], v153 offset:32768
	ds_read_b128 v[192:195], v153 offset:33792
	ds_read_b128 v[196:199], v153 offset:34816
	ds_read_b128 v[200:203], v153 offset:35840
	ds_read_b128 v[204:207], v153 offset:36864
	ds_read_b128 v[208:211], v153 offset:37888
	ds_read_b128 v[212:215], v153 offset:38912
	ds_read_b128 v[216:219], v153 offset:39936
	global_load_lds_dwordx4 v128, s[38:39]
	s_mov_b32 m0, s44
	s_nop 0
	global_load_lds_dwordx4 v132, s[38:39]
	s_waitcnt vmcnt(8)
	s_waitcnt lgkmcnt(0)
	s_barrier
; #define PG8_STAGE(bufoff, gbase, voff) do { _Pragma("unroll") for (int _i = 0; _i < 2; ++_i) \
;         __builtin_amdgcn_global_load_lds((const unsigned*)((const char*)(gbase) + (voff)[_i]), (PG8_LAS unsigned*)(lds + (bufoff) + ldsw + _i * 8192), 16, 0, 0); } while (0)
; #define PG8_LDA(dst, b, h) do { _Pragma("unroll") for (int m = 0; m < 4; ++m) _Pragma("unroll") for (int k = 0; k < 2; ++k) dst[m][k] = *(const PG8_LAS bf16x8*)(lds + PG8_SA(b, h) + aoff + m * 2048 + k * 1024); } while (0)
; #define PG8_LDB(dst, b, h) do { _Pragma("unroll") for (int n = 0; n < 2; ++n) _Pragma("unroll") for (int k = 0; k < 2; ++k) dst[n][k] = *(const PG8_LAS bf16x8*)(lds + PG8_SB(b, h) + boff + n * 2048 + k * 1024); } while (0)
; #define PG8_MMA(ai, bj, At, Bt) do { __builtin_amdgcn_s_setprio(1); _Pragma("unroll") for (int m = 0; m < 4; ++m) _Pragma("unroll") for (int n = 0; n < 2; ++n) _Pragma("unroll") for (int k = 0; k < 2; ++k) \
;         acc[ai][bj][m][n] = __builtin_amdgcn_mfma_f32_16x16x32_bf16(Bt[n][k], At[m][k], acc[ai][bj][m][n], 0, 0, 0); __builtin_amdgcn_s_setprio(0); } while (0)
; template <class Epi, class Sched, bool ALIGN_EPI = false, bool SP2 = false>
; __device__ __forceinline__ void gemm_phase(PG8_LAS unsigned char* lds, const Gemm g, const Sched& S, const Epi& E) {
;     ...
;             PG8_LDB(B0, 0, 0); PG8_LDB(B1, 0, 1); PG8_SCHED; PG8_LDA(At, 0, 0); PG8_STAGE(PG8_SA(1, 1), a1 + hstep, voffA);
;             PG8_WAIT_V(8); PG8_WAIT_L(0); PG8_BAR; PG8_MMA(0, 0, At, B0); PG8_MMA(0, 1, At, B1); PG8_BAR; PG8_SCHED;
;             PG8_LDA(At, 0, 1); PG8_STAGE(PG8_SB(0, 0), b2, voffB); PG8_STAGE(PG8_SB(0, 1), b2 + hstep, voffB); PG8_STAGE(PG8_SA(0, 0), a2, voffA);
;             PG8_WAIT_V(8); PG8_WAIT_L(0); PG8_BAR; PG8_MMA(1, 0, At, B0); PG8_MMA(1, 1, At, B1); PG8_BAR; PG8_SCHED;
;             PG8_LDB(B0, 1, 0); PG8_LDB(B1, 1, 1); PG8_SCHED; PG8_LDA(At, 1, 0); PG8_STAGE(PG8_SA(0, 1), a2 + hstep, voffA);
;             PG8_WAIT_V(8); PG8_WAIT_L(0); PG8_BAR; PG8_MMA(0, 0, At, B0); PG8_MMA(0, 1, At, B1); PG8_BAR; PG8_SCHED;
;             PG8_LDA(At, 1, 1); PG8_STAGE(PG8_SB(1, 0), b3, voffB); PG8_STAGE(PG8_SB(1, 1), b3 + hstep, voffB); PG8_STAGE(PG8_SA(1, 0), a3, voffA);
;             PG8_WAIT_V(8); PG8_WAIT_L(0); PG8_BAR; PG8_MMA(1, 0, At, B0); PG8_MMA(1, 1, At, B1); PG8_BAR; PG8_SCHED;
;     ...
;         if constexpr (ALIGN_EPI) { if (wr == 0) PG8_BAR; }
	s_waitcnt lgkmcnt(0)
	v_mfma_f32_16x16x32_bf16 v[124:127], v[144:147], v[188:191], v[124:127]
	v_mfma_f32_16x16x32_bf16 v[120:123], v[158:161], v[188:191], v[120:123]
	v_mfma_f32_16x16x32_bf16 v[108:111], v[144:147], v[196:199], v[108:111]
	v_mfma_f32_16x16x32_bf16 v[104:107], v[158:161], v[196:199], v[104:107]
	v_mfma_f32_16x16x32_bf16 v[92:95], v[144:147], v[204:207], v[92:95]
	v_mfma_f32_16x16x32_bf16 v[88:91], v[158:161], v[204:207], v[88:91]
	v_mfma_f32_16x16x32_bf16 v[76:79], v[144:147], v[212:215], v[76:79]
	v_mfma_f32_16x16x32_bf16 v[72:75], v[158:161], v[212:215], v[72:75]
	v_mfma_f32_16x16x32_bf16 v[124:127], v[154:157], v[192:195], v[124:127]
	v_mfma_f32_16x16x32_bf16 v[120:123], v[162:165], v[192:195], v[120:123]
	v_mfma_f32_16x16x32_bf16 v[108:111], v[154:157], v[200:203], v[108:111]
	v_mfma_f32_16x16x32_bf16 v[104:107], v[162:165], v[200:203], v[104:107]
	v_mfma_f32_16x16x32_bf16 v[92:95], v[154:157], v[208:211], v[92:95]
	v_mfma_f32_16x16x32_bf16 v[88:91], v[162:165], v[208:211], v[88:91]
	v_mfma_f32_16x16x32_bf16 v[76:79], v[154:157], v[216:219], v[76:79]
	v_mfma_f32_16x16x32_bf16 v[72:75], v[162:165], v[216:219], v[72:75]
	v_mfma_f32_16x16x32_bf16 v[116:119], v[166:169], v[188:191], v[116:119]
	v_mfma_f32_16x16x32_bf16 v[112:115], v[174:177], v[188:191], v[112:115]
	v_mfma_f32_16x16x32_bf16 v[100:103], v[166:169], v[196:199], v[100:103]
	v_mfma_f32_16x16x32_bf16 v[96:99], v[174:177], v[196:199], v[96:99]
	v_mfma_f32_16x16x32_bf16 v[84:87], v[166:169], v[204:207], v[84:87]
	v_mfma_f32_16x16x32_bf16 v[80:83], v[174:177], v[204:207], v[80:83]
	v_mfma_f32_16x16x32_bf16 v[68:71], v[166:169], v[212:215], v[68:71]
	v_mfma_f32_16x16x32_bf16 v[64:67], v[174:177], v[212:215], v[64:67]
	v_mfma_f32_16x16x32_bf16 v[116:119], v[170:173], v[192:195], v[116:119]
	v_mfma_f32_16x16x32_bf16 v[112:115], v[178:181], v[192:195], v[112:115]
	v_mfma_f32_16x16x32_bf16 v[100:103], v[170:173], v[200:203], v[100:103]
	v_mfma_f32_16x16x32_bf16 v[96:99], v[178:181], v[200:203], v[96:99]
	v_mfma_f32_16x16x32_bf16 v[84:87], v[170:173], v[208:211], v[84:87]
	v_mfma_f32_16x16x32_bf16 v[80:83], v[178:181], v[208:211], v[80:83]
	v_mfma_f32_16x16x32_bf16 v[68:71], v[170:173], v[216:219], v[68:71]
	v_mfma_f32_16x16x32_bf16 v[64:67], v[178:181], v[216:219], v[64:67]
	s_barrier
	s_add_i32 s38, s62, s40
	s_mov_b32 m0, s38
	ds_read_b128 v[188:191], v153 offset:49152
	ds_read_b128 v[192:195], v153 offset:50176
	ds_read_b128 v[196:199], v153 offset:51200
	ds_read_b128 v[200:203], v153 offset:52224
	ds_read_b128 v[204:207], v153 offset:53248
	ds_read_b128 v[208:211], v153 offset:54272
	ds_read_b128 v[212:215], v153 offset:55296
	ds_read_b128 v[216:219], v153 offset:56320
	global_load_lds_dwordx4 v130, s[98:99]
	s_add_i32 m0, s38, 0x2000
	s_add_u32 s36, s36, 0x40080
	s_addc_u32 s37, s37, 0
	s_add_i32 s38, s63, s40
	global_load_lds_dwordx4 v134, s[98:99]
	s_mov_b32 m0, s38
	s_nop 0
	global_load_lds_dwordx4 v130, s[36:37]
	s_add_i32 m0, s38, 0x2000
	s_nop 0
	global_load_lds_dwordx4 v134, s[36:37]
	s_mov_b32 m0, s46
	s_nop 0
	global_load_lds_dwordx4 v128, s[100:101]
	s_mov_b32 m0, s47
	s_nop 0
	global_load_lds_dwordx4 v132, s[100:101]
	s_waitcnt vmcnt(8)
	s_waitcnt lgkmcnt(0)
	s_barrier
	s_waitcnt lgkmcnt(0)
	v_mfma_f32_16x16x32_bf16 v[60:63], v[144:147], v[188:191], v[60:63]
	v_mfma_f32_16x16x32_bf16 v[56:59], v[158:161], v[188:191], v[56:59]
	v_mfma_f32_16x16x32_bf16 v[44:47], v[144:147], v[196:199], v[44:47]
	v_mfma_f32_16x16x32_bf16 v[40:43], v[158:161], v[196:199], v[40:43]
	v_mfma_f32_16x16x32_bf16 v[28:31], v[144:147], v[204:207], v[28:31]
	v_mfma_f32_16x16x32_bf16 v[24:27], v[158:161], v[204:207], v[24:27]
	v_mfma_f32_16x16x32_bf16 v[12:15], v[144:147], v[212:215], v[12:15]
	v_mfma_f32_16x16x32_bf16 v[8:11], v[158:161], v[212:215], v[8:11]
	v_mfma_f32_16x16x32_bf16 v[60:63], v[154:157], v[192:195], v[60:63]
	v_mfma_f32_16x16x32_bf16 v[56:59], v[162:165], v[192:195], v[56:59]
	v_mfma_f32_16x16x32_bf16 v[44:47], v[154:157], v[200:203], v[44:47]
	v_mfma_f32_16x16x32_bf16 v[40:43], v[162:165], v[200:203], v[40:43]
	v_mfma_f32_16x16x32_bf16 v[28:31], v[154:157], v[208:211], v[28:31]
	v_mfma_f32_16x16x32_bf16 v[24:27], v[162:165], v[208:211], v[24:27]
	v_mfma_f32_16x16x32_bf16 v[12:15], v[154:157], v[216:219], v[12:15]
	v_mfma_f32_16x16x32_bf16 v[8:11], v[162:165], v[216:219], v[8:11]
	v_mfma_f32_16x16x32_bf16 v[52:55], v[166:169], v[188:191], v[52:55]
	v_mfma_f32_16x16x32_bf16 v[48:51], v[174:177], v[188:191], v[48:51]
	v_mfma_f32_16x16x32_bf16 v[36:39], v[166:169], v[196:199], v[36:39]
	v_mfma_f32_16x16x32_bf16 v[32:35], v[174:177], v[196:199], v[32:35]
	v_mfma_f32_16x16x32_bf16 v[20:23], v[166:169], v[204:207], v[20:23]
	v_mfma_f32_16x16x32_bf16 v[16:19], v[174:177], v[204:207], v[16:19]
	v_mfma_f32_16x16x32_bf16 v[4:7], v[166:169], v[212:215], v[4:7]
	v_mfma_f32_16x16x32_bf16 v[0:3], v[174:177], v[212:215], v[0:3]
	v_mfma_f32_16x16x32_bf16 v[52:55], v[170:173], v[192:195], v[52:55]
	v_mfma_f32_16x16x32_bf16 v[48:51], v[178:181], v[192:195], v[48:51]
	v_mfma_f32_16x16x32_bf16 v[36:39], v[170:173], v[200:203], v[36:39]
	v_mfma_f32_16x16x32_bf16 v[32:35], v[178:181], v[200:203], v[32:35]
	v_mfma_f32_16x16x32_bf16 v[20:23], v[170:173], v[208:211], v[20:23]
	v_mfma_f32_16x16x32_bf16 v[16:19], v[178:181], v[208:211], v[16:19]
	v_mfma_f32_16x16x32_bf16 v[4:7], v[170:173], v[216:219], v[4:7]
	v_mfma_f32_16x16x32_bf16 v[0:3], v[178:181], v[216:219], v[0:3]
	s_barrier
	s_add_i32 s61, s61, 2
	s_add_u32 s30, s30, 0x100
	s_addc_u32 s31, s31, 0
	s_add_u32 s59, s59, 0x100
	s_addc_u32 s60, s60, 0
	s_cmp_gt_u32 s61, 13
	s_cbranch_scc0 .LBB0_810
	s_and_b64 vcc, exec, s[18:19]
	s_cbranch_vccz .LBB0_813
	s_barrier

; #define PG8_WAIT_V(n) asm volatile("s_waitcnt vmcnt(" #n ")" ::: "memory")
; #define PG8_BAR __builtin_amdgcn_s_barrier()
; template <class Epi, class Sched, bool ALIGN_EPI = false, bool SP2 = false>
; __device__ __forceinline__ void gemm_phase(PG8_LAS unsigned char* lds, const Gemm g, const Sched& S, const Epi& E) {
;     ...
;     PG8_WAIT_V(0);
;     if constexpr (!ALIGN_EPI) { if (wr == 0) PG8_BAR; }
;     PG8_BAR;
.LBB0_832:
	s_setprio 0
	s_waitcnt vmcnt(0)
	s_barrier

; #define PG8_STAGE(bufoff, gbase, voff) do { _Pragma("unroll") for (int _i = 0; _i < 2; ++_i) \
;         __builtin_amdgcn_global_load_lds((const unsigned*)((const char*)(gbase) + (voff)[_i]), (PG8_LAS unsigned*)(lds + (bufoff) + ldsw + _i * 8192), 16, 0, 0); } while (0)
; #define PG8_WAIT_V(n) asm volatile("s_waitcnt vmcnt(" #n ")" ::: "memory")
; #define PG8_BAR __builtin_amdgcn_s_barrier()
; template <class Epi, class Sched, bool ALIGN_EPI = false, bool SP2 = false>
; __device__ __forceinline__ void gemm_phase(PG8_LAS unsigned char* lds, const Gemm g, const Sched& S, const Epi& E) {
;     ...
;         PG8_STAGE(PG8_SB(1, 0), cB + kstep, voffB); PG8_STAGE(PG8_SA(1, 0), cA + kstep, voffA); PG8_STAGE(PG8_SB(1, 1), cB + hstep + kstep, voffB);
;         PG8_WAIT_V(6); PG8_BAR;
;     } else {
;         PG8_STAGE(PG8_SB(0, 0), cB, voffB); PG8_STAGE(PG8_SA(0, 0), cA, voffA); PG8_STAGE(PG8_SB(0, 1), cB + hstep, voffB); PG8_STAGE(PG8_SA(0, 1), cA + hstep, voffA);
;         if (wr == 1) PG8_BAR;
;         PG8_WAIT_V(4); PG8_BAR;
;         PG8_STAGE(PG8_SB(1, 0), cB + kstep, voffB); PG8_STAGE(PG8_SA(1, 0), cA + kstep, voffA); PG8_STAGE(PG8_SB(1, 1), cB + hstep + kstep, voffB);
;         PG8_WAIT_V(6); PG8_BAR;
.LBB0_854:
	s_lshl_b32 s12, s12, 5
	s_and_b32 s17, s12, 0x60
	s_mov_b64 s[12:13], 0x80
	s_add_i32 m0, s38, 0x18000
	v_lshl_add_u64 v[6:7], v[6:7], 0, s[12:13]
	s_lshl_b32 s16, s8, 13
	s_lshl_b32 s18, s17, 7
	s_waitcnt vmcnt(2)
	s_barrier
	global_load_lds_dwordx4 v[6:7], off
	v_lshl_add_u64 v[4:5], v[4:5], 0, s[12:13]
	s_add_i32 m0, s38, 0x1a000
	s_add_i32 s42, s38, 0x8000
	s_add_i32 s43, s38, 0xa000
	global_load_lds_dwordx4 v[4:5], off
	v_lshl_add_u64 v[0:1], v[0:1], 0, s[12:13]
	s_mov_b32 m0, s42
	s_add_u32 s14, s28, 0x40080
	global_load_lds_dwordx4 v[0:1], off
	v_lshl_add_u64 v[0:1], v[2:3], 0, s[12:13]
	s_mov_b32 m0, s43
	s_addc_u32 s15, s29, 0
	global_load_lds_dwordx4 v[0:1], off
	s_add_i32 m0, s38, 0x1c000
	v_lshl_add_u64 v[0:1], s[14:15], 0, v[132:133]
	global_load_lds_dwordx4 v[0:1], off
	v_lshl_add_u64 v[0:1], s[14:15], 0, v[128:129]
	s_add_i32 m0, s38, 0x1e000
	s_cmpk_lt_u32 s7, 0x100
	global_load_lds_dwordx4 v[0:1], off
	v_lshrrev_b32_e32 v0, 1, v10
	v_and_b32_e32 v0, 24, v0
	v_and_b32_e32 v1, 15, v10
	v_lshlrev_b32_e32 v2, 1, v0
	v_lshl_or_b32 v150, s8, 6, v1
	v_lshl_or_b32 v1, v1, 6, v2
	v_lshlrev_b32_e32 v2, 2, v10
	v_and_b32_e32 v2, 32, v2
	v_bitop3_b32 v3, v1, s16, v2 bitop3:0xde
	v_bitop3_b32 v151, v1, s18, v2 bitop3:0xde
	v_lshlrev_b32_e32 v1, 14, v13
	v_and_b32_e32 v1, 0xffff8000, v1
	v_lshl_add_u32 v1, v12, 11, v1
	v_and_b32_e32 v2, 1, v13
	v_lshl_or_b32 v1, v2, 6, v1
	v_lshl_add_u32 v138, v14, 1, v1
	v_lshlrev_b32_e32 v1, 14, v8
	v_and_b32_e32 v1, 0xffff8000, v1
	s_waitcnt vmcnt(6)
	v_lshl_add_u32 v1, v9, 11, v1
	v_and_b32_e32 v2, 1, v8
	s_cselect_b64 s[14:15], -1, 0
	v_lshl_or_b32 v1, v2, 6, v1
	s_add_i32 s45, 0, 0x10000
	s_add_i32 s46, 0, 0x14000
	s_sext_i32_i16 s25, s6
	s_ashr_i32 s44, s3, 31
	v_mov_b32_e32 v139, v137
	v_lshl_add_u32 v140, v11, 1, v1
	v_mov_b32_e32 v141, v137
	v_mov_b64_e32 v[142:143], 0x1658
	v_mov_b64_e32 v[144:145], 0x1657
	v_add_u32_e32 v152, s45, v151
	v_add_u32_e32 v153, s46, v151
	v_add_u32_e32 v154, 0, v3
	v_mov_b32_e32 v155, 0x358637bd
	s_mov_b32 s47, 0x800000
	s_movk_i32 s48, 0x1600
	s_lshl_b32 s8, s17, 1
	v_lshlrev_b32_e32 v136, 1, v0
	s_mov_b32 s49, s9
	v_and_b32_e32 v246, 0xff, v182
	v_lshlrev_b32_e32 v247, 2, v246
	v_add_u32_e32 v247, 0x20000, v247
	v_lshlrev_b32_e32 v246, 6, v246
	s_waitcnt vmcnt(0)
	s_barrier
	v_readfirstlane_b32 s98, v182
	s_nop 0
	s_cmpk_lt_u32 s98, 0x100
	s_cbranch_scc1 .Lprio_p4
	s_setprio 1
.Lprio_p4:
	s_branch .LBB0_857
.LBB0_855:
	s_mov_b64 s[6:7], 0

; #define PG8_LDA(dst, b, h) do { _Pragma("unroll") for (int m = 0; m < 4; ++m) _Pragma("unroll") for (int k = 0; k < 2; ++k) dst[m][k] = *(const PG8_LAS bf16x8*)(lds + PG8_SA(b, h) + aoff + m * 2048 + k * 1024); } while (0)
; template <class Epi, class Sched, bool ALIGN_EPI = false, bool SP2 = false>
; __device__ __forceinline__ void gemm_phase(PG8_LAS unsigned char* lds, const Gemm g, const Sched& S, const Epi& E) {
;     ...
;         const char* nA = has_next ? (const char*)g.A + (size_t)nxt.pm * tstep : cA; const char* nB = has_next ? (const char*)g.Bt + (size_t)nxt.pn * tstep : cB;
;         for (int t = 0; t < nt; t += 2) {
;             const bool last = (t == nt - 2);
;             const char* a1 = cA + (size_t)(t + 1) * kstep;
;             const char* a2 = last ? nA : cA + (size_t)(t + 2) * kstep; const char* b2 = last ? nB : cB + (size_t)(t + 2) * kstep;
;             const char* a3 = a2 + kstep; const char* b3 = b2 + kstep;
;             if (last && has_next) S.a_ready(nxt);
;             if constexpr (SP2) {
;             PG8_LDB(B0, 0, 0); PG8_LDB(B1, 0, 1); PG8_SCHED; PG8_LDA(At, 0, 0); PG8_STAGE(PG8_SA(1, 1), a1 + hstep, voffA);
;             PG8_WAIT_V(8); PG8_WAIT_L(0); PG8_BAR; PG8_MMA(0, 0, At, B0); PG8_MMA(0, 1, At, B1); PG8_BAR; PG8_SCHED;
;             PG8_LDA(At, 0, 1); PG8_STAGE(PG8_SB(0, 0), b2, voffB); PG8_STAGE(PG8_SB(0, 1), b2 + hstep, voffB); PG8_STAGE(PG8_SA(0, 0), a2, voffA);
;             PG8_WAIT_V(8); PG8_WAIT_L(0); PG8_BAR; PG8_MMA(1, 0, At, B0); PG8_MMA(1, 1, At, B1); PG8_BAR; PG8_SCHED;
;             PG8_LDB(B0, 1, 0); PG8_LDB(B1, 1, 1); PG8_SCHED; PG8_LDA(At, 1, 0); PG8_STAGE(PG8_SA(0, 1), a2 + hstep, voffA);
;             PG8_WAIT_V(8); PG8_WAIT_L(0); PG8_BAR; PG8_MMA(0, 0, At, B0); PG8_MMA(0, 1, At, B1); PG8_BAR; PG8_SCHED;
;             PG8_LDA(At, 1, 1); PG8_STAGE(PG8_SB(1, 0), b3, voffB); PG8_STAGE(PG8_SB(1, 1), b3 + hstep, voffB); PG8_STAGE(PG8_SA(1, 0), a3, voffA);
;             PG8_WAIT_V(8); PG8_WAIT_L(0); PG8_BAR; PG8_MMA(1, 0, At, B0); PG8_MMA(1, 1, At, B1); PG8_BAR; PG8_SCHED;
;     DI void operator()(const f32x4 (&acc)[2][2][4][2], const Unit& u, int wr, int wc, int fr, int fq) const {
;     ...
;                 const float* sp = SSQ + (size_t)row * 16;
;                 const f32x4 s0 = *(const f32x4*)sp, s1 = *(const f32x4*)(sp + 4), s2 = *(const f32x4*)(sp + 8), s3 = *(const f32x4*)(sp + 12);
.LBB0_859:
	s_ashr_i32 s19, s18, 31
	s_lshl_b64 s[20:21], s[18:19], 19
	s_add_u32 s20, s50, s20
	s_addc_u32 s21, s51, s21
	s_and_b64 s[22:23], s[6:7], exec
	s_cselect_b32 s19, s21, s27
	s_cselect_b32 s54, s20, s26
	s_ashr_i32 s17, s16, 31
	s_lshl_b64 s[22:23], s[16:17], 19
	s_add_u32 s22, s33, s22
	s_addc_u32 s23, s34, s23
	s_and_b64 s[30:31], s[6:7], exec
	s_cselect_b32 s17, s23, s29
	s_cselect_b32 s55, s22, s28
	s_add_u32 s26, s26, 0x40080
	s_addc_u32 s27, s27, 0
	s_add_u32 s56, s28, 0x100
	s_addc_u32 s57, s29, 0
	s_mov_b32 s58, -2
	s_lshl_b32 s59, s24, 14
	v_add_u32_e32 v248, s59, v246
	global_load_dwordx4 v[230:233], v248, s[0:1]
	global_load_dwordx4 v[234:237], v248, s[0:1] offset:16
	global_load_dwordx4 v[238:241], v248, s[0:1] offset:32
	global_load_dwordx4 v[242:245], v248, s[0:1] offset:48
	ds_read_b128 v[146:149], v152
	ds_read_b128 v[156:159], v152 offset:1024
	ds_read_b128 v[160:163], v152 offset:2048
	ds_read_b128 v[164:167], v152 offset:3072
	ds_read_b128 v[168:171], v153
	ds_read_b128 v[172:175], v153 offset:1024
	ds_read_b128 v[176:179], v153 offset:2048
	ds_read_b128 v[186:189], v153 offset:3072
	s_add_u32 s28, s26, 0xfffc0080
	s_addc_u32 s29, s27, -1
	s_cmp_eq_u32 s58, 12
	s_cselect_b32 s31, s19, s29
	s_cselect_b32 s30, s54, s28
	s_cselect_b32 s29, s17, s57
	s_cselect_b32 s28, s55, s56
	s_add_i32 m0, s38, 0xc000
	ds_read_b128 v[190:193], v154
	ds_read_b128 v[194:197], v154 offset:1024
	ds_read_b128 v[198:201], v154 offset:2048
	ds_read_b128 v[202:205], v154 offset:3072
	ds_read_b128 v[206:209], v154 offset:4096
	ds_read_b128 v[210:213], v154 offset:5120
	ds_read_b128 v[214:217], v154 offset:6144
	ds_read_b128 v[218:221], v154 offset:7168
	global_load_lds_dwordx4 v138, s[26:27]
	s_add_i32 m0, s38, 0xe000
	s_nop 0
	global_load_lds_dwordx4 v140, s[26:27]
	s_waitcnt vmcnt(20)
	s_waitcnt lgkmcnt(0)
	s_barrier
	s_waitcnt lgkmcnt(0)
	v_mfma_f32_16x16x32_bf16 v[124:127], v[146:149], v[190:193], 0
	v_mfma_f32_16x16x32_bf16 v[120:123], v[160:163], v[190:193], 0
	v_mfma_f32_16x16x32_bf16 v[108:111], v[146:149], v[198:201], 0
	v_mfma_f32_16x16x32_bf16 v[104:107], v[160:163], v[198:201], 0
	v_mfma_f32_16x16x32_bf16 v[92:95], v[146:149], v[206:209], 0
	v_mfma_f32_16x16x32_bf16 v[88:91], v[160:163], v[206:209], 0
	v_mfma_f32_16x16x32_bf16 v[76:79], v[146:149], v[214:217], 0
	v_mfma_f32_16x16x32_bf16 v[72:75], v[160:163], v[214:217], 0
	v_mfma_f32_16x16x32_bf16 v[124:127], v[156:159], v[194:197], v[124:127]
	v_mfma_f32_16x16x32_bf16 v[120:123], v[164:167], v[194:197], v[120:123]
	v_mfma_f32_16x16x32_bf16 v[108:111], v[156:159], v[202:205], v[108:111]
	v_mfma_f32_16x16x32_bf16 v[104:107], v[164:167], v[202:205], v[104:107]
	v_mfma_f32_16x16x32_bf16 v[92:95], v[156:159], v[210:213], v[92:95]
	v_mfma_f32_16x16x32_bf16 v[88:91], v[164:167], v[210:213], v[88:91]
	v_mfma_f32_16x16x32_bf16 v[76:79], v[156:159], v[218:221], v[76:79]
	v_mfma_f32_16x16x32_bf16 v[72:75], v[164:167], v[218:221], v[72:75]
	v_mfma_f32_16x16x32_bf16 v[116:119], v[168:171], v[190:193], 0
	v_mfma_f32_16x16x32_bf16 v[112:115], v[176:179], v[190:193], 0
	v_mfma_f32_16x16x32_bf16 v[100:103], v[168:171], v[198:201], 0
	v_mfma_f32_16x16x32_bf16 v[96:99], v[176:179], v[198:201], 0
	v_mfma_f32_16x16x32_bf16 v[84:87], v[168:171], v[206:209], 0
	v_mfma_f32_16x16x32_bf16 v[80:83], v[176:179], v[206:209], 0
	v_mfma_f32_16x16x32_bf16 v[68:71], v[168:171], v[214:217], 0
	v_mfma_f32_16x16x32_bf16 v[64:67], v[176:179], v[214:217], 0
	v_mfma_f32_16x16x32_bf16 v[116:119], v[172:175], v[194:197], v[116:119]
	v_mfma_f32_16x16x32_bf16 v[112:115], v[186:189], v[194:197], v[112:115]
	v_mfma_f32_16x16x32_bf16 v[100:103], v[172:175], v[202:205], v[100:103]
	v_mfma_f32_16x16x32_bf16 v[96:99], v[186:189], v[202:205], v[96:99]
	v_mfma_f32_16x16x32_bf16 v[84:87], v[172:175], v[210:213], v[84:87]
	v_mfma_f32_16x16x32_bf16 v[80:83], v[186:189], v[210:213], v[80:83]
	v_mfma_f32_16x16x32_bf16 v[68:71], v[172:175], v[218:221], v[68:71]
	v_mfma_f32_16x16x32_bf16 v[64:67], v[186:189], v[218:221], v[64:67]
	s_barrier
	s_add_i32 s59, s45, s35
	s_mov_b32 m0, s59
	ds_read_b128 v[190:193], v154 offset:16384
	ds_read_b128 v[194:197], v154 offset:17408
	ds_read_b128 v[198:201], v154 offset:18432
	ds_read_b128 v[202:205], v154 offset:19456
	ds_read_b128 v[206:209], v154 offset:20480
	ds_read_b128 v[210:213], v154 offset:21504
	ds_read_b128 v[214:217], v154 offset:22528
	ds_read_b128 v[218:221], v154 offset:23552
	global_load_lds_dwordx4 v132, s[28:29]
	s_add_i32 m0, s59, 0x2000
	s_add_u32 s60, s28, 0x40000
	s_addc_u32 s61, s29, 0
	s_add_u32 s98, s28, s12
	s_addc_u32 s99, s29, s13
	s_add_u32 s100, s30, s12
	s_addc_u32 s101, s31, s13
	s_add_i32 s59, s46, s35
	global_load_lds_dwordx4 v128, s[28:29]
	s_mov_b32 m0, s59
	s_nop 0
	global_load_lds_dwordx4 v132, s[60:61]
	s_add_i32 m0, s59, 0x2000
	s_nop 0
	global_load_lds_dwordx4 v128, s[60:61]
	s_mov_b32 m0, s38
	s_nop 0
	global_load_lds_dwordx4 v134, s[30:31]
	s_mov_b32 m0, s39
	s_nop 0
	global_load_lds_dwordx4 v130, s[30:31]
	s_waitcnt vmcnt(20)
	s_waitcnt lgkmcnt(0)
	s_barrier
; #define PG8_STAGE(bufoff, gbase, voff) do { _Pragma("unroll") for (int _i = 0; _i < 2; ++_i) \
;         __builtin_amdgcn_global_load_lds((const unsigned*)((const char*)(gbase) + (voff)[_i]), (PG8_LAS unsigned*)(lds + (bufoff) + ldsw + _i * 8192), 16, 0, 0); } while (0)
; #define PG8_LDA(dst, b, h) do { _Pragma("unroll") for (int m = 0; m < 4; ++m) _Pragma("unroll") for (int k = 0; k < 2; ++k) dst[m][k] = *(const PG8_LAS bf16x8*)(lds + PG8_SA(b, h) + aoff + m * 2048 + k * 1024); } while (0)
; #define PG8_LDB(dst, b, h) do { _Pragma("unroll") for (int n = 0; n < 2; ++n) _Pragma("unroll") for (int k = 0; k < 2; ++k) dst[n][k] = *(const PG8_LAS bf16x8*)(lds + PG8_SB(b, h) + boff + n * 2048 + k * 1024); } while (0)
; #define PG8_MMA(ai, bj, At, Bt) do { __builtin_amdgcn_s_setprio(1); _Pragma("unroll") for (int m = 0; m < 4; ++m) _Pragma("unroll") for (int n = 0; n < 2; ++n) _Pragma("unroll") for (int k = 0; k < 2; ++k) \
;         acc[ai][bj][m][n] = __builtin_amdgcn_mfma_f32_16x16x32_bf16(Bt[n][k], At[m][k], acc[ai][bj][m][n], 0, 0, 0); __builtin_amdgcn_s_setprio(0); } while (0)
; #define PG8_WAIT_V(n) asm volatile("s_waitcnt vmcnt(" #n ")" ::: "memory")
; template <class Epi, class Sched, bool ALIGN_EPI = false, bool SP2 = false>
; __device__ __forceinline__ void gemm_phase(PG8_LAS unsigned char* lds, const Gemm g, const Sched& S, const Epi& E) {
;     ...
;             PG8_LDB(B0, 0, 0); PG8_LDB(B1, 0, 1); PG8_SCHED; PG8_LDA(At, 0, 0); PG8_STAGE(PG8_SA(1, 1), a1 + hstep, voffA);
;             PG8_WAIT_V(8); PG8_WAIT_L(0); PG8_BAR; PG8_MMA(0, 0, At, B0); PG8_MMA(0, 1, At, B1); PG8_BAR; PG8_SCHED;
;             PG8_LDA(At, 0, 1); PG8_STAGE(PG8_SB(0, 0), b2, voffB); PG8_STAGE(PG8_SB(0, 1), b2 + hstep, voffB); PG8_STAGE(PG8_SA(0, 0), a2, voffA);
;             PG8_WAIT_V(8); PG8_WAIT_L(0); PG8_BAR; PG8_MMA(1, 0, At, B0); PG8_MMA(1, 1, At, B1); PG8_BAR; PG8_SCHED;
;             PG8_LDB(B0, 1, 0); PG8_LDB(B1, 1, 1); PG8_SCHED; PG8_LDA(At, 1, 0); PG8_STAGE(PG8_SA(0, 1), a2 + hstep, voffA);
;             PG8_WAIT_V(8); PG8_WAIT_L(0); PG8_BAR; PG8_MMA(0, 0, At, B0); PG8_MMA(0, 1, At, B1); PG8_BAR; PG8_SCHED;
;             PG8_LDA(At, 1, 1); PG8_STAGE(PG8_SB(1, 0), b3, voffB); PG8_STAGE(PG8_SB(1, 1), b3 + hstep, voffB); PG8_STAGE(PG8_SA(1, 0), a3, voffA);
;             PG8_WAIT_V(8); PG8_WAIT_L(0); PG8_BAR; PG8_MMA(1, 0, At, B0); PG8_MMA(1, 1, At, B1); PG8_BAR; PG8_SCHED;
	s_waitcnt lgkmcnt(0)
	v_mfma_f32_16x16x32_bf16 v[60:63], v[146:149], v[190:193], 0
	v_mfma_f32_16x16x32_bf16 v[56:59], v[160:163], v[190:193], 0
	v_mfma_f32_16x16x32_bf16 v[44:47], v[146:149], v[198:201], 0
	v_mfma_f32_16x16x32_bf16 v[40:43], v[160:163], v[198:201], 0
	v_mfma_f32_16x16x32_bf16 v[28:31], v[146:149], v[206:209], 0
	v_mfma_f32_16x16x32_bf16 v[24:27], v[160:163], v[206:209], 0
	v_mfma_f32_16x16x32_bf16 v[12:15], v[146:149], v[214:217], 0
	v_mfma_f32_16x16x32_bf16 v[8:11], v[160:163], v[214:217], 0
	v_mfma_f32_16x16x32_bf16 v[60:63], v[156:159], v[194:197], v[60:63]
	v_mfma_f32_16x16x32_bf16 v[56:59], v[164:167], v[194:197], v[56:59]
	v_mfma_f32_16x16x32_bf16 v[44:47], v[156:159], v[202:205], v[44:47]
	v_mfma_f32_16x16x32_bf16 v[40:43], v[164:167], v[202:205], v[40:43]
	v_mfma_f32_16x16x32_bf16 v[28:31], v[156:159], v[210:213], v[28:31]
	v_mfma_f32_16x16x32_bf16 v[24:27], v[164:167], v[210:213], v[24:27]
	v_mfma_f32_16x16x32_bf16 v[12:15], v[156:159], v[218:221], v[12:15]
	v_mfma_f32_16x16x32_bf16 v[8:11], v[164:167], v[218:221], v[8:11]
	v_mfma_f32_16x16x32_bf16 v[52:55], v[168:171], v[190:193], 0
	v_mfma_f32_16x16x32_bf16 v[48:51], v[176:179], v[190:193], 0
	v_mfma_f32_16x16x32_bf16 v[36:39], v[168:171], v[198:201], 0
	v_mfma_f32_16x16x32_bf16 v[32:35], v[176:179], v[198:201], 0
	v_mfma_f32_16x16x32_bf16 v[20:23], v[168:171], v[206:209], 0
	v_mfma_f32_16x16x32_bf16 v[16:19], v[176:179], v[206:209], 0
	v_mfma_f32_16x16x32_bf16 v[4:7], v[168:171], v[214:217], 0
	v_mfma_f32_16x16x32_bf16 v[0:3], v[176:179], v[214:217], 0
	v_mfma_f32_16x16x32_bf16 v[52:55], v[172:175], v[194:197], v[52:55]
	v_mfma_f32_16x16x32_bf16 v[48:51], v[186:189], v[194:197], v[48:51]
	v_mfma_f32_16x16x32_bf16 v[36:39], v[172:175], v[202:205], v[36:39]
	v_mfma_f32_16x16x32_bf16 v[32:35], v[186:189], v[202:205], v[32:35]
	v_mfma_f32_16x16x32_bf16 v[20:23], v[172:175], v[210:213], v[20:23]
	v_mfma_f32_16x16x32_bf16 v[16:19], v[186:189], v[210:213], v[16:19]
	v_mfma_f32_16x16x32_bf16 v[4:7], v[172:175], v[218:221], v[4:7]
	v_mfma_f32_16x16x32_bf16 v[0:3], v[186:189], v[218:221], v[0:3]
	s_barrier
	s_add_i32 s59, 0, 0x18000
	s_add_i32 s60, 0, 0x1c000
	v_add_u32_e32 v164, s59, v151
	v_add_u32_e32 v185, s60, v151
	ds_read_b128 v[146:149], v164
	ds_read_b128 v[156:159], v164 offset:1024
	ds_read_b128 v[160:163], v164 offset:2048
	ds_read_b128 v[164:167], v164 offset:3072
	ds_read_b128 v[168:171], v185
	ds_read_b128 v[172:175], v185 offset:1024
	ds_read_b128 v[176:179], v185 offset:2048
	ds_read_b128 v[186:189], v185 offset:3072
	s_add_u32 s30, s30, 0x40000
	s_addc_u32 s31, s31, 0
	s_mov_b32 m0, s40
	ds_read_b128 v[190:193], v154 offset:32768
	ds_read_b128 v[194:197], v154 offset:33792
	ds_read_b128 v[198:201], v154 offset:34816
	ds_read_b128 v[202:205], v154 offset:35840
	ds_read_b128 v[206:209], v154 offset:36864
	ds_read_b128 v[210:213], v154 offset:37888
	ds_read_b128 v[214:217], v154 offset:38912
	ds_read_b128 v[218:221], v154 offset:39936
	global_load_lds_dwordx4 v134, s[30:31]
	s_mov_b32 m0, s41
	s_nop 0
	global_load_lds_dwordx4 v130, s[30:31]
	s_waitcnt vmcnt(8)
	s_waitcnt lgkmcnt(0)
	s_barrier
	s_waitcnt lgkmcnt(0)
	v_mfma_f32_16x16x32_bf16 v[124:127], v[146:149], v[190:193], v[124:127]
	v_mfma_f32_16x16x32_bf16 v[120:123], v[160:163], v[190:193], v[120:123]
	v_mfma_f32_16x16x32_bf16 v[108:111], v[146:149], v[198:201], v[108:111]
	v_mfma_f32_16x16x32_bf16 v[104:107], v[160:163], v[198:201], v[104:107]
	v_mfma_f32_16x16x32_bf16 v[92:95], v[146:149], v[206:209], v[92:95]
	v_mfma_f32_16x16x32_bf16 v[88:91], v[160:163], v[206:209], v[88:91]
	v_mfma_f32_16x16x32_bf16 v[76:79], v[146:149], v[214:217], v[76:79]
	v_mfma_f32_16x16x32_bf16 v[72:75], v[160:163], v[214:217], v[72:75]
	v_mfma_f32_16x16x32_bf16 v[124:127], v[156:159], v[194:197], v[124:127]
	v_mfma_f32_16x16x32_bf16 v[120:123], v[164:167], v[194:197], v[120:123]
	v_mfma_f32_16x16x32_bf16 v[108:111], v[156:159], v[202:205], v[108:111]
	v_mfma_f32_16x16x32_bf16 v[104:107], v[164:167], v[202:205], v[104:107]
	v_mfma_f32_16x16x32_bf16 v[92:95], v[156:159], v[210:213], v[92:95]
	v_mfma_f32_16x16x32_bf16 v[88:91], v[164:167], v[210:213], v[88:91]
	v_mfma_f32_16x16x32_bf16 v[76:79], v[156:159], v[218:221], v[76:79]
	v_mfma_f32_16x16x32_bf16 v[72:75], v[164:167], v[218:221], v[72:75]
	v_mfma_f32_16x16x32_bf16 v[116:119], v[168:171], v[190:193], v[116:119]
	v_mfma_f32_16x16x32_bf16 v[112:115], v[176:179], v[190:193], v[112:115]
	v_mfma_f32_16x16x32_bf16 v[100:103], v[168:171], v[198:201], v[100:103]
	v_mfma_f32_16x16x32_bf16 v[96:99], v[176:179], v[198:201], v[96:99]
	v_mfma_f32_16x16x32_bf16 v[84:87], v[168:171], v[206:209], v[84:87]
	v_mfma_f32_16x16x32_bf16 v[80:83], v[176:179], v[206:209], v[80:83]
	v_mfma_f32_16x16x32_bf16 v[68:71], v[168:171], v[214:217], v[68:71]
	v_mfma_f32_16x16x32_bf16 v[64:67], v[176:179], v[214:217], v[64:67]
	v_mfma_f32_16x16x32_bf16 v[116:119], v[172:175], v[194:197], v[116:119]
	v_mfma_f32_16x16x32_bf16 v[112:115], v[186:189], v[194:197], v[112:115]
	v_mfma_f32_16x16x32_bf16 v[100:103], v[172:175], v[202:205], v[100:103]
	v_mfma_f32_16x16x32_bf16 v[96:99], v[186:189], v[202:205], v[96:99]
	v_mfma_f32_16x16x32_bf16 v[84:87], v[172:175], v[210:213], v[84:87]
	v_mfma_f32_16x16x32_bf16 v[80:83], v[186:189], v[210:213], v[80:83]
	v_mfma_f32_16x16x32_bf16 v[68:71], v[172:175], v[218:221], v[68:71]
	v_mfma_f32_16x16x32_bf16 v[64:67], v[186:189], v[218:221], v[64:67]
	s_barrier
; #define PG8_STAGE(bufoff, gbase, voff) do { _Pragma("unroll") for (int _i = 0; _i < 2; ++_i) \
;         __builtin_amdgcn_global_load_lds((const unsigned*)((const char*)(gbase) + (voff)[_i]), (PG8_LAS unsigned*)(lds + (bufoff) + ldsw + _i * 8192), 16, 0, 0); } while (0)
; #define PG8_LDA(dst, b, h) do { _Pragma("unroll") for (int m = 0; m < 4; ++m) _Pragma("unroll") for (int k = 0; k < 2; ++k) dst[m][k] = *(const PG8_LAS bf16x8*)(lds + PG8_SA(b, h) + aoff + m * 2048 + k * 1024); } while (0)
; #define PG8_LDB(dst, b, h) do { _Pragma("unroll") for (int n = 0; n < 2; ++n) _Pragma("unroll") for (int k = 0; k < 2; ++k) dst[n][k] = *(const PG8_LAS bf16x8*)(lds + PG8_SB(b, h) + boff + n * 2048 + k * 1024); } while (0)
; #define PG8_MMA(ai, bj, At, Bt) do { __builtin_amdgcn_s_setprio(1); _Pragma("unroll") for (int m = 0; m < 4; ++m) _Pragma("unroll") for (int n = 0; n < 2; ++n) _Pragma("unroll") for (int k = 0; k < 2; ++k) \
;         acc[ai][bj][m][n] = __builtin_amdgcn_mfma_f32_16x16x32_bf16(Bt[n][k], At[m][k], acc[ai][bj][m][n], 0, 0, 0); __builtin_amdgcn_s_setprio(0); } while (0)
; #define PG8_WAIT_V(n) asm volatile("s_waitcnt vmcnt(" #n ")" ::: "memory")
; template <class Epi, class Sched, bool ALIGN_EPI = false, bool SP2 = false>
; __device__ __forceinline__ void gemm_phase(PG8_LAS unsigned char* lds, const Gemm g, const Sched& S, const Epi& E) {
;     ...
;             PG8_LDB(B0, 0, 0); PG8_LDB(B1, 0, 1); PG8_SCHED; PG8_LDA(At, 0, 0); PG8_STAGE(PG8_SA(1, 1), a1 + hstep, voffA);
;             PG8_WAIT_V(8); PG8_WAIT_L(0); PG8_BAR; PG8_MMA(0, 0, At, B0); PG8_MMA(0, 1, At, B1); PG8_BAR; PG8_SCHED;
;             PG8_LDA(At, 0, 1); PG8_STAGE(PG8_SB(0, 0), b2, voffB); PG8_STAGE(PG8_SB(0, 1), b2 + hstep, voffB); PG8_STAGE(PG8_SA(0, 0), a2, voffA);
;             PG8_WAIT_V(8); PG8_WAIT_L(0); PG8_BAR; PG8_MMA(1, 0, At, B0); PG8_MMA(1, 1, At, B1); PG8_BAR; PG8_SCHED;
;             PG8_LDB(B0, 1, 0); PG8_LDB(B1, 1, 1); PG8_SCHED; PG8_LDA(At, 1, 0); PG8_STAGE(PG8_SA(0, 1), a2 + hstep, voffA);
;             PG8_WAIT_V(8); PG8_WAIT_L(0); PG8_BAR; PG8_MMA(0, 0, At, B0); PG8_MMA(0, 1, At, B1); PG8_BAR; PG8_SCHED;
;             PG8_LDA(At, 1, 1); PG8_STAGE(PG8_SB(1, 0), b3, voffB); PG8_STAGE(PG8_SB(1, 1), b3 + hstep, voffB); PG8_STAGE(PG8_SA(1, 0), a3, voffA);
;             PG8_WAIT_V(8); PG8_WAIT_L(0); PG8_BAR; PG8_MMA(1, 0, At, B0); PG8_MMA(1, 1, At, B1); PG8_BAR; PG8_SCHED;
	s_add_i32 s30, s59, s35
	s_mov_b32 m0, s30
	ds_read_b128 v[190:193], v154 offset:49152
	ds_read_b128 v[194:197], v154 offset:50176
	ds_read_b128 v[198:201], v154 offset:51200
	ds_read_b128 v[202:205], v154 offset:52224
	ds_read_b128 v[206:209], v154 offset:53248
	ds_read_b128 v[210:213], v154 offset:54272
	ds_read_b128 v[214:217], v154 offset:55296
	ds_read_b128 v[218:221], v154 offset:56320
	global_load_lds_dwordx4 v132, s[98:99]
	s_add_i32 m0, s30, 0x2000
	s_add_u32 s28, s28, 0x40080
	s_addc_u32 s29, s29, 0
	s_add_i32 s30, s60, s35
	global_load_lds_dwordx4 v128, s[98:99]
	s_mov_b32 m0, s30
	s_nop 0
	global_load_lds_dwordx4 v132, s[28:29]
	s_add_i32 m0, s30, 0x2000
	s_nop 0
	global_load_lds_dwordx4 v128, s[28:29]
	s_mov_b32 m0, s42
	s_nop 0
	global_load_lds_dwordx4 v134, s[100:101]
	s_mov_b32 m0, s43
	s_nop 0
	global_load_lds_dwordx4 v130, s[100:101]
	s_waitcnt vmcnt(8)
	s_waitcnt lgkmcnt(0)
	s_barrier
	s_waitcnt lgkmcnt(0)
	v_mfma_f32_16x16x32_bf16 v[60:63], v[146:149], v[190:193], v[60:63]
	v_mfma_f32_16x16x32_bf16 v[56:59], v[160:163], v[190:193], v[56:59]
	v_mfma_f32_16x16x32_bf16 v[44:47], v[146:149], v[198:201], v[44:47]
	v_mfma_f32_16x16x32_bf16 v[40:43], v[160:163], v[198:201], v[40:43]
	v_mfma_f32_16x16x32_bf16 v[28:31], v[146:149], v[206:209], v[28:31]
	v_mfma_f32_16x16x32_bf16 v[24:27], v[160:163], v[206:209], v[24:27]
	v_mfma_f32_16x16x32_bf16 v[12:15], v[146:149], v[214:217], v[12:15]
	v_mfma_f32_16x16x32_bf16 v[8:11], v[160:163], v[214:217], v[8:11]
	v_mfma_f32_16x16x32_bf16 v[60:63], v[156:159], v[194:197], v[60:63]
	v_mfma_f32_16x16x32_bf16 v[56:59], v[164:167], v[194:197], v[56:59]
	v_mfma_f32_16x16x32_bf16 v[44:47], v[156:159], v[202:205], v[44:47]
	v_mfma_f32_16x16x32_bf16 v[40:43], v[164:167], v[202:205], v[40:43]
	v_mfma_f32_16x16x32_bf16 v[28:31], v[156:159], v[210:213], v[28:31]
	v_mfma_f32_16x16x32_bf16 v[24:27], v[164:167], v[210:213], v[24:27]
	v_mfma_f32_16x16x32_bf16 v[12:15], v[156:159], v[218:221], v[12:15]
	v_mfma_f32_16x16x32_bf16 v[8:11], v[164:167], v[218:221], v[8:11]
	v_mfma_f32_16x16x32_bf16 v[52:55], v[168:171], v[190:193], v[52:55]
	v_mfma_f32_16x16x32_bf16 v[48:51], v[176:179], v[190:193], v[48:51]
	v_mfma_f32_16x16x32_bf16 v[36:39], v[168:171], v[198:201], v[36:39]
	v_mfma_f32_16x16x32_bf16 v[32:35], v[176:179], v[198:201], v[32:35]
	v_mfma_f32_16x16x32_bf16 v[20:23], v[168:171], v[206:209], v[20:23]
	v_mfma_f32_16x16x32_bf16 v[16:19], v[176:179], v[206:209], v[16:19]
	v_mfma_f32_16x16x32_bf16 v[4:7], v[168:171], v[214:217], v[4:7]
	v_mfma_f32_16x16x32_bf16 v[0:3], v[176:179], v[214:217], v[0:3]
	v_mfma_f32_16x16x32_bf16 v[52:55], v[172:175], v[194:197], v[52:55]
	v_mfma_f32_16x16x32_bf16 v[48:51], v[186:189], v[194:197], v[48:51]
	v_mfma_f32_16x16x32_bf16 v[36:39], v[172:175], v[202:205], v[36:39]
	v_mfma_f32_16x16x32_bf16 v[32:35], v[186:189], v[202:205], v[32:35]
	v_mfma_f32_16x16x32_bf16 v[20:23], v[172:175], v[210:213], v[20:23]
	v_mfma_f32_16x16x32_bf16 v[16:19], v[186:189], v[210:213], v[16:19]
	v_mfma_f32_16x16x32_bf16 v[4:7], v[172:175], v[218:221], v[4:7]
	v_mfma_f32_16x16x32_bf16 v[0:3], v[186:189], v[218:221], v[0:3]
	s_barrier
	s_add_i32 s58, s58, 2
	s_add_u32 s26, s26, 0x100
	s_addc_u32 s27, s27, 0
	s_add_u32 s56, s56, 0x100
	s_addc_u32 s57, s57, 0
	s_cmp_gt_u32 s58, 13
.LBB0_860:
	ds_read_b128 v[146:149], v152
	ds_read_b128 v[156:159], v152 offset:1024
	ds_read_b128 v[160:163], v152 offset:2048
	ds_read_b128 v[164:167], v152 offset:3072
	ds_read_b128 v[168:171], v153
	ds_read_b128 v[172:175], v153 offset:1024
	ds_read_b128 v[176:179], v153 offset:2048
	ds_read_b128 v[186:189], v153 offset:3072
	s_add_u32 s28, s26, 0xfffc0080
	s_addc_u32 s29, s27, -1
	s_cmp_eq_u32 s58, 12
	s_cselect_b32 s31, s19, s29
	s_cselect_b32 s30, s54, s28
	s_cselect_b32 s29, s17, s57
	s_cselect_b32 s28, s55, s56
	s_add_i32 m0, s38, 0xc000
	ds_read_b128 v[190:193], v154
	ds_read_b128 v[194:197], v154 offset:1024
	ds_read_b128 v[198:201], v154 offset:2048
	ds_read_b128 v[202:205], v154 offset:3072
	ds_read_b128 v[206:209], v154 offset:4096
	ds_read_b128 v[210:213], v154 offset:5120
	ds_read_b128 v[214:217], v154 offset:6144
	ds_read_b128 v[218:221], v154 offset:7168
	global_load_lds_dwordx4 v138, s[26:27]
	s_add_i32 m0, s38, 0xe000
	s_nop 0
	global_load_lds_dwordx4 v140, s[26:27]
	s_waitcnt vmcnt(8)
	s_waitcnt lgkmcnt(0)
	s_barrier
	s_waitcnt lgkmcnt(0)
	v_mfma_f32_16x16x32_bf16 v[124:127], v[146:149], v[190:193], v[124:127]
	v_mfma_f32_16x16x32_bf16 v[120:123], v[160:163], v[190:193], v[120:123]
	v_mfma_f32_16x16x32_bf16 v[108:111], v[146:149], v[198:201], v[108:111]
	v_mfma_f32_16x16x32_bf16 v[104:107], v[160:163], v[198:201], v[104:107]
	v_mfma_f32_16x16x32_bf16 v[92:95], v[146:149], v[206:209], v[92:95]
	v_mfma_f32_16x16x32_bf16 v[88:91], v[160:163], v[206:209], v[88:91]
	v_mfma_f32_16x16x32_bf16 v[76:79], v[146:149], v[214:217], v[76:79]
	v_mfma_f32_16x16x32_bf16 v[72:75], v[160:163], v[214:217], v[72:75]
	v_mfma_f32_16x16x32_bf16 v[124:127], v[156:159], v[194:197], v[124:127]
	v_mfma_f32_16x16x32_bf16 v[120:123], v[164:167], v[194:197], v[120:123]
	v_mfma_f32_16x16x32_bf16 v[108:111], v[156:159], v[202:205], v[108:111]
	v_mfma_f32_16x16x32_bf16 v[104:107], v[164:167], v[202:205], v[104:107]
	v_mfma_f32_16x16x32_bf16 v[92:95], v[156:159], v[210:213], v[92:95]
	v_mfma_f32_16x16x32_bf16 v[88:91], v[164:167], v[210:213], v[88:91]
	v_mfma_f32_16x16x32_bf16 v[76:79], v[156:159], v[218:221], v[76:79]
	v_mfma_f32_16x16x32_bf16 v[72:75], v[164:167], v[218:221], v[72:75]
	v_mfma_f32_16x16x32_bf16 v[116:119], v[168:171], v[190:193], v[116:119]
	v_mfma_f32_16x16x32_bf16 v[112:115], v[176:179], v[190:193], v[112:115]
	v_mfma_f32_16x16x32_bf16 v[100:103], v[168:171], v[198:201], v[100:103]
	v_mfma_f32_16x16x32_bf16 v[96:99], v[176:179], v[198:201], v[96:99]
	v_mfma_f32_16x16x32_bf16 v[84:87], v[168:171], v[206:209], v[84:87]
	v_mfma_f32_16x16x32_bf16 v[80:83], v[176:179], v[206:209], v[80:83]
	v_mfma_f32_16x16x32_bf16 v[68:71], v[168:171], v[214:217], v[68:71]
	v_mfma_f32_16x16x32_bf16 v[64:67], v[176:179], v[214:217], v[64:67]
	v_mfma_f32_16x16x32_bf16 v[116:119], v[172:175], v[194:197], v[116:119]
	v_mfma_f32_16x16x32_bf16 v[112:115], v[186:189], v[194:197], v[112:115]
	v_mfma_f32_16x16x32_bf16 v[100:103], v[172:175], v[202:205], v[100:103]
	v_mfma_f32_16x16x32_bf16 v[96:99], v[186:189], v[202:205], v[96:99]
	v_mfma_f32_16x16x32_bf16 v[84:87], v[172:175], v[210:213], v[84:87]
	v_mfma_f32_16x16x32_bf16 v[80:83], v[186:189], v[210:213], v[80:83]
	v_mfma_f32_16x16x32_bf16 v[68:71], v[172:175], v[218:221], v[68:71]
	v_mfma_f32_16x16x32_bf16 v[64:67], v[186:189], v[218:221], v[64:67]
	s_barrier
; #define PG8_STAGE(bufoff, gbase, voff) do { _Pragma("unroll") for (int _i = 0; _i < 2; ++_i) \
;         __builtin_amdgcn_global_load_lds((const unsigned*)((const char*)(gbase) + (voff)[_i]), (PG8_LAS unsigned*)(lds + (bufoff) + ldsw + _i * 8192), 16, 0, 0); } while (0)
; #define PG8_LDA(dst, b, h) do { _Pragma("unroll") for (int m = 0; m < 4; ++m) _Pragma("unroll") for (int k = 0; k < 2; ++k) dst[m][k] = *(const PG8_LAS bf16x8*)(lds + PG8_SA(b, h) + aoff + m * 2048 + k * 1024); } while (0)
; #define PG8_LDB(dst, b, h) do { _Pragma("unroll") for (int n = 0; n < 2; ++n) _Pragma("unroll") for (int k = 0; k < 2; ++k) dst[n][k] = *(const PG8_LAS bf16x8*)(lds + PG8_SB(b, h) + boff + n * 2048 + k * 1024); } while (0)
; #define PG8_MMA(ai, bj, At, Bt) do { __builtin_amdgcn_s_setprio(1); _Pragma("unroll") for (int m = 0; m < 4; ++m) _Pragma("unroll") for (int n = 0; n < 2; ++n) _Pragma("unroll") for (int k = 0; k < 2; ++k) \
;         acc[ai][bj][m][n] = __builtin_amdgcn_mfma_f32_16x16x32_bf16(Bt[n][k], At[m][k], acc[ai][bj][m][n], 0, 0, 0); __builtin_amdgcn_s_setprio(0); } while (0)
; #define PG8_WAIT_V(n) asm volatile("s_waitcnt vmcnt(" #n ")" ::: "memory")
; template <class Epi, class Sched, bool ALIGN_EPI = false, bool SP2 = false>
; __device__ __forceinline__ void gemm_phase(PG8_LAS unsigned char* lds, const Gemm g, const Sched& S, const Epi& E) {
;     ...
;             PG8_LDB(B0, 0, 0); PG8_LDB(B1, 0, 1); PG8_SCHED; PG8_LDA(At, 0, 0); PG8_STAGE(PG8_SA(1, 1), a1 + hstep, voffA);
;             PG8_WAIT_V(8); PG8_WAIT_L(0); PG8_BAR; PG8_MMA(0, 0, At, B0); PG8_MMA(0, 1, At, B1); PG8_BAR; PG8_SCHED;
;             PG8_LDA(At, 0, 1); PG8_STAGE(PG8_SB(0, 0), b2, voffB); PG8_STAGE(PG8_SB(0, 1), b2 + hstep, voffB); PG8_STAGE(PG8_SA(0, 0), a2, voffA);
;             PG8_WAIT_V(8); PG8_WAIT_L(0); PG8_BAR; PG8_MMA(1, 0, At, B0); PG8_MMA(1, 1, At, B1); PG8_BAR; PG8_SCHED;
;             PG8_LDB(B0, 1, 0); PG8_LDB(B1, 1, 1); PG8_SCHED; PG8_LDA(At, 1, 0); PG8_STAGE(PG8_SA(0, 1), a2 + hstep, voffA);
;             PG8_WAIT_V(8); PG8_WAIT_L(0); PG8_BAR; PG8_MMA(0, 0, At, B0); PG8_MMA(0, 1, At, B1); PG8_BAR; PG8_SCHED;
;             PG8_LDA(At, 1, 1); PG8_STAGE(PG8_SB(1, 0), b3, voffB); PG8_STAGE(PG8_SB(1, 1), b3 + hstep, voffB); PG8_STAGE(PG8_SA(1, 0), a3, voffA);
;             PG8_WAIT_V(8); PG8_WAIT_L(0); PG8_BAR; PG8_MMA(1, 0, At, B0); PG8_MMA(1, 1, At, B1); PG8_BAR; PG8_SCHED;
	s_add_i32 s59, s45, s35
	s_mov_b32 m0, s59
	ds_read_b128 v[190:193], v154 offset:16384
	ds_read_b128 v[194:197], v154 offset:17408
	ds_read_b128 v[198:201], v154 offset:18432
	ds_read_b128 v[202:205], v154 offset:19456
	ds_read_b128 v[206:209], v154 offset:20480
	ds_read_b128 v[210:213], v154 offset:21504
	ds_read_b128 v[214:217], v154 offset:22528
	ds_read_b128 v[218:221], v154 offset:23552
	global_load_lds_dwordx4 v132, s[28:29]
	s_add_i32 m0, s59, 0x2000
	s_add_u32 s60, s28, 0x40000
	s_addc_u32 s61, s29, 0
	s_add_u32 s98, s28, s12
	s_addc_u32 s99, s29, s13
	s_add_u32 s100, s30, s12
	s_addc_u32 s101, s31, s13
	s_add_i32 s59, s46, s35
	global_load_lds_dwordx4 v128, s[28:29]
	s_mov_b32 m0, s59
	s_nop 0
	global_load_lds_dwordx4 v132, s[60:61]
	s_add_i32 m0, s59, 0x2000
	s_nop 0
	global_load_lds_dwordx4 v128, s[60:61]
	s_mov_b32 m0, s38
	s_nop 0
	global_load_lds_dwordx4 v134, s[30:31]
	s_mov_b32 m0, s39
	s_nop 0
	global_load_lds_dwordx4 v130, s[30:31]
	s_waitcnt vmcnt(8)
	s_waitcnt lgkmcnt(0)
	s_barrier
	s_waitcnt lgkmcnt(0)
	v_mfma_f32_16x16x32_bf16 v[60:63], v[146:149], v[190:193], v[60:63]
	v_mfma_f32_16x16x32_bf16 v[56:59], v[160:163], v[190:193], v[56:59]
	v_mfma_f32_16x16x32_bf16 v[44:47], v[146:149], v[198:201], v[44:47]
	v_mfma_f32_16x16x32_bf16 v[40:43], v[160:163], v[198:201], v[40:43]
	v_mfma_f32_16x16x32_bf16 v[28:31], v[146:149], v[206:209], v[28:31]
	v_mfma_f32_16x16x32_bf16 v[24:27], v[160:163], v[206:209], v[24:27]
	v_mfma_f32_16x16x32_bf16 v[12:15], v[146:149], v[214:217], v[12:15]
	v_mfma_f32_16x16x32_bf16 v[8:11], v[160:163], v[214:217], v[8:11]
	v_mfma_f32_16x16x32_bf16 v[60:63], v[156:159], v[194:197], v[60:63]
	v_mfma_f32_16x16x32_bf16 v[56:59], v[164:167], v[194:197], v[56:59]
	v_mfma_f32_16x16x32_bf16 v[44:47], v[156:159], v[202:205], v[44:47]
	v_mfma_f32_16x16x32_bf16 v[40:43], v[164:167], v[202:205], v[40:43]
	v_mfma_f32_16x16x32_bf16 v[28:31], v[156:159], v[210:213], v[28:31]
	v_mfma_f32_16x16x32_bf16 v[24:27], v[164:167], v[210:213], v[24:27]
	v_mfma_f32_16x16x32_bf16 v[12:15], v[156:159], v[218:221], v[12:15]
	v_mfma_f32_16x16x32_bf16 v[8:11], v[164:167], v[218:221], v[8:11]
	v_mfma_f32_16x16x32_bf16 v[52:55], v[168:171], v[190:193], v[52:55]
	v_mfma_f32_16x16x32_bf16 v[48:51], v[176:179], v[190:193], v[48:51]
	v_mfma_f32_16x16x32_bf16 v[36:39], v[168:171], v[198:201], v[36:39]
	v_mfma_f32_16x16x32_bf16 v[32:35], v[176:179], v[198:201], v[32:35]
	v_mfma_f32_16x16x32_bf16 v[20:23], v[168:171], v[206:209], v[20:23]
	v_mfma_f32_16x16x32_bf16 v[16:19], v[176:179], v[206:209], v[16:19]
	v_mfma_f32_16x16x32_bf16 v[4:7], v[168:171], v[214:217], v[4:7]
	v_mfma_f32_16x16x32_bf16 v[0:3], v[176:179], v[214:217], v[0:3]
	v_mfma_f32_16x16x32_bf16 v[52:55], v[172:175], v[194:197], v[52:55]
	v_mfma_f32_16x16x32_bf16 v[48:51], v[186:189], v[194:197], v[48:51]
	v_mfma_f32_16x16x32_bf16 v[36:39], v[172:175], v[202:205], v[36:39]
	v_mfma_f32_16x16x32_bf16 v[32:35], v[186:189], v[202:205], v[32:35]
	v_mfma_f32_16x16x32_bf16 v[20:23], v[172:175], v[210:213], v[20:23]
	v_mfma_f32_16x16x32_bf16 v[16:19], v[186:189], v[210:213], v[16:19]
	v_mfma_f32_16x16x32_bf16 v[4:7], v[172:175], v[218:221], v[4:7]
	v_mfma_f32_16x16x32_bf16 v[0:3], v[186:189], v[218:221], v[0:3]
	s_barrier
	s_add_i32 s59, 0, 0x18000
	s_add_i32 s60, 0, 0x1c000
	v_add_u32_e32 v164, s59, v151
	v_add_u32_e32 v185, s60, v151
	ds_read_b128 v[146:149], v164
	ds_read_b128 v[156:159], v164 offset:1024
	ds_read_b128 v[160:163], v164 offset:2048
	ds_read_b128 v[164:167], v164 offset:3072
	ds_read_b128 v[168:171], v185
	ds_read_b128 v[172:175], v185 offset:1024
	ds_read_b128 v[176:179], v185 offset:2048
	ds_read_b128 v[186:189], v185 offset:3072
	s_add_u32 s30, s30, 0x40000
	s_addc_u32 s31, s31, 0
	s_mov_b32 m0, s40
	ds_read_b128 v[190:193], v154 offset:32768
	ds_read_b128 v[194:197], v154 offset:33792
	ds_read_b128 v[198:201], v154 offset:34816
	ds_read_b128 v[202:205], v154 offset:35840
	ds_read_b128 v[206:209], v154 offset:36864
	ds_read_b128 v[210:213], v154 offset:37888
	ds_read_b128 v[214:217], v154 offset:38912
	ds_read_b128 v[218:221], v154 offset:39936
	global_load_lds_dwordx4 v134, s[30:31]
	s_mov_b32 m0, s41
	s_nop 0
	global_load_lds_dwordx4 v130, s[30:31]
	s_waitcnt vmcnt(8)
	s_waitcnt lgkmcnt(0)
	s_barrier
; #define PG8_STAGE(bufoff, gbase, voff) do { _Pragma("unroll") for (int _i = 0; _i < 2; ++_i) \
;         __builtin_amdgcn_global_load_lds((const unsigned*)((const char*)(gbase) + (voff)[_i]), (PG8_LAS unsigned*)(lds + (bufoff) + ldsw + _i * 8192), 16, 0, 0); } while (0)
; #define PG8_LDA(dst, b, h) do { _Pragma("unroll") for (int m = 0; m < 4; ++m) _Pragma("unroll") for (int k = 0; k < 2; ++k) dst[m][k] = *(const PG8_LAS bf16x8*)(lds + PG8_SA(b, h) + aoff + m * 2048 + k * 1024); } while (0)
; #define PG8_LDB(dst, b, h) do { _Pragma("unroll") for (int n = 0; n < 2; ++n) _Pragma("unroll") for (int k = 0; k < 2; ++k) dst[n][k] = *(const PG8_LAS bf16x8*)(lds + PG8_SB(b, h) + boff + n * 2048 + k * 1024); } while (0)
; #define PG8_MMA(ai, bj, At, Bt) do { __builtin_amdgcn_s_setprio(1); _Pragma("unroll") for (int m = 0; m < 4; ++m) _Pragma("unroll") for (int n = 0; n < 2; ++n) _Pragma("unroll") for (int k = 0; k < 2; ++k) \
;         acc[ai][bj][m][n] = __builtin_amdgcn_mfma_f32_16x16x32_bf16(Bt[n][k], At[m][k], acc[ai][bj][m][n], 0, 0, 0); __builtin_amdgcn_s_setprio(0); } while (0)
; template <class Epi, class Sched, bool ALIGN_EPI = false, bool SP2 = false>
; __device__ __forceinline__ void gemm_phase(PG8_LAS unsigned char* lds, const Gemm g, const Sched& S, const Epi& E) {
;     ...
;             PG8_LDB(B0, 0, 0); PG8_LDB(B1, 0, 1); PG8_SCHED; PG8_LDA(At, 0, 0); PG8_STAGE(PG8_SA(1, 1), a1 + hstep, voffA);
;             PG8_WAIT_V(8); PG8_WAIT_L(0); PG8_BAR; PG8_MMA(0, 0, At, B0); PG8_MMA(0, 1, At, B1); PG8_BAR; PG8_SCHED;
;             PG8_LDA(At, 0, 1); PG8_STAGE(PG8_SB(0, 0), b2, voffB); PG8_STAGE(PG8_SB(0, 1), b2 + hstep, voffB); PG8_STAGE(PG8_SA(0, 0), a2, voffA);
;             PG8_WAIT_V(8); PG8_WAIT_L(0); PG8_BAR; PG8_MMA(1, 0, At, B0); PG8_MMA(1, 1, At, B1); PG8_BAR; PG8_SCHED;
;             PG8_LDB(B0, 1, 0); PG8_LDB(B1, 1, 1); PG8_SCHED; PG8_LDA(At, 1, 0); PG8_STAGE(PG8_SA(0, 1), a2 + hstep, voffA);
;             PG8_WAIT_V(8); PG8_WAIT_L(0); PG8_BAR; PG8_MMA(0, 0, At, B0); PG8_MMA(0, 1, At, B1); PG8_BAR; PG8_SCHED;
;             PG8_LDA(At, 1, 1); PG8_STAGE(PG8_SB(1, 0), b3, voffB); PG8_STAGE(PG8_SB(1, 1), b3 + hstep, voffB); PG8_STAGE(PG8_SA(1, 0), a3, voffA);
;             PG8_WAIT_V(8); PG8_WAIT_L(0); PG8_BAR; PG8_MMA(1, 0, At, B0); PG8_MMA(1, 1, At, B1); PG8_BAR; PG8_SCHED;
;     ...
;         if constexpr (ALIGN_EPI) { if (wr == 0) PG8_BAR; }
	s_waitcnt lgkmcnt(0)
	v_mfma_f32_16x16x32_bf16 v[124:127], v[146:149], v[190:193], v[124:127]
	v_mfma_f32_16x16x32_bf16 v[120:123], v[160:163], v[190:193], v[120:123]
	v_mfma_f32_16x16x32_bf16 v[108:111], v[146:149], v[198:201], v[108:111]
	v_mfma_f32_16x16x32_bf16 v[104:107], v[160:163], v[198:201], v[104:107]
	v_mfma_f32_16x16x32_bf16 v[92:95], v[146:149], v[206:209], v[92:95]
	v_mfma_f32_16x16x32_bf16 v[88:91], v[160:163], v[206:209], v[88:91]
	v_mfma_f32_16x16x32_bf16 v[76:79], v[146:149], v[214:217], v[76:79]
	v_mfma_f32_16x16x32_bf16 v[72:75], v[160:163], v[214:217], v[72:75]
	v_mfma_f32_16x16x32_bf16 v[124:127], v[156:159], v[194:197], v[124:127]
	v_mfma_f32_16x16x32_bf16 v[120:123], v[164:167], v[194:197], v[120:123]
	v_mfma_f32_16x16x32_bf16 v[108:111], v[156:159], v[202:205], v[108:111]
	v_mfma_f32_16x16x32_bf16 v[104:107], v[164:167], v[202:205], v[104:107]
	v_mfma_f32_16x16x32_bf16 v[92:95], v[156:159], v[210:213], v[92:95]
	v_mfma_f32_16x16x32_bf16 v[88:91], v[164:167], v[210:213], v[88:91]
	v_mfma_f32_16x16x32_bf16 v[76:79], v[156:159], v[218:221], v[76:79]
	v_mfma_f32_16x16x32_bf16 v[72:75], v[164:167], v[218:221], v[72:75]
	v_mfma_f32_16x16x32_bf16 v[116:119], v[168:171], v[190:193], v[116:119]
	v_mfma_f32_16x16x32_bf16 v[112:115], v[176:179], v[190:193], v[112:115]
	v_mfma_f32_16x16x32_bf16 v[100:103], v[168:171], v[198:201], v[100:103]
	v_mfma_f32_16x16x32_bf16 v[96:99], v[176:179], v[198:201], v[96:99]
	v_mfma_f32_16x16x32_bf16 v[84:87], v[168:171], v[206:209], v[84:87]
	v_mfma_f32_16x16x32_bf16 v[80:83], v[176:179], v[206:209], v[80:83]
	v_mfma_f32_16x16x32_bf16 v[68:71], v[168:171], v[214:217], v[68:71]
	v_mfma_f32_16x16x32_bf16 v[64:67], v[176:179], v[214:217], v[64:67]
	v_mfma_f32_16x16x32_bf16 v[116:119], v[172:175], v[194:197], v[116:119]
	v_mfma_f32_16x16x32_bf16 v[112:115], v[186:189], v[194:197], v[112:115]
	v_mfma_f32_16x16x32_bf16 v[100:103], v[172:175], v[202:205], v[100:103]
	v_mfma_f32_16x16x32_bf16 v[96:99], v[186:189], v[202:205], v[96:99]
	v_mfma_f32_16x16x32_bf16 v[84:87], v[172:175], v[210:213], v[84:87]
	v_mfma_f32_16x16x32_bf16 v[80:83], v[186:189], v[210:213], v[80:83]
	v_mfma_f32_16x16x32_bf16 v[68:71], v[172:175], v[218:221], v[68:71]
	v_mfma_f32_16x16x32_bf16 v[64:67], v[186:189], v[218:221], v[64:67]
	s_barrier
	s_add_i32 s30, s59, s35
	s_mov_b32 m0, s30
	ds_read_b128 v[190:193], v154 offset:49152
	ds_read_b128 v[194:197], v154 offset:50176
	ds_read_b128 v[198:201], v154 offset:51200
	ds_read_b128 v[202:205], v154 offset:52224
	ds_read_b128 v[206:209], v154 offset:53248
	ds_read_b128 v[210:213], v154 offset:54272
	ds_read_b128 v[214:217], v154 offset:55296
	ds_read_b128 v[218:221], v154 offset:56320
	global_load_lds_dwordx4 v132, s[98:99]
	s_add_i32 m0, s30, 0x2000
	s_add_u32 s28, s28, 0x40080
	s_addc_u32 s29, s29, 0
	s_add_i32 s30, s60, s35
	global_load_lds_dwordx4 v128, s[98:99]
	s_mov_b32 m0, s30
	s_nop 0
	global_load_lds_dwordx4 v132, s[28:29]
	s_add_i32 m0, s30, 0x2000
	s_nop 0
	global_load_lds_dwordx4 v128, s[28:29]
	s_mov_b32 m0, s42
	s_nop 0
	global_load_lds_dwordx4 v134, s[100:101]
	s_mov_b32 m0, s43
	s_nop 0
	global_load_lds_dwordx4 v130, s[100:101]
	s_waitcnt vmcnt(8)
	s_waitcnt lgkmcnt(0)
	s_barrier
	s_waitcnt lgkmcnt(0)
	v_mfma_f32_16x16x32_bf16 v[60:63], v[146:149], v[190:193], v[60:63]
	v_mfma_f32_16x16x32_bf16 v[56:59], v[160:163], v[190:193], v[56:59]
	v_mfma_f32_16x16x32_bf16 v[44:47], v[146:149], v[198:201], v[44:47]
	v_mfma_f32_16x16x32_bf16 v[40:43], v[160:163], v[198:201], v[40:43]
	v_mfma_f32_16x16x32_bf16 v[28:31], v[146:149], v[206:209], v[28:31]
	v_mfma_f32_16x16x32_bf16 v[24:27], v[160:163], v[206:209], v[24:27]
	v_mfma_f32_16x16x32_bf16 v[12:15], v[146:149], v[214:217], v[12:15]
	v_mfma_f32_16x16x32_bf16 v[8:11], v[160:163], v[214:217], v[8:11]
	v_mfma_f32_16x16x32_bf16 v[60:63], v[156:159], v[194:197], v[60:63]
	v_mfma_f32_16x16x32_bf16 v[56:59], v[164:167], v[194:197], v[56:59]
	v_mfma_f32_16x16x32_bf16 v[44:47], v[156:159], v[202:205], v[44:47]
	v_mfma_f32_16x16x32_bf16 v[40:43], v[164:167], v[202:205], v[40:43]
	v_mfma_f32_16x16x32_bf16 v[28:31], v[156:159], v[210:213], v[28:31]
	v_mfma_f32_16x16x32_bf16 v[24:27], v[164:167], v[210:213], v[24:27]
	v_mfma_f32_16x16x32_bf16 v[12:15], v[156:159], v[218:221], v[12:15]
	v_mfma_f32_16x16x32_bf16 v[8:11], v[164:167], v[218:221], v[8:11]
	v_mfma_f32_16x16x32_bf16 v[52:55], v[168:171], v[190:193], v[52:55]
	v_mfma_f32_16x16x32_bf16 v[48:51], v[176:179], v[190:193], v[48:51]
	v_mfma_f32_16x16x32_bf16 v[36:39], v[168:171], v[198:201], v[36:39]
	v_mfma_f32_16x16x32_bf16 v[32:35], v[176:179], v[198:201], v[32:35]
	v_mfma_f32_16x16x32_bf16 v[20:23], v[168:171], v[206:209], v[20:23]
	v_mfma_f32_16x16x32_bf16 v[16:19], v[176:179], v[206:209], v[16:19]
	v_mfma_f32_16x16x32_bf16 v[4:7], v[168:171], v[214:217], v[4:7]
	v_mfma_f32_16x16x32_bf16 v[0:3], v[176:179], v[214:217], v[0:3]
	v_mfma_f32_16x16x32_bf16 v[52:55], v[172:175], v[194:197], v[52:55]
	v_mfma_f32_16x16x32_bf16 v[48:51], v[186:189], v[194:197], v[48:51]
	v_mfma_f32_16x16x32_bf16 v[36:39], v[172:175], v[202:205], v[36:39]
	v_mfma_f32_16x16x32_bf16 v[32:35], v[186:189], v[202:205], v[32:35]
	v_mfma_f32_16x16x32_bf16 v[20:23], v[172:175], v[210:213], v[20:23]
	v_mfma_f32_16x16x32_bf16 v[16:19], v[186:189], v[210:213], v[16:19]
	v_mfma_f32_16x16x32_bf16 v[4:7], v[172:175], v[218:221], v[4:7]
	v_mfma_f32_16x16x32_bf16 v[0:3], v[186:189], v[218:221], v[0:3]
	s_barrier
	s_add_i32 s58, s58, 2
	s_add_u32 s26, s26, 0x100
	s_addc_u32 s27, s27, 0
	s_add_u32 s56, s56, 0x100
	s_addc_u32 s57, s57, 0
	s_cmp_gt_u32 s58, 13
	s_cbranch_scc0 .LBB0_860
	s_and_b64 vcc, exec, s[14:15]
	s_cbranch_vccz .LBB0_863
	s_barrier

; #define PG8_WAIT_V(n) asm volatile("s_waitcnt vmcnt(" #n ")" ::: "memory")
; #define PG8_BAR __builtin_amdgcn_s_barrier()
; #define LAS __attribute__((address_space(3)))
; template <class Epi, class Sched, bool ALIGN_EPI = false, bool SP2 = false>
; __device__ __forceinline__ void gemm_phase(PG8_LAS unsigned char* lds, const Gemm g, const Sched& S, const Epi& E) {
;     ...
;         PG8_STAGE(PG8_SB(1, 0), cB + kstep, voffB); PG8_STAGE(PG8_SA(1, 0), cA + kstep, voffA); PG8_STAGE(PG8_SB(1, 1), cB + hstep + kstep, voffB);
;         PG8_WAIT_V(6); PG8_BAR;
;     } else {
;         PG8_STAGE(PG8_SB(0, 0), cB, voffB); PG8_STAGE(PG8_SA(0, 0), cA, voffA); PG8_STAGE(PG8_SB(0, 1), cB + hstep, voffB); PG8_STAGE(PG8_SA(0, 1), cA + hstep, voffA);
;         if (wr == 1) PG8_BAR;
;         PG8_WAIT_V(4); PG8_BAR;
;         PG8_STAGE(PG8_SB(1, 0), cB + kstep, voffB); PG8_STAGE(PG8_SA(1, 0), cA + kstep, voffA); PG8_STAGE(PG8_SB(1, 1), cB + hstep + kstep, voffB);
;         PG8_WAIT_V(6); PG8_BAR;
;     DI void operator()(const f32x4 (&acc)[2][2][4][2], const Unit& u, int wr, int wc, int fr, int fq) const {
;         LAS unsigned char* st = lstage + (wr * 4 + wc) * 4096;
; #pragma unroll
;         for (int ai = 0; ai < 2; ++ai)
; #pragma unroll
;             for (int m = 0; m < 4; ++m) {
;                 const int row0g = u.pm * 256 + 128 * ai + 64 * wr + 16 * m, row = row0g + fr;
; #pragma unroll
;                 for (int bj = 0; bj < 2; ++bj) {
;                     const size_t idx = (size_t)row * DM + u.pn * 256 + 128 * bj + 32 * wc + 8 * fq;
;                     const u32x4 hb = *(const u32x4*)(HB + idx);
;                     f32x4 v0 = acc[ai][bj][m][0], v1 = acc[ai][bj][m][1];
;                     v0[0] += bflo(hb.x); v0[1] += bfhi(hb.x); v0[2] += bflo(hb.y); v0[3] += bfhi(hb.y); v1[0] += bflo(hb.z); v1[1] += bfhi(hb.z); v1[2] += bflo(hb.w); v1[3] += bfhi(hb.w);
;                     *(LAS f32x4*)(st + fr * 256 + (((bj * 8 + fq * 2) ^ fr) << 4)) = v0; *(LAS f32x4*)(st + fr * 256 + (((bj * 8 + fq * 2 + 1) ^ fr) << 4)) = v1;
;                 }
;                 float* ob = out + (size_t)row0g * DM + u.pn * 256 + 128 * (fr >> 3) + 32 * wc + (fr & 7) * 4;
; #pragma unroll
;                 for (int j = 0; j < 4; ++j) { const int rr = 4 * j + fq; const f32x4 d = *(const LAS f32x4*)(st + rr * 256 + ((fr ^ rr) << 4));
.LBB0_888:
	v_and_b32_e32 v158, 15, v182
	v_bfe_u32 v19, v182, 4, 2
	v_lshlrev_b32_e32 v20, 4, v19
	v_lshlrev_b32_e32 v21, 2, v158
	s_sext_i32_i8 s24, s0
	s_and_b32 s0, s10, 3
	v_lshl_or_b32 v20, v158, 6, v20
	s_lshl_b32 s10, s5, 13
	v_and_b32_e32 v22, 32, v21
	v_bitop3_b32 v24, v20, s10, v22 bitop3:0xde
	s_mov_b64 s[10:11], 0x80
	s_add_i32 m0, s31, 0x18000
	v_lshl_add_u64 v[6:7], v[6:7], 0, s[10:11]
	s_lshl_b32 s36, s5, 6
	s_lshl_b32 s37, s0, 5
	s_lshl_b32 s0, s0, 12
	s_waitcnt vmcnt(2)
	s_barrier
	global_load_lds_dwordx4 v[6:7], off
	v_lshl_add_u64 v[4:5], v[4:5], 0, s[10:11]
	s_add_i32 m0, s31, 0x1a000
	s_add_i32 s38, s31, 0x8000
	s_add_i32 s39, s31, 0xa000
	global_load_lds_dwordx4 v[4:5], off
	v_lshl_add_u64 v[0:1], v[0:1], 0, s[10:11]
	s_mov_b32 m0, s38
	s_add_u32 s12, s18, 0xb0080
	global_load_lds_dwordx4 v[0:1], off
	v_lshl_add_u64 v[0:1], v[2:3], 0, s[10:11]
	s_mov_b32 m0, s39
	s_addc_u32 s13, s19, 0
	global_load_lds_dwordx4 v[0:1], off
	s_add_i32 m0, s31, 0x1c000
	v_lshl_add_u64 v[0:1], s[12:13], 0, v[132:133]
	global_load_lds_dwordx4 v[0:1], off
	v_lshl_add_u64 v[0:1], s[12:13], 0, v[128:129]
	s_add_i32 m0, s31, 0x1e000
	s_cmpk_lt_u32 s4, 0x100
	global_load_lds_dwordx4 v[0:1], off
	s_cselect_b64 s[12:13], -1, 0
	s_lshl_b32 s4, s5, 14
	v_lshlrev_b32_e32 v1, 1, v19
	v_bitop3_b32 v4, v1, v182, 15 bitop3:0x78
	s_add_i32 s4, s4, 0
	v_bitop3_b32 v159, v20, s0, v22 bitop3:0xde
	v_lshlrev_b32_e32 v5, 4, v4
	v_bitop3_b32 v4, v1, v158, 1 bitop3:0x36
	s_add_i32 s0, s4, s0
	v_lshrrev_b32_e32 v17, 4, v182
	v_and_b32_e32 v0, 0x80, v12
	v_and_b32_e32 v2, 28, v21
	v_lshlrev_b32_e32 v7, 4, v4
	v_bitop3_b32 v4, v1, v158, 8 bitop3:0x36
	v_or_b32_e32 v21, 4, v19
	v_bitop3_b32 v6, v19, v158, 4 bitop3:0x36
	v_or_b32_e32 v22, 8, v19
	v_bitop3_b32 v12, v19, v158, 8 bitop3:0x36
	v_or_b32_e32 v23, 12, v19
	s_add_i32 s0, s0, 0x20000
	v_lshlrev_b32_e32 v18, 3, v19
	v_bitop3_b32 v3, v17, v158, 3 bitop3:0x6c
	v_lshlrev_b32_e32 v17, 4, v4
	v_lshlrev_b32_e32 v4, 10, v19
	v_lshlrev_b32_e32 v25, 4, v6
	v_lshlrev_b32_e32 v6, 10, v21
	v_lshlrev_b32_e32 v26, 4, v12
	v_lshlrev_b32_e32 v12, 10, v22
	v_bitop3_b32 v20, v19, v158, 12 bitop3:0x36
	v_lshl_add_u32 v28, v158, 8, s0
	v_lshl_add_u32 v19, v19, 8, s0
	v_lshl_add_u32 v21, v21, 8, s0
	v_lshl_add_u32 v29, v22, 8, s0
	v_lshl_add_u32 v30, v23, 8, s0
	v_lshrrev_b32_e32 v22, 1, v14
	v_mul_lo_u32 v14, v13, s1
	s_mov_b32 s0, 0xb000
	v_lshlrev_b32_e32 v27, 4, v20
	v_lshlrev_b32_e32 v20, 10, v23
	v_mad_u64_u32 v[22:23], s[4:5], v22, s0, v[14:15]
	v_or_b32_e32 v13, v22, v15
	v_add_lshl_u32 v136, v13, v16, 1
	v_lshrrev_b32_e32 v13, 1, v8
	v_mul_lo_u32 v8, v9, s1
	v_mad_u64_u32 v[8:9], s[0:1], v13, s0, v[8:9]
	s_mov_b64 s[14:15], 0xb0080
	s_waitcnt vmcnt(6)
	v_bitop3_b32 v1, v1, v158, 9 bitop3:0x36
	v_or_b32_e32 v8, v8, v10
	v_lshlrev_b32_e32 v3, 4, v3
	v_lshlrev_b32_e32 v1, 4, v1
	v_lshl_add_u64 v[138:139], v[136:137], 0, s[14:15]
	v_add_lshl_u32 v136, v8, v11, 1
	s_add_i32 s41, 0, 0x10000
	s_add_i32 s42, 0, 0x14000
	s_ashr_i32 s40, s3, 31
	v_lshl_add_u64 v[140:141], v[136:137], 0, s[14:15]
	v_add_u32_e32 v160, 0, v24
	v_lshlrev_b32_e32 v136, 1, v18
	v_add_u32_e32 v161, v28, v5
	v_add_u32_e32 v162, v28, v7
	v_add_u32_e32 v163, v28, v17
	v_add_u32_e32 v164, v28, v1
	v_lshlrev_b32_e32 v142, 2, v0
	v_lshlrev_b32_e32 v144, 2, v2
	v_add_u32_e32 v165, v19, v3
	v_lshlrev_b32_e32 v146, 2, v4
	v_add_u32_e32 v166, v21, v25
	v_lshlrev_b32_e32 v148, 2, v6
	v_add_u32_e32 v167, v29, v26
	v_lshlrev_b32_e32 v150, 2, v12
	v_add_u32_e32 v168, v30, v27
	v_lshlrev_b32_e32 v152, 2, v20
	v_mov_b64_e32 v[154:155], 0x410
	v_mov_b64_e32 v[156:157], 0x40f
	v_add_u32_e32 v169, s41, v159
	v_add_u32_e32 v170, s42, v159
	s_mov_b32 s43, 0
	s_barrier
	v_readfirstlane_b32 s94, v182
	s_nop 0
	s_cmpk_lt_u32 s94, 0x100
	s_cbranch_scc1 .Lprio_p5
	s_setprio 1
.Lprio_p5:
	s_branch .LBB0_891
.LBB0_889:
	s_mov_b64 s[0:1], 0

; #define PG8_STAGE(bufoff, gbase, voff) do { _Pragma("unroll") for (int _i = 0; _i < 2; ++_i) \
;         __builtin_amdgcn_global_load_lds((const unsigned*)((const char*)(gbase) + (voff)[_i]), (PG8_LAS unsigned*)(lds + (bufoff) + ldsw + _i * 8192), 16, 0, 0); } while (0)
; #define PG8_LDA(dst, b, h) do { _Pragma("unroll") for (int m = 0; m < 4; ++m) _Pragma("unroll") for (int k = 0; k < 2; ++k) dst[m][k] = *(const PG8_LAS bf16x8*)(lds + PG8_SA(b, h) + aoff + m * 2048 + k * 1024); } while (0)
; #define PG8_LDB(dst, b, h) do { _Pragma("unroll") for (int n = 0; n < 2; ++n) _Pragma("unroll") for (int k = 0; k < 2; ++k) dst[n][k] = *(const PG8_LAS bf16x8*)(lds + PG8_SB(b, h) + boff + n * 2048 + k * 1024); } while (0)
; #define PG8_MMA(ai, bj, At, Bt) do { __builtin_amdgcn_s_setprio(1); _Pragma("unroll") for (int m = 0; m < 4; ++m) _Pragma("unroll") for (int n = 0; n < 2; ++n) _Pragma("unroll") for (int k = 0; k < 2; ++k) \
;         acc[ai][bj][m][n] = __builtin_amdgcn_mfma_f32_16x16x32_bf16(Bt[n][k], At[m][k], acc[ai][bj][m][n], 0, 0, 0); __builtin_amdgcn_s_setprio(0); } while (0)
; #define PG8_WAIT_V(n) asm volatile("s_waitcnt vmcnt(" #n ")" ::: "memory")
; #define PG8_WAIT_L(n) asm volatile("s_waitcnt lgkmcnt(" #n ")" ::: "memory")
; #define PG8_BAR __builtin_amdgcn_s_barrier()
; #define PG8_SCHED __builtin_amdgcn_sched_barrier(0)
; template <class Epi, class Sched, bool ALIGN_EPI = false, bool SP2 = false>
; __device__ __forceinline__ void gemm_phase(PG8_LAS unsigned char* lds, const Gemm g, const Sched& S, const Epi& E) {
;     ...
;             const char* a1 = cA + (size_t)(t + 1) * kstep;
;             const char* a2 = last ? nA : cA + (size_t)(t + 2) * kstep; const char* b2 = last ? nB : cB + (size_t)(t + 2) * kstep;
;             const char* a3 = a2 + kstep; const char* b3 = b2 + kstep;
;             if (last && has_next) S.a_ready(nxt);
;     ...
;             PG8_LDB(B0, 0, 0); PG8_LDB(B1, 0, 1); PG8_SCHED; PG8_LDA(At, 0, 0); PG8_STAGE(PG8_SA(1, 1), a1 + hstep, voffA);
;             PG8_WAIT_V(8); PG8_WAIT_L(0); PG8_BAR; PG8_MMA(0, 0, At, B0); PG8_MMA(0, 1, At, B1); PG8_BAR; PG8_SCHED;
;             PG8_LDA(At, 0, 1); PG8_STAGE(PG8_SB(0, 0), b2, voffB); PG8_STAGE(PG8_SB(0, 1), b2 + hstep, voffB); PG8_STAGE(PG8_SA(0, 0), a2, voffA);
;             PG8_WAIT_V(8); PG8_WAIT_L(0); PG8_BAR; PG8_MMA(1, 0, At, B0); PG8_MMA(1, 1, At, B1); PG8_BAR; PG8_SCHED;
.Lsk5_nokoff:
	s_add_u32 s25, s18, 0x100
	s_addc_u32 s46, s19, 0
	s_mov_b32 s47, -2
	s_waitcnt vmcnt(0)
	ds_read_b128 v[172:175], v169
	ds_read_b128 v[176:179], v169 offset:1024
	ds_read_b128 v[180:183], v169 offset:2048
	ds_read_b128 v[184:187], v169 offset:3072
	ds_read_b128 v[188:191], v170
	ds_read_b128 v[192:195], v170 offset:1024
	ds_read_b128 v[196:199], v170 offset:2048
	ds_read_b128 v[200:203], v170 offset:3072
	s_add_u32 s18, s16, 0x100
	s_addc_u32 s19, s17, 0
	s_cmp_eq_u32 s47, s98
	s_cselect_b32 s23, s5, s19
	s_cselect_b32 s22, s4, s18
	s_cselect_b32 s21, s15, s46
	s_cselect_b32 s20, s14, s25
	s_add_i32 m0, s31, 0xc000
	ds_read_b128 v[204:207], v160
	ds_read_b128 v[208:211], v160 offset:1024
	ds_read_b128 v[212:215], v160 offset:2048
	ds_read_b128 v[216:219], v160 offset:3072
	ds_read_b128 v[220:223], v160 offset:4096
	ds_read_b128 v[224:227], v160 offset:5120
	ds_read_b128 v[228:231], v160 offset:6144
	ds_read_b128 v[232:235], v160 offset:7168
	global_load_lds_dwordx4 v138, s[16:17]
	s_add_i32 m0, s31, 0xe000
	s_nop 0
	global_load_lds_dwordx4 v140, s[16:17]
	s_waitcnt vmcnt(8)
	s_waitcnt lgkmcnt(0)
	s_barrier
	s_waitcnt lgkmcnt(0)
	v_mfma_f32_16x16x32_bf16 v[124:127], v[172:175], v[204:207], 0
	v_mfma_f32_16x16x32_bf16 v[120:123], v[180:183], v[204:207], 0
	v_mfma_f32_16x16x32_bf16 v[108:111], v[172:175], v[212:215], 0
	v_mfma_f32_16x16x32_bf16 v[104:107], v[180:183], v[212:215], 0
	v_mfma_f32_16x16x32_bf16 v[92:95], v[172:175], v[220:223], 0
	v_mfma_f32_16x16x32_bf16 v[88:91], v[180:183], v[220:223], 0
	v_mfma_f32_16x16x32_bf16 v[76:79], v[172:175], v[228:231], 0
	v_mfma_f32_16x16x32_bf16 v[72:75], v[180:183], v[228:231], 0
	v_mfma_f32_16x16x32_bf16 v[124:127], v[176:179], v[208:211], v[124:127]
	v_mfma_f32_16x16x32_bf16 v[120:123], v[184:187], v[208:211], v[120:123]
	v_mfma_f32_16x16x32_bf16 v[108:111], v[176:179], v[216:219], v[108:111]
	v_mfma_f32_16x16x32_bf16 v[104:107], v[184:187], v[216:219], v[104:107]
	v_mfma_f32_16x16x32_bf16 v[92:95], v[176:179], v[224:227], v[92:95]
	v_mfma_f32_16x16x32_bf16 v[88:91], v[184:187], v[224:227], v[88:91]
	v_mfma_f32_16x16x32_bf16 v[76:79], v[176:179], v[232:235], v[76:79]
	v_mfma_f32_16x16x32_bf16 v[72:75], v[184:187], v[232:235], v[72:75]
	v_mfma_f32_16x16x32_bf16 v[116:119], v[188:191], v[204:207], 0
	v_mfma_f32_16x16x32_bf16 v[112:115], v[196:199], v[204:207], 0
	v_mfma_f32_16x16x32_bf16 v[100:103], v[188:191], v[212:215], 0
	v_mfma_f32_16x16x32_bf16 v[96:99], v[196:199], v[212:215], 0
	v_mfma_f32_16x16x32_bf16 v[84:87], v[188:191], v[220:223], 0
	v_mfma_f32_16x16x32_bf16 v[80:83], v[196:199], v[220:223], 0
	v_mfma_f32_16x16x32_bf16 v[68:71], v[188:191], v[228:231], 0
	v_mfma_f32_16x16x32_bf16 v[64:67], v[196:199], v[228:231], 0
	v_mfma_f32_16x16x32_bf16 v[116:119], v[192:195], v[208:211], v[116:119]
	v_mfma_f32_16x16x32_bf16 v[112:115], v[200:203], v[208:211], v[112:115]
	v_mfma_f32_16x16x32_bf16 v[100:103], v[192:195], v[216:219], v[100:103]
	v_mfma_f32_16x16x32_bf16 v[96:99], v[200:203], v[216:219], v[96:99]
	v_mfma_f32_16x16x32_bf16 v[84:87], v[192:195], v[224:227], v[84:87]
	v_mfma_f32_16x16x32_bf16 v[80:83], v[200:203], v[224:227], v[80:83]
	v_mfma_f32_16x16x32_bf16 v[68:71], v[192:195], v[232:235], v[68:71]
	v_mfma_f32_16x16x32_bf16 v[64:67], v[200:203], v[232:235], v[64:67]
	s_barrier
	s_add_i32 s16, s41, s28
	s_mov_b32 m0, s16
	ds_read_b128 v[204:207], v160 offset:16384
	ds_read_b128 v[208:211], v160 offset:17408
	ds_read_b128 v[212:215], v160 offset:18432
	ds_read_b128 v[216:219], v160 offset:19456
	ds_read_b128 v[220:223], v160 offset:20480
	ds_read_b128 v[224:227], v160 offset:21504
	ds_read_b128 v[228:231], v160 offset:22528
	ds_read_b128 v[232:235], v160 offset:23552
	global_load_lds_dwordx4 v132, s[20:21]
	s_add_i32 m0, s16, 0x2000
	s_add_u32 s16, s20, 0xb0000
	s_addc_u32 s17, s21, 0
	s_add_u32 s94, s20, s10
	s_addc_u32 s95, s21, s11
	s_add_u32 s96, s22, s10
	s_addc_u32 s97, s23, s11
	s_add_i32 s48, s42, s28
	global_load_lds_dwordx4 v128, s[20:21]
	s_mov_b32 m0, s48
	s_nop 0
	global_load_lds_dwordx4 v132, s[16:17]
	s_add_i32 m0, s48, 0x2000
	s_nop 0
	global_load_lds_dwordx4 v128, s[16:17]
	s_mov_b32 m0, s31
	s_nop 0
	global_load_lds_dwordx4 v134, s[22:23]
	s_mov_b32 m0, s33
	s_nop 0
	global_load_lds_dwordx4 v130, s[22:23]
	s_waitcnt vmcnt(8)
	s_waitcnt lgkmcnt(0)
	s_barrier
	s_waitcnt lgkmcnt(0)
	v_mfma_f32_16x16x32_bf16 v[60:63], v[172:175], v[204:207], 0
	v_mfma_f32_16x16x32_bf16 v[56:59], v[180:183], v[204:207], 0
	v_mfma_f32_16x16x32_bf16 v[44:47], v[172:175], v[212:215], 0
	v_mfma_f32_16x16x32_bf16 v[40:43], v[180:183], v[212:215], 0
	v_mfma_f32_16x16x32_bf16 v[28:31], v[172:175], v[220:223], 0
	v_mfma_f32_16x16x32_bf16 v[24:27], v[180:183], v[220:223], 0
	v_mfma_f32_16x16x32_bf16 v[12:15], v[172:175], v[228:231], 0
	v_mfma_f32_16x16x32_bf16 v[8:11], v[180:183], v[228:231], 0
	v_mfma_f32_16x16x32_bf16 v[60:63], v[176:179], v[208:211], v[60:63]
	v_mfma_f32_16x16x32_bf16 v[56:59], v[184:187], v[208:211], v[56:59]
	v_mfma_f32_16x16x32_bf16 v[44:47], v[176:179], v[216:219], v[44:47]
	v_mfma_f32_16x16x32_bf16 v[40:43], v[184:187], v[216:219], v[40:43]
	v_mfma_f32_16x16x32_bf16 v[28:31], v[176:179], v[224:227], v[28:31]
	v_mfma_f32_16x16x32_bf16 v[24:27], v[184:187], v[224:227], v[24:27]
	v_mfma_f32_16x16x32_bf16 v[12:15], v[176:179], v[232:235], v[12:15]
	v_mfma_f32_16x16x32_bf16 v[8:11], v[184:187], v[232:235], v[8:11]
	v_mfma_f32_16x16x32_bf16 v[52:55], v[188:191], v[204:207], 0
	v_mfma_f32_16x16x32_bf16 v[48:51], v[196:199], v[204:207], 0
	v_mfma_f32_16x16x32_bf16 v[36:39], v[188:191], v[212:215], 0
	v_mfma_f32_16x16x32_bf16 v[32:35], v[196:199], v[212:215], 0
	v_mfma_f32_16x16x32_bf16 v[20:23], v[188:191], v[220:223], 0
	v_mfma_f32_16x16x32_bf16 v[16:19], v[196:199], v[220:223], 0
	v_mfma_f32_16x16x32_bf16 v[4:7], v[188:191], v[228:231], 0
	v_mfma_f32_16x16x32_bf16 v[0:3], v[196:199], v[228:231], 0
	v_mfma_f32_16x16x32_bf16 v[52:55], v[192:195], v[208:211], v[52:55]
	v_mfma_f32_16x16x32_bf16 v[48:51], v[200:203], v[208:211], v[48:51]
	v_mfma_f32_16x16x32_bf16 v[36:39], v[192:195], v[216:219], v[36:39]
	v_mfma_f32_16x16x32_bf16 v[32:35], v[200:203], v[216:219], v[32:35]
	v_mfma_f32_16x16x32_bf16 v[20:23], v[192:195], v[224:227], v[20:23]
	v_mfma_f32_16x16x32_bf16 v[16:19], v[200:203], v[224:227], v[16:19]
	v_mfma_f32_16x16x32_bf16 v[4:7], v[192:195], v[232:235], v[4:7]
	v_mfma_f32_16x16x32_bf16 v[0:3], v[200:203], v[232:235], v[0:3]
	s_barrier
; #define PG8_STAGE(bufoff, gbase, voff) do { _Pragma("unroll") for (int _i = 0; _i < 2; ++_i) \
;         __builtin_amdgcn_global_load_lds((const unsigned*)((const char*)(gbase) + (voff)[_i]), (PG8_LAS unsigned*)(lds + (bufoff) + ldsw + _i * 8192), 16, 0, 0); } while (0)
; #define PG8_LDA(dst, b, h) do { _Pragma("unroll") for (int m = 0; m < 4; ++m) _Pragma("unroll") for (int k = 0; k < 2; ++k) dst[m][k] = *(const PG8_LAS bf16x8*)(lds + PG8_SA(b, h) + aoff + m * 2048 + k * 1024); } while (0)
; #define PG8_LDB(dst, b, h) do { _Pragma("unroll") for (int n = 0; n < 2; ++n) _Pragma("unroll") for (int k = 0; k < 2; ++k) dst[n][k] = *(const PG8_LAS bf16x8*)(lds + PG8_SB(b, h) + boff + n * 2048 + k * 1024); } while (0)
; #define PG8_MMA(ai, bj, At, Bt) do { __builtin_amdgcn_s_setprio(1); _Pragma("unroll") for (int m = 0; m < 4; ++m) _Pragma("unroll") for (int n = 0; n < 2; ++n) _Pragma("unroll") for (int k = 0; k < 2; ++k) \
;         acc[ai][bj][m][n] = __builtin_amdgcn_mfma_f32_16x16x32_bf16(Bt[n][k], At[m][k], acc[ai][bj][m][n], 0, 0, 0); __builtin_amdgcn_s_setprio(0); } while (0)
; #define PG8_WAIT_V(n) asm volatile("s_waitcnt vmcnt(" #n ")" ::: "memory")
; #define PG8_WAIT_L(n) asm volatile("s_waitcnt lgkmcnt(" #n ")" ::: "memory")
; #define PG8_BAR __builtin_amdgcn_s_barrier()
; #define PG8_SCHED __builtin_amdgcn_sched_barrier(0)
; template <class Epi, class Sched, bool ALIGN_EPI = false, bool SP2 = false>
; __device__ __forceinline__ void gemm_phase(PG8_LAS unsigned char* lds, const Gemm g, const Sched& S, const Epi& E) {
;     ...
;             PG8_LDB(B0, 1, 0); PG8_LDB(B1, 1, 1); PG8_SCHED; PG8_LDA(At, 1, 0); PG8_STAGE(PG8_SA(0, 1), a2 + hstep, voffA);
;             PG8_WAIT_V(8); PG8_WAIT_L(0); PG8_BAR; PG8_MMA(0, 0, At, B0); PG8_MMA(0, 1, At, B1); PG8_BAR; PG8_SCHED;
;             PG8_LDA(At, 1, 1); PG8_STAGE(PG8_SB(1, 0), b3, voffB); PG8_STAGE(PG8_SB(1, 1), b3 + hstep, voffB); PG8_STAGE(PG8_SA(1, 0), a3, voffA);
;             PG8_WAIT_V(8); PG8_WAIT_L(0); PG8_BAR; PG8_MMA(1, 0, At, B0); PG8_MMA(1, 1, At, B1); PG8_BAR; PG8_SCHED;
	s_add_i32 s48, 0, 0x18000
	v_add_u32_e32 v143, s48, v159
	s_add_i32 s49, 0, 0x1c000
	ds_read_b128 v[172:175], v143
	ds_read_b128 v[176:179], v143 offset:1024
	ds_read_b128 v[180:183], v143 offset:2048
	ds_read_b128 v[184:187], v143 offset:3072
	v_add_u32_e32 v143, s49, v159
	ds_read_b128 v[188:191], v143
	ds_read_b128 v[192:195], v143 offset:1024
	ds_read_b128 v[196:199], v143 offset:2048
	ds_read_b128 v[200:203], v143 offset:3072
	s_add_u32 s16, s22, 0xb0000
	s_addc_u32 s17, s23, 0
	s_mov_b32 m0, s34
	ds_read_b128 v[204:207], v160 offset:32768
	ds_read_b128 v[208:211], v160 offset:33792
	ds_read_b128 v[212:215], v160 offset:34816
	ds_read_b128 v[216:219], v160 offset:35840
	ds_read_b128 v[220:223], v160 offset:36864
	ds_read_b128 v[224:227], v160 offset:37888
	ds_read_b128 v[228:231], v160 offset:38912
	ds_read_b128 v[232:235], v160 offset:39936
	global_load_lds_dwordx4 v134, s[16:17]
	s_mov_b32 m0, s35
	s_nop 0
	global_load_lds_dwordx4 v130, s[16:17]
	s_waitcnt vmcnt(8)
	s_waitcnt lgkmcnt(0)
	s_barrier
	s_waitcnt lgkmcnt(0)
	v_mfma_f32_16x16x32_bf16 v[124:127], v[172:175], v[204:207], v[124:127]
	v_mfma_f32_16x16x32_bf16 v[120:123], v[180:183], v[204:207], v[120:123]
	v_mfma_f32_16x16x32_bf16 v[108:111], v[172:175], v[212:215], v[108:111]
	v_mfma_f32_16x16x32_bf16 v[104:107], v[180:183], v[212:215], v[104:107]
	v_mfma_f32_16x16x32_bf16 v[92:95], v[172:175], v[220:223], v[92:95]
	v_mfma_f32_16x16x32_bf16 v[88:91], v[180:183], v[220:223], v[88:91]
	v_mfma_f32_16x16x32_bf16 v[76:79], v[172:175], v[228:231], v[76:79]
	v_mfma_f32_16x16x32_bf16 v[72:75], v[180:183], v[228:231], v[72:75]
	v_mfma_f32_16x16x32_bf16 v[124:127], v[176:179], v[208:211], v[124:127]
	v_mfma_f32_16x16x32_bf16 v[120:123], v[184:187], v[208:211], v[120:123]
	v_mfma_f32_16x16x32_bf16 v[108:111], v[176:179], v[216:219], v[108:111]
	v_mfma_f32_16x16x32_bf16 v[104:107], v[184:187], v[216:219], v[104:107]
	v_mfma_f32_16x16x32_bf16 v[92:95], v[176:179], v[224:227], v[92:95]
	v_mfma_f32_16x16x32_bf16 v[88:91], v[184:187], v[224:227], v[88:91]
	v_mfma_f32_16x16x32_bf16 v[76:79], v[176:179], v[232:235], v[76:79]
	v_mfma_f32_16x16x32_bf16 v[72:75], v[184:187], v[232:235], v[72:75]
	v_mfma_f32_16x16x32_bf16 v[116:119], v[188:191], v[204:207], v[116:119]
	v_mfma_f32_16x16x32_bf16 v[112:115], v[196:199], v[204:207], v[112:115]
	v_mfma_f32_16x16x32_bf16 v[100:103], v[188:191], v[212:215], v[100:103]
	v_mfma_f32_16x16x32_bf16 v[96:99], v[196:199], v[212:215], v[96:99]
	v_mfma_f32_16x16x32_bf16 v[84:87], v[188:191], v[220:223], v[84:87]
	v_mfma_f32_16x16x32_bf16 v[80:83], v[196:199], v[220:223], v[80:83]
	v_mfma_f32_16x16x32_bf16 v[68:71], v[188:191], v[228:231], v[68:71]
	v_mfma_f32_16x16x32_bf16 v[64:67], v[196:199], v[228:231], v[64:67]
	v_mfma_f32_16x16x32_bf16 v[116:119], v[192:195], v[208:211], v[116:119]
	v_mfma_f32_16x16x32_bf16 v[112:115], v[200:203], v[208:211], v[112:115]
	v_mfma_f32_16x16x32_bf16 v[100:103], v[192:195], v[216:219], v[100:103]
	v_mfma_f32_16x16x32_bf16 v[96:99], v[200:203], v[216:219], v[96:99]
	v_mfma_f32_16x16x32_bf16 v[84:87], v[192:195], v[224:227], v[84:87]
	v_mfma_f32_16x16x32_bf16 v[80:83], v[200:203], v[224:227], v[80:83]
	v_mfma_f32_16x16x32_bf16 v[68:71], v[192:195], v[232:235], v[68:71]
	v_mfma_f32_16x16x32_bf16 v[64:67], v[200:203], v[232:235], v[64:67]
	s_barrier
	s_add_i32 s16, s48, s28
	s_mov_b32 m0, s16
	ds_read_b128 v[204:207], v160 offset:49152
	ds_read_b128 v[208:211], v160 offset:50176
	ds_read_b128 v[212:215], v160 offset:51200
	ds_read_b128 v[216:219], v160 offset:52224
	ds_read_b128 v[220:223], v160 offset:53248
	ds_read_b128 v[224:227], v160 offset:54272
	ds_read_b128 v[228:231], v160 offset:55296
	ds_read_b128 v[232:235], v160 offset:56320
	global_load_lds_dwordx4 v132, s[94:95]
	s_add_i32 m0, s16, 0x2000
	s_add_u32 s16, s20, 0xb0080
	s_addc_u32 s17, s21, 0
	s_add_i32 s20, s49, s28
	global_load_lds_dwordx4 v128, s[94:95]
	s_mov_b32 m0, s20
	s_nop 0
	global_load_lds_dwordx4 v132, s[16:17]
	s_add_i32 m0, s20, 0x2000
	s_nop 0
	global_load_lds_dwordx4 v128, s[16:17]
	s_mov_b32 m0, s38
	s_nop 0
	global_load_lds_dwordx4 v134, s[96:97]
	s_mov_b32 m0, s39
	s_nop 0
	global_load_lds_dwordx4 v130, s[96:97]
	s_waitcnt vmcnt(8)
	s_waitcnt lgkmcnt(0)
	s_barrier
	s_waitcnt lgkmcnt(0)
	v_mfma_f32_16x16x32_bf16 v[60:63], v[172:175], v[204:207], v[60:63]
	v_mfma_f32_16x16x32_bf16 v[56:59], v[180:183], v[204:207], v[56:59]
	v_mfma_f32_16x16x32_bf16 v[44:47], v[172:175], v[212:215], v[44:47]
	v_mfma_f32_16x16x32_bf16 v[40:43], v[180:183], v[212:215], v[40:43]
	v_mfma_f32_16x16x32_bf16 v[28:31], v[172:175], v[220:223], v[28:31]
	v_mfma_f32_16x16x32_bf16 v[24:27], v[180:183], v[220:223], v[24:27]
	v_mfma_f32_16x16x32_bf16 v[12:15], v[172:175], v[228:231], v[12:15]
	v_mfma_f32_16x16x32_bf16 v[8:11], v[180:183], v[228:231], v[8:11]
	v_mfma_f32_16x16x32_bf16 v[60:63], v[176:179], v[208:211], v[60:63]
	v_mfma_f32_16x16x32_bf16 v[56:59], v[184:187], v[208:211], v[56:59]
	v_mfma_f32_16x16x32_bf16 v[44:47], v[176:179], v[216:219], v[44:47]
	v_mfma_f32_16x16x32_bf16 v[40:43], v[184:187], v[216:219], v[40:43]
	v_mfma_f32_16x16x32_bf16 v[28:31], v[176:179], v[224:227], v[28:31]
	v_mfma_f32_16x16x32_bf16 v[24:27], v[184:187], v[224:227], v[24:27]
	v_mfma_f32_16x16x32_bf16 v[12:15], v[176:179], v[232:235], v[12:15]
	v_mfma_f32_16x16x32_bf16 v[8:11], v[184:187], v[232:235], v[8:11]
	v_mfma_f32_16x16x32_bf16 v[52:55], v[188:191], v[204:207], v[52:55]
	v_mfma_f32_16x16x32_bf16 v[48:51], v[196:199], v[204:207], v[48:51]
	v_mfma_f32_16x16x32_bf16 v[36:39], v[188:191], v[212:215], v[36:39]
	v_mfma_f32_16x16x32_bf16 v[32:35], v[196:199], v[212:215], v[32:35]
	v_mfma_f32_16x16x32_bf16 v[20:23], v[188:191], v[220:223], v[20:23]
	v_mfma_f32_16x16x32_bf16 v[16:19], v[196:199], v[220:223], v[16:19]
	v_mfma_f32_16x16x32_bf16 v[4:7], v[188:191], v[228:231], v[4:7]
	v_mfma_f32_16x16x32_bf16 v[0:3], v[196:199], v[228:231], v[0:3]
	v_mfma_f32_16x16x32_bf16 v[52:55], v[192:195], v[208:211], v[52:55]
	v_mfma_f32_16x16x32_bf16 v[48:51], v[200:203], v[208:211], v[48:51]
	v_mfma_f32_16x16x32_bf16 v[36:39], v[192:195], v[216:219], v[36:39]
	v_mfma_f32_16x16x32_bf16 v[32:35], v[200:203], v[216:219], v[32:35]
	v_mfma_f32_16x16x32_bf16 v[20:23], v[192:195], v[224:227], v[20:23]
	v_mfma_f32_16x16x32_bf16 v[16:19], v[200:203], v[224:227], v[16:19]
	v_mfma_f32_16x16x32_bf16 v[4:7], v[192:195], v[232:235], v[4:7]
	v_mfma_f32_16x16x32_bf16 v[0:3], v[200:203], v[232:235], v[0:3]
	s_barrier
	s_add_i32 s47, s47, 2
	s_add_u32 s25, s25, 0x100
	s_addc_u32 s46, s46, 0
	s_cmp_gt_u32 s47, s99
	s_mov_b64 s[16:17], s[18:19]
; #define PG8_STAGE(bufoff, gbase, voff) do { _Pragma("unroll") for (int _i = 0; _i < 2; ++_i) \
;         __builtin_amdgcn_global_load_lds((const unsigned*)((const char*)(gbase) + (voff)[_i]), (PG8_LAS unsigned*)(lds + (bufoff) + ldsw + _i * 8192), 16, 0, 0); } while (0)
; #define PG8_LDA(dst, b, h) do { _Pragma("unroll") for (int m = 0; m < 4; ++m) _Pragma("unroll") for (int k = 0; k < 2; ++k) dst[m][k] = *(const PG8_LAS bf16x8*)(lds + PG8_SA(b, h) + aoff + m * 2048 + k * 1024); } while (0)
; #define PG8_LDB(dst, b, h) do { _Pragma("unroll") for (int n = 0; n < 2; ++n) _Pragma("unroll") for (int k = 0; k < 2; ++k) dst[n][k] = *(const PG8_LAS bf16x8*)(lds + PG8_SB(b, h) + boff + n * 2048 + k * 1024); } while (0)
; #define PG8_MMA(ai, bj, At, Bt) do { __builtin_amdgcn_s_setprio(1); _Pragma("unroll") for (int m = 0; m < 4; ++m) _Pragma("unroll") for (int n = 0; n < 2; ++n) _Pragma("unroll") for (int k = 0; k < 2; ++k) \
;         acc[ai][bj][m][n] = __builtin_amdgcn_mfma_f32_16x16x32_bf16(Bt[n][k], At[m][k], acc[ai][bj][m][n], 0, 0, 0); __builtin_amdgcn_s_setprio(0); } while (0)
; #define PG8_WAIT_V(n) asm volatile("s_waitcnt vmcnt(" #n ")" ::: "memory")
; #define PG8_WAIT_L(n) asm volatile("s_waitcnt lgkmcnt(" #n ")" ::: "memory")
; #define PG8_BAR __builtin_amdgcn_s_barrier()
; #define PG8_SCHED __builtin_amdgcn_sched_barrier(0)
; template <class Epi, class Sched, bool ALIGN_EPI = false, bool SP2 = false>
; __device__ __forceinline__ void gemm_phase(PG8_LAS unsigned char* lds, const Gemm g, const Sched& S, const Epi& E) {
;     ...
;             PG8_LDB(B0, 0, 0); PG8_LDB(B1, 0, 1); PG8_SCHED; PG8_LDA(At, 0, 0); PG8_STAGE(PG8_SA(1, 1), a1 + hstep, voffA);
;             PG8_WAIT_V(8); PG8_WAIT_L(0); PG8_BAR; PG8_MMA(0, 0, At, B0); PG8_MMA(0, 1, At, B1); PG8_BAR; PG8_SCHED;
;             PG8_LDA(At, 0, 1); PG8_STAGE(PG8_SB(0, 0), b2, voffB); PG8_STAGE(PG8_SB(0, 1), b2 + hstep, voffB); PG8_STAGE(PG8_SA(0, 0), a2, voffA);
;             PG8_WAIT_V(8); PG8_WAIT_L(0); PG8_BAR; PG8_MMA(1, 0, At, B0); PG8_MMA(1, 1, At, B1); PG8_BAR; PG8_SCHED;
.LBB0_898:
	ds_read_b128 v[172:175], v169
	ds_read_b128 v[176:179], v169 offset:1024
	ds_read_b128 v[180:183], v169 offset:2048
	ds_read_b128 v[184:187], v169 offset:3072
	ds_read_b128 v[188:191], v170
	ds_read_b128 v[192:195], v170 offset:1024
	ds_read_b128 v[196:199], v170 offset:2048
	ds_read_b128 v[200:203], v170 offset:3072
	s_add_u32 s18, s16, 0x100
	s_addc_u32 s19, s17, 0
	s_cmp_eq_u32 s47, s98
	s_cselect_b32 s23, s5, s19
	s_cselect_b32 s22, s4, s18
	s_cselect_b32 s21, s15, s46
	s_cselect_b32 s20, s14, s25
	s_add_i32 m0, s31, 0xc000
	ds_read_b128 v[204:207], v160
	ds_read_b128 v[208:211], v160 offset:1024
	ds_read_b128 v[212:215], v160 offset:2048
	ds_read_b128 v[216:219], v160 offset:3072
	ds_read_b128 v[220:223], v160 offset:4096
	ds_read_b128 v[224:227], v160 offset:5120
	ds_read_b128 v[228:231], v160 offset:6144
	ds_read_b128 v[232:235], v160 offset:7168
	global_load_lds_dwordx4 v138, s[16:17]
	s_add_i32 m0, s31, 0xe000
	s_nop 0
	global_load_lds_dwordx4 v140, s[16:17]
	s_waitcnt vmcnt(8)
	s_waitcnt lgkmcnt(0)
	s_barrier
	s_waitcnt lgkmcnt(0)
	v_mfma_f32_16x16x32_bf16 v[124:127], v[172:175], v[204:207], v[124:127]
	v_mfma_f32_16x16x32_bf16 v[120:123], v[180:183], v[204:207], v[120:123]
	v_mfma_f32_16x16x32_bf16 v[108:111], v[172:175], v[212:215], v[108:111]
	v_mfma_f32_16x16x32_bf16 v[104:107], v[180:183], v[212:215], v[104:107]
	v_mfma_f32_16x16x32_bf16 v[92:95], v[172:175], v[220:223], v[92:95]
	v_mfma_f32_16x16x32_bf16 v[88:91], v[180:183], v[220:223], v[88:91]
	v_mfma_f32_16x16x32_bf16 v[76:79], v[172:175], v[228:231], v[76:79]
	v_mfma_f32_16x16x32_bf16 v[72:75], v[180:183], v[228:231], v[72:75]
	v_mfma_f32_16x16x32_bf16 v[124:127], v[176:179], v[208:211], v[124:127]
	v_mfma_f32_16x16x32_bf16 v[120:123], v[184:187], v[208:211], v[120:123]
	v_mfma_f32_16x16x32_bf16 v[108:111], v[176:179], v[216:219], v[108:111]
	v_mfma_f32_16x16x32_bf16 v[104:107], v[184:187], v[216:219], v[104:107]
	v_mfma_f32_16x16x32_bf16 v[92:95], v[176:179], v[224:227], v[92:95]
	v_mfma_f32_16x16x32_bf16 v[88:91], v[184:187], v[224:227], v[88:91]
	v_mfma_f32_16x16x32_bf16 v[76:79], v[176:179], v[232:235], v[76:79]
	v_mfma_f32_16x16x32_bf16 v[72:75], v[184:187], v[232:235], v[72:75]
	v_mfma_f32_16x16x32_bf16 v[116:119], v[188:191], v[204:207], v[116:119]
	v_mfma_f32_16x16x32_bf16 v[112:115], v[196:199], v[204:207], v[112:115]
	v_mfma_f32_16x16x32_bf16 v[100:103], v[188:191], v[212:215], v[100:103]
	v_mfma_f32_16x16x32_bf16 v[96:99], v[196:199], v[212:215], v[96:99]
	v_mfma_f32_16x16x32_bf16 v[84:87], v[188:191], v[220:223], v[84:87]
	v_mfma_f32_16x16x32_bf16 v[80:83], v[196:199], v[220:223], v[80:83]
	v_mfma_f32_16x16x32_bf16 v[68:71], v[188:191], v[228:231], v[68:71]
	v_mfma_f32_16x16x32_bf16 v[64:67], v[196:199], v[228:231], v[64:67]
	v_mfma_f32_16x16x32_bf16 v[116:119], v[192:195], v[208:211], v[116:119]
	v_mfma_f32_16x16x32_bf16 v[112:115], v[200:203], v[208:211], v[112:115]
	v_mfma_f32_16x16x32_bf16 v[100:103], v[192:195], v[216:219], v[100:103]
	v_mfma_f32_16x16x32_bf16 v[96:99], v[200:203], v[216:219], v[96:99]
	v_mfma_f32_16x16x32_bf16 v[84:87], v[192:195], v[224:227], v[84:87]
	v_mfma_f32_16x16x32_bf16 v[80:83], v[200:203], v[224:227], v[80:83]
	v_mfma_f32_16x16x32_bf16 v[68:71], v[192:195], v[232:235], v[68:71]
	v_mfma_f32_16x16x32_bf16 v[64:67], v[200:203], v[232:235], v[64:67]
	s_barrier
	s_add_i32 s16, s41, s28
	s_mov_b32 m0, s16
	ds_read_b128 v[204:207], v160 offset:16384
	ds_read_b128 v[208:211], v160 offset:17408
	ds_read_b128 v[212:215], v160 offset:18432
	ds_read_b128 v[216:219], v160 offset:19456
	ds_read_b128 v[220:223], v160 offset:20480
	ds_read_b128 v[224:227], v160 offset:21504
	ds_read_b128 v[228:231], v160 offset:22528
	ds_read_b128 v[232:235], v160 offset:23552
	global_load_lds_dwordx4 v132, s[20:21]
	s_add_i32 m0, s16, 0x2000
	s_add_u32 s16, s20, 0xb0000
	s_addc_u32 s17, s21, 0
	s_add_u32 s94, s20, s10
	s_addc_u32 s95, s21, s11
	s_add_u32 s96, s22, s10
	s_addc_u32 s97, s23, s11
	s_add_i32 s48, s42, s28
	global_load_lds_dwordx4 v128, s[20:21]
	s_mov_b32 m0, s48
	s_nop 0
	global_load_lds_dwordx4 v132, s[16:17]
	s_add_i32 m0, s48, 0x2000
	s_nop 0
	global_load_lds_dwordx4 v128, s[16:17]
	s_mov_b32 m0, s31
	s_nop 0
	global_load_lds_dwordx4 v134, s[22:23]
	s_mov_b32 m0, s33
	s_nop 0
	global_load_lds_dwordx4 v130, s[22:23]
	s_waitcnt vmcnt(8)
	s_waitcnt lgkmcnt(0)
	s_barrier
	s_waitcnt lgkmcnt(0)
	v_mfma_f32_16x16x32_bf16 v[60:63], v[172:175], v[204:207], v[60:63]
	v_mfma_f32_16x16x32_bf16 v[56:59], v[180:183], v[204:207], v[56:59]
	v_mfma_f32_16x16x32_bf16 v[44:47], v[172:175], v[212:215], v[44:47]
	v_mfma_f32_16x16x32_bf16 v[40:43], v[180:183], v[212:215], v[40:43]
	v_mfma_f32_16x16x32_bf16 v[28:31], v[172:175], v[220:223], v[28:31]
	v_mfma_f32_16x16x32_bf16 v[24:27], v[180:183], v[220:223], v[24:27]
	v_mfma_f32_16x16x32_bf16 v[12:15], v[172:175], v[228:231], v[12:15]
	v_mfma_f32_16x16x32_bf16 v[8:11], v[180:183], v[228:231], v[8:11]
	v_mfma_f32_16x16x32_bf16 v[60:63], v[176:179], v[208:211], v[60:63]
	v_mfma_f32_16x16x32_bf16 v[56:59], v[184:187], v[208:211], v[56:59]
	v_mfma_f32_16x16x32_bf16 v[44:47], v[176:179], v[216:219], v[44:47]
	v_mfma_f32_16x16x32_bf16 v[40:43], v[184:187], v[216:219], v[40:43]
	v_mfma_f32_16x16x32_bf16 v[28:31], v[176:179], v[224:227], v[28:31]
	v_mfma_f32_16x16x32_bf16 v[24:27], v[184:187], v[224:227], v[24:27]
	v_mfma_f32_16x16x32_bf16 v[12:15], v[176:179], v[232:235], v[12:15]
	v_mfma_f32_16x16x32_bf16 v[8:11], v[184:187], v[232:235], v[8:11]
	v_mfma_f32_16x16x32_bf16 v[52:55], v[188:191], v[204:207], v[52:55]
	v_mfma_f32_16x16x32_bf16 v[48:51], v[196:199], v[204:207], v[48:51]
	v_mfma_f32_16x16x32_bf16 v[36:39], v[188:191], v[212:215], v[36:39]
	v_mfma_f32_16x16x32_bf16 v[32:35], v[196:199], v[212:215], v[32:35]
	v_mfma_f32_16x16x32_bf16 v[20:23], v[188:191], v[220:223], v[20:23]
	v_mfma_f32_16x16x32_bf16 v[16:19], v[196:199], v[220:223], v[16:19]
	v_mfma_f32_16x16x32_bf16 v[4:7], v[188:191], v[228:231], v[4:7]
	v_mfma_f32_16x16x32_bf16 v[0:3], v[196:199], v[228:231], v[0:3]
	v_mfma_f32_16x16x32_bf16 v[52:55], v[192:195], v[208:211], v[52:55]
	v_mfma_f32_16x16x32_bf16 v[48:51], v[200:203], v[208:211], v[48:51]
	v_mfma_f32_16x16x32_bf16 v[36:39], v[192:195], v[216:219], v[36:39]
	v_mfma_f32_16x16x32_bf16 v[32:35], v[200:203], v[216:219], v[32:35]
	v_mfma_f32_16x16x32_bf16 v[20:23], v[192:195], v[224:227], v[20:23]
	v_mfma_f32_16x16x32_bf16 v[16:19], v[200:203], v[224:227], v[16:19]
	v_mfma_f32_16x16x32_bf16 v[4:7], v[192:195], v[232:235], v[4:7]
	v_mfma_f32_16x16x32_bf16 v[0:3], v[200:203], v[232:235], v[0:3]
	s_barrier
; #define PG8_STAGE(bufoff, gbase, voff) do { _Pragma("unroll") for (int _i = 0; _i < 2; ++_i) \
;         __builtin_amdgcn_global_load_lds((const unsigned*)((const char*)(gbase) + (voff)[_i]), (PG8_LAS unsigned*)(lds + (bufoff) + ldsw + _i * 8192), 16, 0, 0); } while (0)
; #define PG8_LDA(dst, b, h) do { _Pragma("unroll") for (int m = 0; m < 4; ++m) _Pragma("unroll") for (int k = 0; k < 2; ++k) dst[m][k] = *(const PG8_LAS bf16x8*)(lds + PG8_SA(b, h) + aoff + m * 2048 + k * 1024); } while (0)
; #define PG8_LDB(dst, b, h) do { _Pragma("unroll") for (int n = 0; n < 2; ++n) _Pragma("unroll") for (int k = 0; k < 2; ++k) dst[n][k] = *(const PG8_LAS bf16x8*)(lds + PG8_SB(b, h) + boff + n * 2048 + k * 1024); } while (0)
; #define PG8_MMA(ai, bj, At, Bt) do { __builtin_amdgcn_s_setprio(1); _Pragma("unroll") for (int m = 0; m < 4; ++m) _Pragma("unroll") for (int n = 0; n < 2; ++n) _Pragma("unroll") for (int k = 0; k < 2; ++k) \
;         acc[ai][bj][m][n] = __builtin_amdgcn_mfma_f32_16x16x32_bf16(Bt[n][k], At[m][k], acc[ai][bj][m][n], 0, 0, 0); __builtin_amdgcn_s_setprio(0); } while (0)
; #define PG8_WAIT_V(n) asm volatile("s_waitcnt vmcnt(" #n ")" ::: "memory")
; #define PG8_WAIT_L(n) asm volatile("s_waitcnt lgkmcnt(" #n ")" ::: "memory")
; #define PG8_BAR __builtin_amdgcn_s_barrier()
; #define PG8_SCHED __builtin_amdgcn_sched_barrier(0)
; template <class Epi, class Sched, bool ALIGN_EPI = false, bool SP2 = false>
; __device__ __forceinline__ void gemm_phase(PG8_LAS unsigned char* lds, const Gemm g, const Sched& S, const Epi& E) {
;     ...
;         for (int t = 0; t < nt; t += 2) {
;             const bool last = (t == nt - 2);
;     ...
;             PG8_LDB(B0, 1, 0); PG8_LDB(B1, 1, 1); PG8_SCHED; PG8_LDA(At, 1, 0); PG8_STAGE(PG8_SA(0, 1), a2 + hstep, voffA);
;             PG8_WAIT_V(8); PG8_WAIT_L(0); PG8_BAR; PG8_MMA(0, 0, At, B0); PG8_MMA(0, 1, At, B1); PG8_BAR; PG8_SCHED;
;             PG8_LDA(At, 1, 1); PG8_STAGE(PG8_SB(1, 0), b3, voffB); PG8_STAGE(PG8_SB(1, 1), b3 + hstep, voffB); PG8_STAGE(PG8_SA(1, 0), a3, voffA);
;             PG8_WAIT_V(8); PG8_WAIT_L(0); PG8_BAR; PG8_MMA(1, 0, At, B0); PG8_MMA(1, 1, At, B1); PG8_BAR; PG8_SCHED;
	s_add_i32 s48, 0, 0x18000
	v_add_u32_e32 v143, s48, v159
	s_add_i32 s49, 0, 0x1c000
	ds_read_b128 v[172:175], v143
	ds_read_b128 v[176:179], v143 offset:1024
	ds_read_b128 v[180:183], v143 offset:2048
	ds_read_b128 v[184:187], v143 offset:3072
	v_add_u32_e32 v143, s49, v159
	ds_read_b128 v[188:191], v143
	ds_read_b128 v[192:195], v143 offset:1024
	ds_read_b128 v[196:199], v143 offset:2048
	ds_read_b128 v[200:203], v143 offset:3072
	s_add_u32 s16, s22, 0xb0000
	s_addc_u32 s17, s23, 0
	s_mov_b32 m0, s34
	ds_read_b128 v[204:207], v160 offset:32768
	ds_read_b128 v[208:211], v160 offset:33792
	ds_read_b128 v[212:215], v160 offset:34816
	ds_read_b128 v[216:219], v160 offset:35840
	ds_read_b128 v[220:223], v160 offset:36864
	ds_read_b128 v[224:227], v160 offset:37888
	ds_read_b128 v[228:231], v160 offset:38912
	ds_read_b128 v[232:235], v160 offset:39936
	global_load_lds_dwordx4 v134, s[16:17]
	s_mov_b32 m0, s35
	s_nop 0
	global_load_lds_dwordx4 v130, s[16:17]
	s_waitcnt vmcnt(8)
	s_waitcnt lgkmcnt(0)
	s_barrier
	s_waitcnt lgkmcnt(0)
	v_mfma_f32_16x16x32_bf16 v[124:127], v[172:175], v[204:207], v[124:127]
	v_mfma_f32_16x16x32_bf16 v[120:123], v[180:183], v[204:207], v[120:123]
	v_mfma_f32_16x16x32_bf16 v[108:111], v[172:175], v[212:215], v[108:111]
	v_mfma_f32_16x16x32_bf16 v[104:107], v[180:183], v[212:215], v[104:107]
	v_mfma_f32_16x16x32_bf16 v[92:95], v[172:175], v[220:223], v[92:95]
	v_mfma_f32_16x16x32_bf16 v[88:91], v[180:183], v[220:223], v[88:91]
	v_mfma_f32_16x16x32_bf16 v[76:79], v[172:175], v[228:231], v[76:79]
	v_mfma_f32_16x16x32_bf16 v[72:75], v[180:183], v[228:231], v[72:75]
	v_mfma_f32_16x16x32_bf16 v[124:127], v[176:179], v[208:211], v[124:127]
	v_mfma_f32_16x16x32_bf16 v[120:123], v[184:187], v[208:211], v[120:123]
	v_mfma_f32_16x16x32_bf16 v[108:111], v[176:179], v[216:219], v[108:111]
	v_mfma_f32_16x16x32_bf16 v[104:107], v[184:187], v[216:219], v[104:107]
	v_mfma_f32_16x16x32_bf16 v[92:95], v[176:179], v[224:227], v[92:95]
	v_mfma_f32_16x16x32_bf16 v[88:91], v[184:187], v[224:227], v[88:91]
	v_mfma_f32_16x16x32_bf16 v[76:79], v[176:179], v[232:235], v[76:79]
	v_mfma_f32_16x16x32_bf16 v[72:75], v[184:187], v[232:235], v[72:75]
	v_mfma_f32_16x16x32_bf16 v[116:119], v[188:191], v[204:207], v[116:119]
	v_mfma_f32_16x16x32_bf16 v[112:115], v[196:199], v[204:207], v[112:115]
	v_mfma_f32_16x16x32_bf16 v[100:103], v[188:191], v[212:215], v[100:103]
	v_mfma_f32_16x16x32_bf16 v[96:99], v[196:199], v[212:215], v[96:99]
	v_mfma_f32_16x16x32_bf16 v[84:87], v[188:191], v[220:223], v[84:87]
	v_mfma_f32_16x16x32_bf16 v[80:83], v[196:199], v[220:223], v[80:83]
	v_mfma_f32_16x16x32_bf16 v[68:71], v[188:191], v[228:231], v[68:71]
	v_mfma_f32_16x16x32_bf16 v[64:67], v[196:199], v[228:231], v[64:67]
	v_mfma_f32_16x16x32_bf16 v[116:119], v[192:195], v[208:211], v[116:119]
	v_mfma_f32_16x16x32_bf16 v[112:115], v[200:203], v[208:211], v[112:115]
	v_mfma_f32_16x16x32_bf16 v[100:103], v[192:195], v[216:219], v[100:103]
	v_mfma_f32_16x16x32_bf16 v[96:99], v[200:203], v[216:219], v[96:99]
	v_mfma_f32_16x16x32_bf16 v[84:87], v[192:195], v[224:227], v[84:87]
	v_mfma_f32_16x16x32_bf16 v[80:83], v[200:203], v[224:227], v[80:83]
	v_mfma_f32_16x16x32_bf16 v[68:71], v[192:195], v[232:235], v[68:71]
	v_mfma_f32_16x16x32_bf16 v[64:67], v[200:203], v[232:235], v[64:67]
	s_barrier
	s_add_i32 s16, s48, s28
	s_mov_b32 m0, s16
	ds_read_b128 v[204:207], v160 offset:49152
	ds_read_b128 v[208:211], v160 offset:50176
	ds_read_b128 v[212:215], v160 offset:51200
	ds_read_b128 v[216:219], v160 offset:52224
	ds_read_b128 v[220:223], v160 offset:53248
	ds_read_b128 v[224:227], v160 offset:54272
	ds_read_b128 v[228:231], v160 offset:55296
	ds_read_b128 v[232:235], v160 offset:56320
	global_load_lds_dwordx4 v132, s[94:95]
	s_add_i32 m0, s16, 0x2000
	s_add_u32 s16, s20, 0xb0080
	s_addc_u32 s17, s21, 0
	s_add_i32 s20, s49, s28
	global_load_lds_dwordx4 v128, s[94:95]
	s_mov_b32 m0, s20
	s_nop 0
	global_load_lds_dwordx4 v132, s[16:17]
	s_add_i32 m0, s20, 0x2000
	s_nop 0
	global_load_lds_dwordx4 v128, s[16:17]
	s_mov_b32 m0, s38
	s_nop 0
	global_load_lds_dwordx4 v134, s[96:97]
	s_mov_b32 m0, s39
	s_nop 0
	global_load_lds_dwordx4 v130, s[96:97]
	s_waitcnt vmcnt(8)
	s_waitcnt lgkmcnt(0)
	s_barrier
	s_waitcnt lgkmcnt(0)
	v_mfma_f32_16x16x32_bf16 v[60:63], v[172:175], v[204:207], v[60:63]
	v_mfma_f32_16x16x32_bf16 v[56:59], v[180:183], v[204:207], v[56:59]
	v_mfma_f32_16x16x32_bf16 v[44:47], v[172:175], v[212:215], v[44:47]
	v_mfma_f32_16x16x32_bf16 v[40:43], v[180:183], v[212:215], v[40:43]
	v_mfma_f32_16x16x32_bf16 v[28:31], v[172:175], v[220:223], v[28:31]
	v_mfma_f32_16x16x32_bf16 v[24:27], v[180:183], v[220:223], v[24:27]
	v_mfma_f32_16x16x32_bf16 v[12:15], v[172:175], v[228:231], v[12:15]
	v_mfma_f32_16x16x32_bf16 v[8:11], v[180:183], v[228:231], v[8:11]
	v_mfma_f32_16x16x32_bf16 v[60:63], v[176:179], v[208:211], v[60:63]
	v_mfma_f32_16x16x32_bf16 v[56:59], v[184:187], v[208:211], v[56:59]
	v_mfma_f32_16x16x32_bf16 v[44:47], v[176:179], v[216:219], v[44:47]
	v_mfma_f32_16x16x32_bf16 v[40:43], v[184:187], v[216:219], v[40:43]
	v_mfma_f32_16x16x32_bf16 v[28:31], v[176:179], v[224:227], v[28:31]
	v_mfma_f32_16x16x32_bf16 v[24:27], v[184:187], v[224:227], v[24:27]
	v_mfma_f32_16x16x32_bf16 v[12:15], v[176:179], v[232:235], v[12:15]
	v_mfma_f32_16x16x32_bf16 v[8:11], v[184:187], v[232:235], v[8:11]
	v_mfma_f32_16x16x32_bf16 v[52:55], v[188:191], v[204:207], v[52:55]
	v_mfma_f32_16x16x32_bf16 v[48:51], v[196:199], v[204:207], v[48:51]
	v_mfma_f32_16x16x32_bf16 v[36:39], v[188:191], v[212:215], v[36:39]
	v_mfma_f32_16x16x32_bf16 v[32:35], v[196:199], v[212:215], v[32:35]
	v_mfma_f32_16x16x32_bf16 v[20:23], v[188:191], v[220:223], v[20:23]
	v_mfma_f32_16x16x32_bf16 v[16:19], v[196:199], v[220:223], v[16:19]
	v_mfma_f32_16x16x32_bf16 v[4:7], v[188:191], v[228:231], v[4:7]
	v_mfma_f32_16x16x32_bf16 v[0:3], v[196:199], v[228:231], v[0:3]
	v_mfma_f32_16x16x32_bf16 v[52:55], v[192:195], v[208:211], v[52:55]
	v_mfma_f32_16x16x32_bf16 v[48:51], v[200:203], v[208:211], v[48:51]
	v_mfma_f32_16x16x32_bf16 v[36:39], v[192:195], v[216:219], v[36:39]
	v_mfma_f32_16x16x32_bf16 v[32:35], v[200:203], v[216:219], v[32:35]
	v_mfma_f32_16x16x32_bf16 v[20:23], v[192:195], v[224:227], v[20:23]
	v_mfma_f32_16x16x32_bf16 v[16:19], v[200:203], v[224:227], v[16:19]
	v_mfma_f32_16x16x32_bf16 v[4:7], v[192:195], v[232:235], v[4:7]
	v_mfma_f32_16x16x32_bf16 v[0:3], v[200:203], v[232:235], v[0:3]
	s_barrier
	s_add_i32 s47, s47, 2
	s_add_u32 s25, s25, 0x100
	s_addc_u32 s46, s46, 0
	s_cmp_gt_u32 s47, s99
	s_mov_b64 s[16:17], s[18:19]
	s_cbranch_scc0 .LBB0_898
	s_and_b64 vcc, exec, s[12:13]
	s_cbranch_vccz .LBB0_901
	s_barrier
